# v21 with s_nop 3 in front of each barrier that closes an MFMA block (hand-off delayed by four slots)
# baseline (speedup 1.0000x reference)
; #define PG8_STAGE(bufoff, gbase, voff) do { _Pragma("unroll") for (int _i = 0; _i < 2; ++_i) \
;         __builtin_amdgcn_global_load_lds((const unsigned*)((const char*)(gbase) + (voff)[_i]), (PG8_LAS unsigned*)(lds + (bufoff) + ldsw + _i * 8192), 16, 0, 0); } while (0)
; #define PG8_WAIT_V(n) asm volatile("s_waitcnt vmcnt(" #n ")" ::: "memory")
; #define PG8_WAIT_L(n) asm volatile("s_waitcnt lgkmcnt(" #n ")" ::: "memory")
; #define PG8_BAR __builtin_amdgcn_s_barrier()
; #define PG8_SCHED __builtin_amdgcn_sched_barrier(0)
; template <class Epi, class Sched, bool ALIGN_EPI = true, bool SP2 = true>
; __device__ __forceinline__ void gemm_phase(PG8_LAS unsigned char* lds, const int K  , const Sched& S, const Epi& E) {
;     ...
;             PG8_LDB(B0, 0, 0); PG8_LDB(B1, 0, 1); PG8_SCHED; PG8_LDA(At, 0, 0); PG8_STAGE(PG8_SA(1, 1), a1 + hstep, voffA);
;             PG8_WAIT_V(8); PG8_WAIT_L(0); PG8_BAR; PG8_MMA(0, 0, At, B0); PG8_MMA(0, 1, At, B1); PG8_BAR; PG8_SCHED;
;             PG8_LDA(At, 0, 1); PG8_STAGE(PG8_SB(0, 0), b2, voffB); PG8_STAGE(PG8_SB(0, 1), b2 + hstep, voffB); PG8_STAGE(PG8_SA(0, 0), a2, voffA);
;             PG8_WAIT_V(8); PG8_WAIT_L(0); PG8_BAR; PG8_MMA(1, 0, At, B0); PG8_MMA(1, 1, At, B1); PG8_BAR; PG8_SCHED;
.LBB0_219:
	ds_read_b128 v[148:151], v154
	ds_read_b128 v[160:163], v154 offset:1024
	ds_read_b128 v[164:167], v154 offset:2048
	ds_read_b128 v[168:171], v154 offset:3072
	ds_read_b128 v[172:175], v155
	ds_read_b128 v[176:179], v155 offset:1024
	ds_read_b128 v[180:183], v155 offset:2048
	ds_read_b128 v[184:187], v155 offset:3072
	s_add_u32 s22, s20, 0xfff80080
	s_addc_u32 s23, s21, -1
	s_cmp_eq_u32 s48, 28
	s_cselect_b32 s25, s13, s23
	s_cselect_b32 s24, s44, s22
	s_cselect_b32 s23, s11, s47
	s_cselect_b32 s22, s45, s46
	v_lshl_add_u64 v[220:221], s[20:21], 0, v[140:141]
	s_add_i32 m0, s19, 0xc000
	ds_read_b128 v[188:191], v156
	ds_read_b128 v[192:195], v156 offset:1024
	ds_read_b128 v[196:199], v156 offset:2048
	ds_read_b128 v[200:203], v156 offset:3072
	ds_read_b128 v[204:207], v156 offset:4096
	ds_read_b128 v[208:211], v156 offset:5120
	ds_read_b128 v[212:215], v156 offset:6144
	ds_read_b128 v[216:219], v156 offset:7168
	global_load_lds_dwordx4 v[220:221], off
	v_lshl_add_u64 v[220:221], s[20:21], 0, v[142:143]
	s_add_i32 m0, s19, 0xe000
	s_nop 0
	global_load_lds_dwordx4 v[220:221], off
	s_waitcnt vmcnt(8)
	s_waitcnt lgkmcnt(0)
	s_setprio 1
	s_barrier
	v_mfma_f32_16x16x32_bf16 v[126:129], v[148:151], v[188:191], v[126:129]
	v_mfma_f32_16x16x32_bf16 v[118:121], v[164:167], v[188:191], v[118:121]
	v_mfma_f32_16x16x32_bf16 v[110:113], v[148:151], v[196:199], v[110:113]
	v_mfma_f32_16x16x32_bf16 v[102:105], v[164:167], v[196:199], v[102:105]
	v_mfma_f32_16x16x32_bf16 v[94:97], v[148:151], v[204:207], v[94:97]
	v_mfma_f32_16x16x32_bf16 v[86:89], v[164:167], v[204:207], v[86:89]
	v_mfma_f32_16x16x32_bf16 v[78:81], v[148:151], v[212:215], v[78:81]
	v_mfma_f32_16x16x32_bf16 v[70:73], v[164:167], v[212:215], v[70:73]
	v_mfma_f32_16x16x32_bf16 v[126:129], v[160:163], v[192:195], v[126:129]
	v_mfma_f32_16x16x32_bf16 v[118:121], v[168:171], v[192:195], v[118:121]
	v_mfma_f32_16x16x32_bf16 v[110:113], v[160:163], v[200:203], v[110:113]
	v_mfma_f32_16x16x32_bf16 v[102:105], v[168:171], v[200:203], v[102:105]
	v_mfma_f32_16x16x32_bf16 v[94:97], v[160:163], v[208:211], v[94:97]
	v_mfma_f32_16x16x32_bf16 v[86:89], v[168:171], v[208:211], v[86:89]
	v_mfma_f32_16x16x32_bf16 v[78:81], v[160:163], v[216:219], v[78:81]
	v_mfma_f32_16x16x32_bf16 v[70:73], v[168:171], v[216:219], v[70:73]
	s_setprio 0
	s_setprio 1
	v_mfma_f32_16x16x32_bf16 v[122:125], v[172:175], v[188:191], v[122:125]
	v_mfma_f32_16x16x32_bf16 v[114:117], v[180:183], v[188:191], v[114:117]
	v_mfma_f32_16x16x32_bf16 v[106:109], v[172:175], v[196:199], v[106:109]
	v_mfma_f32_16x16x32_bf16 v[98:101], v[180:183], v[196:199], v[98:101]
	v_mfma_f32_16x16x32_bf16 v[90:93], v[172:175], v[204:207], v[90:93]
	v_mfma_f32_16x16x32_bf16 v[82:85], v[180:183], v[204:207], v[82:85]
	v_mfma_f32_16x16x32_bf16 v[74:77], v[172:175], v[212:215], v[74:77]
	v_mfma_f32_16x16x32_bf16 v[66:69], v[180:183], v[212:215], v[66:69]
	v_mfma_f32_16x16x32_bf16 v[122:125], v[176:179], v[192:195], v[122:125]
	v_mfma_f32_16x16x32_bf16 v[114:117], v[184:187], v[192:195], v[114:117]
	v_mfma_f32_16x16x32_bf16 v[106:109], v[176:179], v[200:203], v[106:109]
	v_mfma_f32_16x16x32_bf16 v[98:101], v[184:187], v[200:203], v[98:101]
	v_mfma_f32_16x16x32_bf16 v[90:93], v[176:179], v[208:211], v[90:93]
	v_mfma_f32_16x16x32_bf16 v[82:85], v[184:187], v[208:211], v[82:85]
	v_mfma_f32_16x16x32_bf16 v[74:77], v[176:179], v[216:219], v[74:77]
	v_mfma_f32_16x16x32_bf16 v[66:69], v[184:187], v[216:219], v[66:69]
	s_nop 3
	s_barrier
	s_setprio 0
	s_add_i32 s49, s39, s29
	v_lshl_add_u64 v[220:221], s[22:23], 0, v[136:137]
	s_mov_b32 m0, s49
	ds_read_b128 v[188:191], v156 offset:16384
	ds_read_b128 v[192:195], v156 offset:17408
	ds_read_b128 v[196:199], v156 offset:18432
	ds_read_b128 v[200:203], v156 offset:19456
	ds_read_b128 v[204:207], v156 offset:20480
	ds_read_b128 v[208:211], v156 offset:21504
	ds_read_b128 v[212:215], v156 offset:22528
	ds_read_b128 v[216:219], v156 offset:23552
	global_load_lds_dwordx4 v[220:221], off
	s_add_i32 m0, s49, 0x2000
	s_add_u32 s50, s22, 0x80000
	v_lshl_add_u64 v[222:223], s[22:23], 0, v[132:133]
	s_addc_u32 s51, s23, 0
	s_add_i32 s49, s40, s29
	global_load_lds_dwordx4 v[222:223], off
	v_lshl_add_u64 v[224:225], s[50:51], 0, v[136:137]
	s_mov_b32 m0, s49
	v_lshl_add_u64 v[226:227], s[24:25], 0, v[134:135]
	global_load_lds_dwordx4 v[224:225], off
	v_lshl_add_u64 v[224:225], s[50:51], 0, v[132:133]
	s_add_i32 m0, s49, 0x2000
	s_nop 0
	global_load_lds_dwordx4 v[224:225], off
	v_lshl_add_u64 v[224:225], s[24:25], 0, v[138:139]
	s_mov_b32 m0, s19
	s_nop 0
	global_load_lds_dwordx4 v[224:225], off
	s_mov_b32 m0, s31
	s_nop 0
	global_load_lds_dwordx4 v[226:227], off
	s_waitcnt vmcnt(8)
	s_waitcnt lgkmcnt(0)
	s_setprio 1
	s_barrier
; #define PG8_STAGE(bufoff, gbase, voff) do { _Pragma("unroll") for (int _i = 0; _i < 2; ++_i) \
;         __builtin_amdgcn_global_load_lds((const unsigned*)((const char*)(gbase) + (voff)[_i]), (PG8_LAS unsigned*)(lds + (bufoff) + ldsw + _i * 8192), 16, 0, 0); } while (0)
; #define PG8_WAIT_V(n) asm volatile("s_waitcnt vmcnt(" #n ")" ::: "memory")
; #define PG8_WAIT_L(n) asm volatile("s_waitcnt lgkmcnt(" #n ")" ::: "memory")
; #define PG8_BAR __builtin_amdgcn_s_barrier()
; #define PG8_SCHED __builtin_amdgcn_sched_barrier(0)
; template <class Epi, class Sched, bool ALIGN_EPI = true, bool SP2 = true>
; __device__ __forceinline__ void gemm_phase(PG8_LAS unsigned char* lds, const int K  , const Sched& S, const Epi& E) {
;     ...
;             PG8_WAIT_V(8); PG8_WAIT_L(0); PG8_BAR; PG8_MMA(1, 0, At, B0); PG8_MMA(1, 1, At, B1); PG8_BAR; PG8_SCHED;
;             PG8_LDB(B0, 1, 0); PG8_LDB(B1, 1, 1); PG8_SCHED; PG8_LDA(At, 1, 0); PG8_STAGE(PG8_SA(0, 1), a2 + hstep, voffA);
;             PG8_WAIT_V(8); PG8_WAIT_L(0); PG8_BAR; PG8_MMA(0, 0, At, B0); PG8_MMA(0, 1, At, B1); PG8_BAR; PG8_SCHED;
	v_mfma_f32_16x16x32_bf16 v[62:65], v[148:151], v[188:191], v[62:65]
	v_mfma_f32_16x16x32_bf16 v[54:57], v[164:167], v[188:191], v[54:57]
	v_mfma_f32_16x16x32_bf16 v[46:49], v[148:151], v[196:199], v[46:49]
	v_mfma_f32_16x16x32_bf16 v[38:41], v[164:167], v[196:199], v[38:41]
	v_mfma_f32_16x16x32_bf16 v[30:33], v[148:151], v[204:207], v[30:33]
	v_mfma_f32_16x16x32_bf16 v[22:25], v[164:167], v[204:207], v[22:25]
	v_mfma_f32_16x16x32_bf16 v[14:17], v[148:151], v[212:215], v[14:17]
	v_mfma_f32_16x16x32_bf16 v[6:9], v[164:167], v[212:215], v[6:9]
	v_mfma_f32_16x16x32_bf16 v[62:65], v[160:163], v[192:195], v[62:65]
	v_mfma_f32_16x16x32_bf16 v[54:57], v[168:171], v[192:195], v[54:57]
	v_mfma_f32_16x16x32_bf16 v[46:49], v[160:163], v[200:203], v[46:49]
	v_mfma_f32_16x16x32_bf16 v[38:41], v[168:171], v[200:203], v[38:41]
	v_mfma_f32_16x16x32_bf16 v[30:33], v[160:163], v[208:211], v[30:33]
	v_mfma_f32_16x16x32_bf16 v[22:25], v[168:171], v[208:211], v[22:25]
	v_mfma_f32_16x16x32_bf16 v[14:17], v[160:163], v[216:219], v[14:17]
	v_mfma_f32_16x16x32_bf16 v[6:9], v[168:171], v[216:219], v[6:9]
	s_setprio 0
	s_setprio 1
	v_mfma_f32_16x16x32_bf16 v[58:61], v[172:175], v[188:191], v[58:61]
	v_mfma_f32_16x16x32_bf16 v[50:53], v[180:183], v[188:191], v[50:53]
	v_mfma_f32_16x16x32_bf16 v[42:45], v[172:175], v[196:199], v[42:45]
	v_mfma_f32_16x16x32_bf16 v[34:37], v[180:183], v[196:199], v[34:37]
	v_mfma_f32_16x16x32_bf16 v[26:29], v[172:175], v[204:207], v[26:29]
	v_mfma_f32_16x16x32_bf16 v[18:21], v[180:183], v[204:207], v[18:21]
	v_mfma_f32_16x16x32_bf16 v[10:13], v[172:175], v[212:215], v[10:13]
	v_mfma_f32_16x16x32_bf16 v[2:5], v[180:183], v[212:215], v[2:5]
	v_mfma_f32_16x16x32_bf16 v[58:61], v[176:179], v[192:195], v[58:61]
	v_mfma_f32_16x16x32_bf16 v[50:53], v[184:187], v[192:195], v[50:53]
	v_mfma_f32_16x16x32_bf16 v[42:45], v[176:179], v[200:203], v[42:45]
	v_mfma_f32_16x16x32_bf16 v[34:37], v[184:187], v[200:203], v[34:37]
	v_mfma_f32_16x16x32_bf16 v[26:29], v[176:179], v[208:211], v[26:29]
	v_mfma_f32_16x16x32_bf16 v[18:21], v[184:187], v[208:211], v[18:21]
	v_mfma_f32_16x16x32_bf16 v[10:13], v[176:179], v[216:219], v[10:13]
	v_mfma_f32_16x16x32_bf16 v[2:5], v[184:187], v[216:219], v[2:5]
	s_nop 3
	s_barrier
	s_setprio 0
	s_add_i32 s49, 0, 0x18000
	v_add_u32_e32 v159, s49, v152
	s_add_i32 s50, 0, 0x1c000
	ds_read_b128 v[148:151], v159
	ds_read_b128 v[160:163], v159 offset:1024
	ds_read_b128 v[164:167], v159 offset:2048
	ds_read_b128 v[168:171], v159 offset:3072
	v_add_u32_e32 v159, s50, v152
	ds_read_b128 v[172:175], v159
	ds_read_b128 v[176:179], v159 offset:1024
	ds_read_b128 v[180:183], v159 offset:2048
	ds_read_b128 v[184:187], v159 offset:3072
	s_add_u32 s24, s24, 0x80000
	s_addc_u32 s25, s25, 0
	s_mov_b32 m0, s33
	v_lshl_add_u64 v[230:231], s[24:25], 0, v[138:139]
	ds_read_b128 v[188:191], v156 offset:32768
	ds_read_b128 v[192:195], v156 offset:33792
	ds_read_b128 v[196:199], v156 offset:34816
	ds_read_b128 v[200:203], v156 offset:35840
	ds_read_b128 v[204:207], v156 offset:36864
	ds_read_b128 v[208:211], v156 offset:37888
	ds_read_b128 v[212:215], v156 offset:38912
	ds_read_b128 v[216:219], v156 offset:39936
	global_load_lds_dwordx4 v[230:231], off
	v_lshl_add_u64 v[230:231], s[24:25], 0, v[134:135]
	s_mov_b32 m0, s34
	s_nop 0
	global_load_lds_dwordx4 v[230:231], off
	s_waitcnt vmcnt(8)
	s_waitcnt lgkmcnt(0)
	s_setprio 1
	s_barrier
	v_mfma_f32_16x16x32_bf16 v[126:129], v[148:151], v[188:191], v[126:129]
	v_mfma_f32_16x16x32_bf16 v[118:121], v[164:167], v[188:191], v[118:121]
	v_mfma_f32_16x16x32_bf16 v[110:113], v[148:151], v[196:199], v[110:113]
	v_mfma_f32_16x16x32_bf16 v[102:105], v[164:167], v[196:199], v[102:105]
	v_mfma_f32_16x16x32_bf16 v[94:97], v[148:151], v[204:207], v[94:97]
	v_mfma_f32_16x16x32_bf16 v[86:89], v[164:167], v[204:207], v[86:89]
	v_mfma_f32_16x16x32_bf16 v[78:81], v[148:151], v[212:215], v[78:81]
	v_mfma_f32_16x16x32_bf16 v[70:73], v[164:167], v[212:215], v[70:73]
	v_mfma_f32_16x16x32_bf16 v[126:129], v[160:163], v[192:195], v[126:129]
	v_mfma_f32_16x16x32_bf16 v[118:121], v[168:171], v[192:195], v[118:121]
	v_mfma_f32_16x16x32_bf16 v[110:113], v[160:163], v[200:203], v[110:113]
	v_mfma_f32_16x16x32_bf16 v[102:105], v[168:171], v[200:203], v[102:105]
	v_mfma_f32_16x16x32_bf16 v[94:97], v[160:163], v[208:211], v[94:97]
	v_mfma_f32_16x16x32_bf16 v[86:89], v[168:171], v[208:211], v[86:89]
	v_mfma_f32_16x16x32_bf16 v[78:81], v[160:163], v[216:219], v[78:81]
	v_mfma_f32_16x16x32_bf16 v[70:73], v[168:171], v[216:219], v[70:73]
	s_setprio 0
	s_setprio 1
	v_mfma_f32_16x16x32_bf16 v[122:125], v[172:175], v[188:191], v[122:125]
	v_mfma_f32_16x16x32_bf16 v[114:117], v[180:183], v[188:191], v[114:117]
	v_mfma_f32_16x16x32_bf16 v[106:109], v[172:175], v[196:199], v[106:109]
	v_mfma_f32_16x16x32_bf16 v[98:101], v[180:183], v[196:199], v[98:101]
	v_mfma_f32_16x16x32_bf16 v[90:93], v[172:175], v[204:207], v[90:93]
	v_mfma_f32_16x16x32_bf16 v[82:85], v[180:183], v[204:207], v[82:85]
	v_mfma_f32_16x16x32_bf16 v[74:77], v[172:175], v[212:215], v[74:77]
	v_mfma_f32_16x16x32_bf16 v[66:69], v[180:183], v[212:215], v[66:69]
	v_mfma_f32_16x16x32_bf16 v[122:125], v[176:179], v[192:195], v[122:125]
	v_mfma_f32_16x16x32_bf16 v[114:117], v[184:187], v[192:195], v[114:117]
	v_mfma_f32_16x16x32_bf16 v[106:109], v[176:179], v[200:203], v[106:109]
	v_mfma_f32_16x16x32_bf16 v[98:101], v[184:187], v[200:203], v[98:101]
	v_mfma_f32_16x16x32_bf16 v[90:93], v[176:179], v[208:211], v[90:93]
	v_mfma_f32_16x16x32_bf16 v[82:85], v[184:187], v[208:211], v[82:85]
	v_mfma_f32_16x16x32_bf16 v[74:77], v[176:179], v[216:219], v[74:77]
	v_mfma_f32_16x16x32_bf16 v[66:69], v[184:187], v[216:219], v[66:69]
	s_nop 3
	s_barrier
; #define PG8_STAGE(bufoff, gbase, voff) do { _Pragma("unroll") for (int _i = 0; _i < 2; ++_i) \
;         __builtin_amdgcn_global_load_lds((const unsigned*)((const char*)(gbase) + (voff)[_i]), (PG8_LAS unsigned*)(lds + (bufoff) + ldsw + _i * 8192), 16, 0, 0); } while (0)
; #define PG8_WAIT_V(n) asm volatile("s_waitcnt vmcnt(" #n ")" ::: "memory")
; #define PG8_WAIT_L(n) asm volatile("s_waitcnt lgkmcnt(" #n ")" ::: "memory")
; #define PG8_BAR __builtin_amdgcn_s_barrier()
; #define PG8_SCHED __builtin_amdgcn_sched_barrier(0)
; template <class Epi, class Sched, bool ALIGN_EPI = true, bool SP2 = true>
; __device__ __forceinline__ void gemm_phase(PG8_LAS unsigned char* lds, const int K  , const Sched& S, const Epi& E) {
;     ...
;             PG8_LDA(At, 1, 1); PG8_STAGE(PG8_SB(1, 0), b3, voffB); PG8_STAGE(PG8_SB(1, 1), b3 + hstep, voffB); PG8_STAGE(PG8_SA(1, 0), a3, voffA);
;             PG8_WAIT_V(8); PG8_WAIT_L(0); PG8_BAR; PG8_MMA(1, 0, At, B0); PG8_MMA(1, 1, At, B1); PG8_BAR; PG8_SCHED;
;     ...
;         if constexpr (ALIGN_EPI) { if (wr == 0) PG8_BAR; }
	s_setprio 0
	s_add_i32 s24, s49, s29
	v_lshl_add_u64 v[220:221], v[220:221], 0, s[6:7]
	s_mov_b32 m0, s24
	ds_read_b128 v[188:191], v156 offset:49152
	ds_read_b128 v[192:195], v156 offset:50176
	ds_read_b128 v[196:199], v156 offset:51200
	ds_read_b128 v[200:203], v156 offset:52224
	ds_read_b128 v[204:207], v156 offset:53248
	ds_read_b128 v[208:211], v156 offset:54272
	ds_read_b128 v[212:215], v156 offset:55296
	ds_read_b128 v[216:219], v156 offset:56320
	global_load_lds_dwordx4 v[220:221], off
	s_add_i32 m0, s24, 0x2000
	s_add_u32 s22, s22, 0x80080
	v_lshl_add_u64 v[220:221], v[222:223], 0, s[6:7]
	s_addc_u32 s23, s23, 0
	s_add_i32 s24, s50, s29
	global_load_lds_dwordx4 v[220:221], off
	v_lshl_add_u64 v[220:221], s[22:23], 0, v[136:137]
	s_mov_b32 m0, s24
	s_nop 0
	global_load_lds_dwordx4 v[220:221], off
	v_lshl_add_u64 v[220:221], s[22:23], 0, v[132:133]
	s_add_i32 m0, s24, 0x2000
	s_nop 0
	global_load_lds_dwordx4 v[220:221], off
	v_lshl_add_u64 v[220:221], v[224:225], 0, s[6:7]
	s_mov_b32 m0, s36
	s_nop 0
	global_load_lds_dwordx4 v[220:221], off
	v_lshl_add_u64 v[220:221], v[226:227], 0, s[6:7]
	s_mov_b32 m0, s37
	s_nop 0
	global_load_lds_dwordx4 v[220:221], off
	s_waitcnt vmcnt(8)
	s_waitcnt lgkmcnt(0)
	s_setprio 1
	s_barrier
	v_mfma_f32_16x16x32_bf16 v[62:65], v[148:151], v[188:191], v[62:65]
	v_mfma_f32_16x16x32_bf16 v[54:57], v[164:167], v[188:191], v[54:57]
	v_mfma_f32_16x16x32_bf16 v[46:49], v[148:151], v[196:199], v[46:49]
	v_mfma_f32_16x16x32_bf16 v[38:41], v[164:167], v[196:199], v[38:41]
	v_mfma_f32_16x16x32_bf16 v[30:33], v[148:151], v[204:207], v[30:33]
	v_mfma_f32_16x16x32_bf16 v[22:25], v[164:167], v[204:207], v[22:25]
	v_mfma_f32_16x16x32_bf16 v[14:17], v[148:151], v[212:215], v[14:17]
	v_mfma_f32_16x16x32_bf16 v[6:9], v[164:167], v[212:215], v[6:9]
	v_mfma_f32_16x16x32_bf16 v[62:65], v[160:163], v[192:195], v[62:65]
	v_mfma_f32_16x16x32_bf16 v[54:57], v[168:171], v[192:195], v[54:57]
	v_mfma_f32_16x16x32_bf16 v[46:49], v[160:163], v[200:203], v[46:49]
	v_mfma_f32_16x16x32_bf16 v[38:41], v[168:171], v[200:203], v[38:41]
	v_mfma_f32_16x16x32_bf16 v[30:33], v[160:163], v[208:211], v[30:33]
	v_mfma_f32_16x16x32_bf16 v[22:25], v[168:171], v[208:211], v[22:25]
	v_mfma_f32_16x16x32_bf16 v[14:17], v[160:163], v[216:219], v[14:17]
	v_mfma_f32_16x16x32_bf16 v[6:9], v[168:171], v[216:219], v[6:9]
	s_setprio 0
	s_setprio 1
	v_mfma_f32_16x16x32_bf16 v[58:61], v[172:175], v[188:191], v[58:61]
	v_mfma_f32_16x16x32_bf16 v[50:53], v[180:183], v[188:191], v[50:53]
	v_mfma_f32_16x16x32_bf16 v[42:45], v[172:175], v[196:199], v[42:45]
	v_mfma_f32_16x16x32_bf16 v[34:37], v[180:183], v[196:199], v[34:37]
	v_mfma_f32_16x16x32_bf16 v[26:29], v[172:175], v[204:207], v[26:29]
	v_mfma_f32_16x16x32_bf16 v[18:21], v[180:183], v[204:207], v[18:21]
	v_mfma_f32_16x16x32_bf16 v[10:13], v[172:175], v[212:215], v[10:13]
	v_mfma_f32_16x16x32_bf16 v[2:5], v[180:183], v[212:215], v[2:5]
	v_mfma_f32_16x16x32_bf16 v[58:61], v[176:179], v[192:195], v[58:61]
	v_mfma_f32_16x16x32_bf16 v[50:53], v[184:187], v[192:195], v[50:53]
	v_mfma_f32_16x16x32_bf16 v[42:45], v[176:179], v[200:203], v[42:45]
	v_mfma_f32_16x16x32_bf16 v[34:37], v[184:187], v[200:203], v[34:37]
	v_mfma_f32_16x16x32_bf16 v[26:29], v[176:179], v[208:211], v[26:29]
	v_mfma_f32_16x16x32_bf16 v[18:21], v[184:187], v[208:211], v[18:21]
	v_mfma_f32_16x16x32_bf16 v[10:13], v[176:179], v[216:219], v[10:13]
	v_mfma_f32_16x16x32_bf16 v[2:5], v[184:187], v[216:219], v[2:5]
	s_nop 3
	s_barrier
	s_setprio 0
	s_add_i32 s48, s48, 2
	s_add_u32 s20, s20, 0x100
	s_addc_u32 s21, s21, 0
	s_add_u32 s46, s46, 0x100
	s_addc_u32 s47, s47, 0
	s_cmp_gt_u32 s48, 29
	s_cbranch_scc0 .LBB0_219
	s_and_b64 vcc, exec, s[8:9]
	s_cbranch_vccz .LBB0_222
	s_barrier

; #define PG8_STAGE(bufoff, gbase, voff) do { _Pragma("unroll") for (int _i = 0; _i < 2; ++_i) \
;         __builtin_amdgcn_global_load_lds((const unsigned*)((const char*)(gbase) + (voff)[_i]), (PG8_LAS unsigned*)(lds + (bufoff) + ldsw + _i * 8192), 16, 0, 0); } while (0)
; #define PG8_WAIT_V(n) asm volatile("s_waitcnt vmcnt(" #n ")" ::: "memory")
; #define PG8_WAIT_L(n) asm volatile("s_waitcnt lgkmcnt(" #n ")" ::: "memory")
; #define PG8_BAR __builtin_amdgcn_s_barrier()
; #define PG8_SCHED __builtin_amdgcn_sched_barrier(0)
; template <class Epi, class Sched, bool ALIGN_EPI = true, bool SP2 = true>
; __device__ __forceinline__ void gemm_phase(PG8_LAS unsigned char* lds, const int K  , const Sched& S, const Epi& E) {
;     ...
;             PG8_LDB(B0, 0, 0); PG8_LDB(B1, 0, 1); PG8_SCHED; PG8_LDA(At, 0, 0); PG8_STAGE(PG8_SA(1, 1), a1 + hstep, voffA);
;             PG8_WAIT_V(8); PG8_WAIT_L(0); PG8_BAR; PG8_MMA(0, 0, At, B0); PG8_MMA(0, 1, At, B1); PG8_BAR; PG8_SCHED;
;             PG8_LDA(At, 0, 1); PG8_STAGE(PG8_SB(0, 0), b2, voffB); PG8_STAGE(PG8_SB(0, 1), b2 + hstep, voffB); PG8_STAGE(PG8_SA(0, 0), a2, voffA);
;             PG8_WAIT_V(8); PG8_WAIT_L(0); PG8_BAR; PG8_MMA(1, 0, At, B0); PG8_MMA(1, 1, At, B1); PG8_BAR; PG8_SCHED;
.LBB0_393:
	ds_read_b128 v[18:21], v190
	ds_read_b128 v[22:25], v190 offset:1024
	ds_read_b128 v[26:29], v190 offset:2048
	ds_read_b128 v[30:33], v190 offset:3072
	ds_read_b128 v[2:5], v191
	ds_read_b128 v[6:9], v191 offset:1024
	ds_read_b128 v[10:13], v191 offset:2048
	ds_read_b128 v[14:17], v191 offset:3072
	s_add_i32 s50, s22, 2
	s_add_u32 s20, s18, 0xfff50080
	s_addc_u32 s21, s19, -1
	s_cmp_eq_u32 s47, s22
	s_cselect_b32 s22, s14, s20
	s_cselect_b32 s23, s15, s21
	s_cselect_b32 s21, s17, s49
	s_cselect_b32 s20, s16, s48
	v_lshl_add_u64 v[218:219], s[18:19], 0, v[170:171]
	s_add_i32 m0, s26, 0xc000
	ds_read_b128 v[178:181], v192
	ds_read_b128 v[182:185], v192 offset:1024
	ds_read_b128 v[194:197], v192 offset:2048
	ds_read_b128 v[198:201], v192 offset:3072
	ds_read_b128 v[202:205], v192 offset:4096
	ds_read_b128 v[206:209], v192 offset:5120
	ds_read_b128 v[210:213], v192 offset:6144
	ds_read_b128 v[214:217], v192 offset:7168
	global_load_lds_dwordx4 v[218:219], off
	v_lshl_add_u64 v[218:219], s[18:19], 0, v[172:173]
	s_add_i32 m0, s26, 0xe000
	s_nop 0
	global_load_lds_dwordx4 v[218:219], off
	s_waitcnt vmcnt(8)
	s_waitcnt lgkmcnt(0)
	s_setprio 1
	s_barrier
	v_mfma_scale_f32_16x16x128_f8f6f4 v[158:161], v[18:25], v[178:185], v[158:161], v186, v186 op_sel_hi:[0,0,0]
	v_mfma_scale_f32_16x16x128_f8f6f4 v[154:157], v[26:33], v[178:185], v[154:157], v186, v186 op_sel_hi:[0,0,0]
	v_mfma_scale_f32_16x16x128_f8f6f4 v[150:153], v[18:25], v[194:201], v[150:153], v186, v186 op_sel_hi:[0,0,0]
	v_mfma_scale_f32_16x16x128_f8f6f4 v[142:145], v[26:33], v[194:201], v[142:145], v186, v186 op_sel_hi:[0,0,0]
	v_mfma_scale_f32_16x16x128_f8f6f4 v[134:137], v[18:25], v[202:209], v[134:137], v186, v186 op_sel_hi:[0,0,0]
	v_mfma_scale_f32_16x16x128_f8f6f4 v[126:129], v[26:33], v[202:209], v[126:129], v186, v186 op_sel_hi:[0,0,0]
	v_mfma_scale_f32_16x16x128_f8f6f4 v[118:121], v[18:25], v[210:217], v[118:121], v186, v186 op_sel_hi:[0,0,0]
	v_mfma_scale_f32_16x16x128_f8f6f4 v[110:113], v[26:33], v[210:217], v[110:113], v186, v186 op_sel_hi:[0,0,0]
	s_setprio 0
	s_setprio 1
	v_mfma_scale_f32_16x16x128_f8f6f4 v[146:149], v[2:9], v[178:185], v[146:149], v186, v186 op_sel_hi:[0,0,0]
	v_mfma_scale_f32_16x16x128_f8f6f4 v[138:141], v[10:17], v[178:185], v[138:141], v186, v186 op_sel_hi:[0,0,0]
	v_mfma_scale_f32_16x16x128_f8f6f4 v[130:133], v[2:9], v[194:201], v[130:133], v186, v186 op_sel_hi:[0,0,0]
	v_mfma_scale_f32_16x16x128_f8f6f4 v[122:125], v[10:17], v[194:201], v[122:125], v186, v186 op_sel_hi:[0,0,0]
	v_mfma_scale_f32_16x16x128_f8f6f4 v[114:117], v[2:9], v[202:209], v[114:117], v186, v186 op_sel_hi:[0,0,0]
	v_mfma_scale_f32_16x16x128_f8f6f4 v[106:109], v[10:17], v[202:209], v[106:109], v186, v186 op_sel_hi:[0,0,0]
	v_mfma_scale_f32_16x16x128_f8f6f4 v[102:105], v[2:9], v[210:217], v[102:105], v186, v186 op_sel_hi:[0,0,0]
	v_mfma_scale_f32_16x16x128_f8f6f4 v[98:101], v[10:17], v[210:217], v[98:101], v186, v186 op_sel_hi:[0,0,0]
	s_nop 3
	s_barrier
	s_setprio 0
	s_add_i32 s51, s37, s25
	v_lshl_add_u64 v[178:179], s[20:21], 0, v[164:165]
	s_mov_b32 m0, s51
	ds_read_b128 v[194:197], v192 offset:16384
	ds_read_b128 v[198:201], v192 offset:17408
	ds_read_b128 v[202:205], v192 offset:18432
	ds_read_b128 v[206:209], v192 offset:19456
	ds_read_b128 v[210:213], v192 offset:20480
	ds_read_b128 v[214:217], v192 offset:21504
	ds_read_b128 v[218:221], v192 offset:22528
	ds_read_b128 v[222:225], v192 offset:23552
	global_load_lds_dwordx4 v[178:179], off
	s_add_i32 m0, s51, 0x2000
	s_add_u32 s68, s20, 0xb0000
	v_lshl_add_u64 v[180:181], s[20:21], 0, v[168:169]
	s_addc_u32 s69, s21, 0
	s_add_i32 s51, s38, s25
	global_load_lds_dwordx4 v[180:181], off
	v_lshl_add_u64 v[182:183], s[68:69], 0, v[164:165]
	s_mov_b32 m0, s51
	v_lshl_add_u64 v[184:185], s[22:23], 0, v[166:167]
	global_load_lds_dwordx4 v[182:183], off
	v_lshl_add_u64 v[182:183], s[68:69], 0, v[168:169]
	s_add_i32 m0, s51, 0x2000
	s_nop 0
	global_load_lds_dwordx4 v[182:183], off
	v_lshl_add_u64 v[182:183], s[22:23], 0, v[162:163]
	s_mov_b32 m0, s26
	s_nop 0
	global_load_lds_dwordx4 v[182:183], off
	s_mov_b32 m0, s27
	s_nop 0
	global_load_lds_dwordx4 v[184:185], off
	s_waitcnt vmcnt(8)
	s_waitcnt lgkmcnt(0)
	s_setprio 1
	s_barrier
	v_mfma_scale_f32_16x16x128_f8f6f4 v[94:97], v[18:25], v[194:201], v[94:97], v186, v186 op_sel_hi:[0,0,0]
	v_mfma_scale_f32_16x16x128_f8f6f4 v[90:93], v[26:33], v[194:201], v[90:93], v186, v186 op_sel_hi:[0,0,0]
	v_mfma_scale_f32_16x16x128_f8f6f4 v[86:89], v[18:25], v[202:209], v[86:89], v186, v186 op_sel_hi:[0,0,0]
	v_mfma_scale_f32_16x16x128_f8f6f4 v[78:81], v[26:33], v[202:209], v[78:81], v186, v186 op_sel_hi:[0,0,0]
	v_mfma_scale_f32_16x16x128_f8f6f4 v[70:73], v[18:25], v[210:217], v[70:73], v186, v186 op_sel_hi:[0,0,0]
	v_mfma_scale_f32_16x16x128_f8f6f4 v[62:65], v[26:33], v[210:217], v[62:65], v186, v186 op_sel_hi:[0,0,0]
	v_mfma_scale_f32_16x16x128_f8f6f4 v[54:57], v[18:25], v[218:225], v[54:57], v186, v186 op_sel_hi:[0,0,0]
	v_mfma_scale_f32_16x16x128_f8f6f4 v[46:49], v[26:33], v[218:225], v[46:49], v186, v186 op_sel_hi:[0,0,0]
	s_setprio 0
	s_setprio 1
	v_mfma_scale_f32_16x16x128_f8f6f4 v[82:85], v[2:9], v[194:201], v[82:85], v186, v186 op_sel_hi:[0,0,0]
	v_mfma_scale_f32_16x16x128_f8f6f4 v[74:77], v[10:17], v[194:201], v[74:77], v186, v186 op_sel_hi:[0,0,0]
	v_mfma_scale_f32_16x16x128_f8f6f4 v[66:69], v[2:9], v[202:209], v[66:69], v186, v186 op_sel_hi:[0,0,0]
	v_mfma_scale_f32_16x16x128_f8f6f4 v[58:61], v[10:17], v[202:209], v[58:61], v186, v186 op_sel_hi:[0,0,0]
	v_mfma_scale_f32_16x16x128_f8f6f4 v[50:53], v[2:9], v[210:217], v[50:53], v186, v186 op_sel_hi:[0,0,0]
	v_mfma_scale_f32_16x16x128_f8f6f4 v[42:45], v[10:17], v[210:217], v[42:45], v186, v186 op_sel_hi:[0,0,0]
	v_mfma_scale_f32_16x16x128_f8f6f4 v[38:41], v[2:9], v[218:225], v[38:41], v186, v186 op_sel_hi:[0,0,0]
	v_mfma_scale_f32_16x16x128_f8f6f4 v[34:37], v[10:17], v[218:225], v[34:37], v186, v186 op_sel_hi:[0,0,0]
	s_nop 3
	s_barrier
; #define PG8_STAGE(bufoff, gbase, voff) do { _Pragma("unroll") for (int _i = 0; _i < 2; ++_i) \
;         __builtin_amdgcn_global_load_lds((const unsigned*)((const char*)(gbase) + (voff)[_i]), (PG8_LAS unsigned*)(lds + (bufoff) + ldsw + _i * 8192), 16, 0, 0); } while (0)
; #define PG8_WAIT_V(n) asm volatile("s_waitcnt vmcnt(" #n ")" ::: "memory")
; #define PG8_WAIT_L(n) asm volatile("s_waitcnt lgkmcnt(" #n ")" ::: "memory")
; #define PG8_BAR __builtin_amdgcn_s_barrier()
; #define PG8_SCHED __builtin_amdgcn_sched_barrier(0)
; template <class Epi, class Sched, bool ALIGN_EPI = true, bool SP2 = true>
; __device__ __forceinline__ void gemm_phase(PG8_LAS unsigned char* lds, const int K  , const Sched& S, const Epi& E) {
;     ...
;             PG8_LDB(B0, 1, 0); PG8_LDB(B1, 1, 1); PG8_SCHED; PG8_LDA(At, 1, 0); PG8_STAGE(PG8_SA(0, 1), a2 + hstep, voffA);
;             PG8_WAIT_V(8); PG8_WAIT_L(0); PG8_BAR; PG8_MMA(0, 0, At, B0); PG8_MMA(0, 1, At, B1); PG8_BAR; PG8_SCHED;
;             PG8_LDA(At, 1, 1); PG8_STAGE(PG8_SB(1, 0), b3, voffB); PG8_STAGE(PG8_SB(1, 1), b3 + hstep, voffB); PG8_STAGE(PG8_SA(1, 0), a3, voffA);
;             PG8_WAIT_V(8); PG8_WAIT_L(0); PG8_BAR; PG8_MMA(1, 0, At, B0); PG8_MMA(1, 1, At, B1); PG8_BAR; PG8_SCHED;
;     ...
;         if constexpr (Epi::FP8) asm volatile("s_nop 15\n\ts_nop 15\n\ts_nop 15\n\ts_nop 15\n\ts_nop 15" ::: "memory");
;         if constexpr (ALIGN_EPI) { if (wr == 0) PG8_BAR; }
	s_setprio 0
	s_add_i32 s51, 0, 0x18000
	s_add_i32 s68, 0, 0x1c000
	v_add_u32_e32 v14, s51, v188
	v_add_u32_e32 v30, s68, v188
	ds_read_b128 v[2:5], v14
	ds_read_b128 v[6:9], v14 offset:1024
	ds_read_b128 v[10:13], v14 offset:2048
	ds_read_b128 v[14:17], v14 offset:3072
	ds_read_b128 v[18:21], v30
	ds_read_b128 v[22:25], v30 offset:1024
	ds_read_b128 v[26:29], v30 offset:2048
	ds_read_b128 v[30:33], v30 offset:3072
	s_add_u32 s22, s22, 0xb0000
	s_addc_u32 s23, s23, 0
	s_mov_b32 m0, s28
	v_lshl_add_u64 v[226:227], s[22:23], 0, v[162:163]
	ds_read_b128 v[194:197], v192 offset:32768
	ds_read_b128 v[198:201], v192 offset:33792
	ds_read_b128 v[202:205], v192 offset:34816
	ds_read_b128 v[206:209], v192 offset:35840
	ds_read_b128 v[210:213], v192 offset:36864
	ds_read_b128 v[214:217], v192 offset:37888
	ds_read_b128 v[218:221], v192 offset:38912
	ds_read_b128 v[222:225], v192 offset:39936
	global_load_lds_dwordx4 v[226:227], off
	v_lshl_add_u64 v[226:227], s[22:23], 0, v[166:167]
	s_mov_b32 m0, s29
	s_nop 0
	global_load_lds_dwordx4 v[226:227], off
	s_waitcnt vmcnt(8)
	s_waitcnt lgkmcnt(0)
	s_setprio 1
	s_barrier
	v_mfma_scale_f32_16x16x128_f8f6f4 v[158:161], v[2:9], v[194:201], v[158:161], v186, v186 op_sel_hi:[0,0,0]
	v_mfma_scale_f32_16x16x128_f8f6f4 v[154:157], v[10:17], v[194:201], v[154:157], v186, v186 op_sel_hi:[0,0,0]
	v_mfma_scale_f32_16x16x128_f8f6f4 v[150:153], v[2:9], v[202:209], v[150:153], v186, v186 op_sel_hi:[0,0,0]
	v_mfma_scale_f32_16x16x128_f8f6f4 v[142:145], v[10:17], v[202:209], v[142:145], v186, v186 op_sel_hi:[0,0,0]
	v_mfma_scale_f32_16x16x128_f8f6f4 v[134:137], v[2:9], v[210:217], v[134:137], v186, v186 op_sel_hi:[0,0,0]
	v_mfma_scale_f32_16x16x128_f8f6f4 v[126:129], v[10:17], v[210:217], v[126:129], v186, v186 op_sel_hi:[0,0,0]
	v_mfma_scale_f32_16x16x128_f8f6f4 v[118:121], v[2:9], v[218:225], v[118:121], v186, v186 op_sel_hi:[0,0,0]
	v_mfma_scale_f32_16x16x128_f8f6f4 v[110:113], v[10:17], v[218:225], v[110:113], v186, v186 op_sel_hi:[0,0,0]
	s_setprio 0
	s_setprio 1
	v_mfma_scale_f32_16x16x128_f8f6f4 v[146:149], v[18:25], v[194:201], v[146:149], v186, v186 op_sel_hi:[0,0,0]
	v_mfma_scale_f32_16x16x128_f8f6f4 v[138:141], v[26:33], v[194:201], v[138:141], v186, v186 op_sel_hi:[0,0,0]
	v_mfma_scale_f32_16x16x128_f8f6f4 v[130:133], v[18:25], v[202:209], v[130:133], v186, v186 op_sel_hi:[0,0,0]
	v_mfma_scale_f32_16x16x128_f8f6f4 v[122:125], v[26:33], v[202:209], v[122:125], v186, v186 op_sel_hi:[0,0,0]
	v_mfma_scale_f32_16x16x128_f8f6f4 v[114:117], v[18:25], v[210:217], v[114:117], v186, v186 op_sel_hi:[0,0,0]
	v_mfma_scale_f32_16x16x128_f8f6f4 v[106:109], v[26:33], v[210:217], v[106:109], v186, v186 op_sel_hi:[0,0,0]
	v_mfma_scale_f32_16x16x128_f8f6f4 v[102:105], v[18:25], v[218:225], v[102:105], v186, v186 op_sel_hi:[0,0,0]
	v_mfma_scale_f32_16x16x128_f8f6f4 v[98:101], v[26:33], v[218:225], v[98:101], v186, v186 op_sel_hi:[0,0,0]
	s_nop 3
	s_barrier
	s_setprio 0
	s_add_i32 s22, s51, s25
	v_lshl_add_u64 v[178:179], v[178:179], 0, s[8:9]
	s_mov_b32 m0, s22
	ds_read_b128 v[194:197], v192 offset:49152
	ds_read_b128 v[198:201], v192 offset:50176
	ds_read_b128 v[202:205], v192 offset:51200
	ds_read_b128 v[206:209], v192 offset:52224
	ds_read_b128 v[210:213], v192 offset:53248
	ds_read_b128 v[214:217], v192 offset:54272
	ds_read_b128 v[218:221], v192 offset:55296
	ds_read_b128 v[222:225], v192 offset:56320
	global_load_lds_dwordx4 v[178:179], off
	s_add_i32 m0, s22, 0x2000
	s_add_u32 s20, s20, 0xb0080
	v_lshl_add_u64 v[178:179], v[180:181], 0, s[8:9]
	s_addc_u32 s21, s21, 0
	s_add_i32 s22, s68, s25
	global_load_lds_dwordx4 v[178:179], off
	v_lshl_add_u64 v[178:179], s[20:21], 0, v[164:165]
	s_mov_b32 m0, s22
	s_nop 0
	global_load_lds_dwordx4 v[178:179], off
	v_lshl_add_u64 v[178:179], s[20:21], 0, v[168:169]
	s_add_i32 m0, s22, 0x2000
	s_nop 0
	global_load_lds_dwordx4 v[178:179], off
	v_lshl_add_u64 v[178:179], v[182:183], 0, s[8:9]
	s_mov_b32 m0, s33
	s_nop 0
	global_load_lds_dwordx4 v[178:179], off
	v_lshl_add_u64 v[178:179], v[184:185], 0, s[8:9]
	s_mov_b32 m0, s34
	s_nop 0
	global_load_lds_dwordx4 v[178:179], off
	s_waitcnt vmcnt(8)
	s_waitcnt lgkmcnt(0)
	s_setprio 1
	s_barrier
	v_mfma_scale_f32_16x16x128_f8f6f4 v[94:97], v[2:9], v[194:201], v[94:97], v186, v186 op_sel_hi:[0,0,0]
	v_mfma_scale_f32_16x16x128_f8f6f4 v[90:93], v[10:17], v[194:201], v[90:93], v186, v186 op_sel_hi:[0,0,0]
	v_mfma_scale_f32_16x16x128_f8f6f4 v[86:89], v[2:9], v[202:209], v[86:89], v186, v186 op_sel_hi:[0,0,0]
	v_mfma_scale_f32_16x16x128_f8f6f4 v[78:81], v[10:17], v[202:209], v[78:81], v186, v186 op_sel_hi:[0,0,0]
	v_mfma_scale_f32_16x16x128_f8f6f4 v[70:73], v[2:9], v[210:217], v[70:73], v186, v186 op_sel_hi:[0,0,0]
	v_mfma_scale_f32_16x16x128_f8f6f4 v[62:65], v[10:17], v[210:217], v[62:65], v186, v186 op_sel_hi:[0,0,0]
	v_mfma_scale_f32_16x16x128_f8f6f4 v[54:57], v[2:9], v[218:225], v[54:57], v186, v186 op_sel_hi:[0,0,0]
	v_mfma_scale_f32_16x16x128_f8f6f4 v[46:49], v[10:17], v[218:225], v[46:49], v186, v186 op_sel_hi:[0,0,0]
	s_setprio 0
	s_setprio 1
	v_mfma_scale_f32_16x16x128_f8f6f4 v[82:85], v[18:25], v[194:201], v[82:85], v186, v186 op_sel_hi:[0,0,0]
	v_mfma_scale_f32_16x16x128_f8f6f4 v[74:77], v[26:33], v[194:201], v[74:77], v186, v186 op_sel_hi:[0,0,0]
	v_mfma_scale_f32_16x16x128_f8f6f4 v[66:69], v[18:25], v[202:209], v[66:69], v186, v186 op_sel_hi:[0,0,0]
	v_mfma_scale_f32_16x16x128_f8f6f4 v[58:61], v[26:33], v[202:209], v[58:61], v186, v186 op_sel_hi:[0,0,0]
	v_mfma_scale_f32_16x16x128_f8f6f4 v[50:53], v[18:25], v[210:217], v[50:53], v186, v186 op_sel_hi:[0,0,0]
	v_mfma_scale_f32_16x16x128_f8f6f4 v[42:45], v[26:33], v[210:217], v[42:45], v186, v186 op_sel_hi:[0,0,0]
	v_mfma_scale_f32_16x16x128_f8f6f4 v[38:41], v[18:25], v[218:225], v[38:41], v186, v186 op_sel_hi:[0,0,0]
	v_mfma_scale_f32_16x16x128_f8f6f4 v[34:37], v[26:33], v[218:225], v[34:37], v186, v186 op_sel_hi:[0,0,0]
	s_nop 3
	s_barrier
	s_setprio 0
	s_add_u32 s18, s18, 0x100
	s_addc_u32 s19, s19, 0
	s_add_u32 s48, s48, 0x100
	s_addc_u32 s49, s49, 0
	s_cmp_ge_u32 s50, s4
	s_mov_b32 s22, s50
	s_cbranch_scc0 .LBB0_393
	s_nop 15
	s_nop 15
	s_nop 15
	s_nop 15
	s_nop 15
	s_and_b64 vcc, exec, s[10:11]
	s_cbranch_vccz .LBB0_396
	s_barrier

; #define PG8_STAGE(bufoff, gbase, voff) do { _Pragma("unroll") for (int _i = 0; _i < 2; ++_i) \
;         __builtin_amdgcn_global_load_lds((const unsigned*)((const char*)(gbase) + (voff)[_i]), (PG8_LAS unsigned*)(lds + (bufoff) + ldsw + _i * 8192), 16, 0, 0); } while (0)
; #define PG8_WAIT_V(n) asm volatile("s_waitcnt vmcnt(" #n ")" ::: "memory")
; #define PG8_WAIT_L(n) asm volatile("s_waitcnt lgkmcnt(" #n ")" ::: "memory")
; #define PG8_BAR __builtin_amdgcn_s_barrier()
; #define PG8_SCHED __builtin_amdgcn_sched_barrier(0)
; template <class Epi, class Sched, bool ALIGN_EPI = true, bool SP2 = true>
; __device__ __forceinline__ void gemm_phase(PG8_LAS unsigned char* lds, const int K  , const Sched& S, const Epi& E) {
;     ...
;             PG8_LDB(B0, 0, 0); PG8_LDB(B1, 0, 1); PG8_SCHED; PG8_LDA(At, 0, 0); PG8_STAGE(PG8_SA(1, 1), a1 + hstep, voffA);
;             PG8_WAIT_V(8); PG8_WAIT_L(0); PG8_BAR; PG8_MMA(0, 0, At, B0); PG8_MMA(0, 1, At, B1); PG8_BAR; PG8_SCHED;
;             PG8_LDA(At, 0, 1); PG8_STAGE(PG8_SB(0, 0), b2, voffB); PG8_STAGE(PG8_SB(0, 1), b2 + hstep, voffB); PG8_STAGE(PG8_SA(0, 0), a2, voffA);
;             PG8_WAIT_V(8); PG8_WAIT_L(0); PG8_BAR; PG8_MMA(1, 0, At, B0); PG8_MMA(1, 1, At, B1); PG8_BAR; PG8_SCHED;
.LBB0_537:
	ds_read_b128 v[150:153], v156
	ds_read_b128 v[160:163], v156 offset:1024
	ds_read_b128 v[164:167], v156 offset:2048
	ds_read_b128 v[168:171], v156 offset:3072
	ds_read_b128 v[172:175], v157
	ds_read_b128 v[176:179], v157 offset:1024
	ds_read_b128 v[180:183], v157 offset:2048
	ds_read_b128 v[184:187], v157 offset:3072
	s_add_u32 s22, s20, 0xfff80080
	s_addc_u32 s23, s21, -1
	s_cmp_eq_u32 s47, 28
	s_cselect_b32 s25, s13, s23
	s_cselect_b32 s24, s19, s22
	s_cselect_b32 s23, s11, s46
	s_cselect_b32 s22, s44, s45
	v_lshl_add_u64 v[220:221], s[20:21], 0, v[142:143]
	s_add_i32 m0, s31, 0xc000
	ds_read_b128 v[188:191], v158
	ds_read_b128 v[192:195], v158 offset:1024
	ds_read_b128 v[196:199], v158 offset:2048
	ds_read_b128 v[200:203], v158 offset:3072
	ds_read_b128 v[204:207], v158 offset:4096
	ds_read_b128 v[208:211], v158 offset:5120
	ds_read_b128 v[212:215], v158 offset:6144
	ds_read_b128 v[216:219], v158 offset:7168
	global_load_lds_dwordx4 v[220:221], off
	v_lshl_add_u64 v[220:221], s[20:21], 0, v[144:145]
	s_add_i32 m0, s31, 0xe000
	s_nop 0
	global_load_lds_dwordx4 v[220:221], off
	s_waitcnt vmcnt(8)
	s_waitcnt lgkmcnt(0)
	s_setprio 1
	s_barrier
	v_mfma_f32_16x16x32_bf16 v[126:129], v[150:153], v[188:191], v[126:129]
	v_mfma_f32_16x16x32_bf16 v[122:125], v[164:167], v[188:191], v[122:125]
	v_mfma_f32_16x16x32_bf16 v[118:121], v[150:153], v[196:199], v[118:121]
	v_mfma_f32_16x16x32_bf16 v[110:113], v[164:167], v[196:199], v[110:113]
	v_mfma_f32_16x16x32_bf16 v[102:105], v[150:153], v[204:207], v[102:105]
	v_mfma_f32_16x16x32_bf16 v[94:97], v[164:167], v[204:207], v[94:97]
	v_mfma_f32_16x16x32_bf16 v[86:89], v[150:153], v[212:215], v[86:89]
	v_mfma_f32_16x16x32_bf16 v[78:81], v[164:167], v[212:215], v[78:81]
	v_mfma_f32_16x16x32_bf16 v[126:129], v[160:163], v[192:195], v[126:129]
	v_mfma_f32_16x16x32_bf16 v[122:125], v[168:171], v[192:195], v[122:125]
	v_mfma_f32_16x16x32_bf16 v[118:121], v[160:163], v[200:203], v[118:121]
	v_mfma_f32_16x16x32_bf16 v[110:113], v[168:171], v[200:203], v[110:113]
	v_mfma_f32_16x16x32_bf16 v[102:105], v[160:163], v[208:211], v[102:105]
	v_mfma_f32_16x16x32_bf16 v[94:97], v[168:171], v[208:211], v[94:97]
	v_mfma_f32_16x16x32_bf16 v[86:89], v[160:163], v[216:219], v[86:89]
	v_mfma_f32_16x16x32_bf16 v[78:81], v[168:171], v[216:219], v[78:81]
	s_setprio 0
	s_setprio 1
	v_mfma_f32_16x16x32_bf16 v[114:117], v[172:175], v[188:191], v[114:117]
	v_mfma_f32_16x16x32_bf16 v[106:109], v[180:183], v[188:191], v[106:109]
	v_mfma_f32_16x16x32_bf16 v[98:101], v[172:175], v[196:199], v[98:101]
	v_mfma_f32_16x16x32_bf16 v[90:93], v[180:183], v[196:199], v[90:93]
	v_mfma_f32_16x16x32_bf16 v[82:85], v[172:175], v[204:207], v[82:85]
	v_mfma_f32_16x16x32_bf16 v[74:77], v[180:183], v[204:207], v[74:77]
	v_mfma_f32_16x16x32_bf16 v[70:73], v[172:175], v[212:215], v[70:73]
	v_mfma_f32_16x16x32_bf16 v[66:69], v[180:183], v[212:215], v[66:69]
	v_mfma_f32_16x16x32_bf16 v[114:117], v[176:179], v[192:195], v[114:117]
	v_mfma_f32_16x16x32_bf16 v[106:109], v[184:187], v[192:195], v[106:109]
	v_mfma_f32_16x16x32_bf16 v[98:101], v[176:179], v[200:203], v[98:101]
	v_mfma_f32_16x16x32_bf16 v[90:93], v[184:187], v[200:203], v[90:93]
	v_mfma_f32_16x16x32_bf16 v[82:85], v[176:179], v[208:211], v[82:85]
	v_mfma_f32_16x16x32_bf16 v[74:77], v[184:187], v[208:211], v[74:77]
	v_mfma_f32_16x16x32_bf16 v[70:73], v[176:179], v[216:219], v[70:73]
	v_mfma_f32_16x16x32_bf16 v[66:69], v[184:187], v[216:219], v[66:69]
	s_nop 3
	s_barrier
	s_setprio 0
	s_add_i32 s48, s40, s29
	v_lshl_add_u64 v[220:221], s[22:23], 0, v[136:137]
	s_mov_b32 m0, s48
	ds_read_b128 v[188:191], v158 offset:16384
	ds_read_b128 v[192:195], v158 offset:17408
	ds_read_b128 v[196:199], v158 offset:18432
	ds_read_b128 v[200:203], v158 offset:19456
	ds_read_b128 v[204:207], v158 offset:20480
	ds_read_b128 v[208:211], v158 offset:21504
	ds_read_b128 v[212:215], v158 offset:22528
	ds_read_b128 v[216:219], v158 offset:23552
	global_load_lds_dwordx4 v[220:221], off
	s_add_i32 m0, s48, 0x2000
	s_add_u32 s48, s22, 0x80000
	v_lshl_add_u64 v[222:223], s[22:23], 0, v[132:133]
	s_addc_u32 s49, s23, 0
	s_add_i32 s50, s41, s29
	global_load_lds_dwordx4 v[222:223], off
	v_lshl_add_u64 v[224:225], s[48:49], 0, v[136:137]
	s_mov_b32 m0, s50
	v_lshl_add_u64 v[226:227], s[24:25], 0, v[134:135]
	global_load_lds_dwordx4 v[224:225], off
	v_lshl_add_u64 v[224:225], s[48:49], 0, v[132:133]
	s_add_i32 m0, s50, 0x2000
	s_nop 0
	global_load_lds_dwordx4 v[224:225], off
	v_lshl_add_u64 v[224:225], s[24:25], 0, v[138:139]
	s_mov_b32 m0, s31
	s_nop 0
	global_load_lds_dwordx4 v[224:225], off
	s_mov_b32 m0, s33
	s_nop 0
	global_load_lds_dwordx4 v[226:227], off
	s_waitcnt vmcnt(8)
	s_waitcnt lgkmcnt(0)
	s_setprio 1
	s_barrier
; #define PG8_STAGE(bufoff, gbase, voff) do { _Pragma("unroll") for (int _i = 0; _i < 2; ++_i) \
;         __builtin_amdgcn_global_load_lds((const unsigned*)((const char*)(gbase) + (voff)[_i]), (PG8_LAS unsigned*)(lds + (bufoff) + ldsw + _i * 8192), 16, 0, 0); } while (0)
; #define PG8_WAIT_V(n) asm volatile("s_waitcnt vmcnt(" #n ")" ::: "memory")
; #define PG8_WAIT_L(n) asm volatile("s_waitcnt lgkmcnt(" #n ")" ::: "memory")
; #define PG8_BAR __builtin_amdgcn_s_barrier()
; #define PG8_SCHED __builtin_amdgcn_sched_barrier(0)
; template <class Epi, class Sched, bool ALIGN_EPI = true, bool SP2 = true>
; __device__ __forceinline__ void gemm_phase(PG8_LAS unsigned char* lds, const int K  , const Sched& S, const Epi& E) {
;     ...
;             PG8_LDA(At, 0, 1); PG8_STAGE(PG8_SB(0, 0), b2, voffB); PG8_STAGE(PG8_SB(0, 1), b2 + hstep, voffB); PG8_STAGE(PG8_SA(0, 0), a2, voffA);
;             PG8_WAIT_V(8); PG8_WAIT_L(0); PG8_BAR; PG8_MMA(1, 0, At, B0); PG8_MMA(1, 1, At, B1); PG8_BAR; PG8_SCHED;
;             PG8_LDB(B0, 1, 0); PG8_LDB(B1, 1, 1); PG8_SCHED; PG8_LDA(At, 1, 0); PG8_STAGE(PG8_SA(0, 1), a2 + hstep, voffA);
;             PG8_WAIT_V(8); PG8_WAIT_L(0); PG8_BAR; PG8_MMA(0, 0, At, B0); PG8_MMA(0, 1, At, B1); PG8_BAR; PG8_SCHED;
	v_mfma_f32_16x16x32_bf16 v[62:65], v[150:153], v[188:191], v[62:65]
	v_mfma_f32_16x16x32_bf16 v[58:61], v[164:167], v[188:191], v[58:61]
	v_mfma_f32_16x16x32_bf16 v[54:57], v[150:153], v[196:199], v[54:57]
	v_mfma_f32_16x16x32_bf16 v[46:49], v[164:167], v[196:199], v[46:49]
	v_mfma_f32_16x16x32_bf16 v[38:41], v[150:153], v[204:207], v[38:41]
	v_mfma_f32_16x16x32_bf16 v[30:33], v[164:167], v[204:207], v[30:33]
	v_mfma_f32_16x16x32_bf16 v[22:25], v[150:153], v[212:215], v[22:25]
	v_mfma_f32_16x16x32_bf16 v[14:17], v[164:167], v[212:215], v[14:17]
	v_mfma_f32_16x16x32_bf16 v[62:65], v[160:163], v[192:195], v[62:65]
	v_mfma_f32_16x16x32_bf16 v[58:61], v[168:171], v[192:195], v[58:61]
	v_mfma_f32_16x16x32_bf16 v[54:57], v[160:163], v[200:203], v[54:57]
	v_mfma_f32_16x16x32_bf16 v[46:49], v[168:171], v[200:203], v[46:49]
	v_mfma_f32_16x16x32_bf16 v[38:41], v[160:163], v[208:211], v[38:41]
	v_mfma_f32_16x16x32_bf16 v[30:33], v[168:171], v[208:211], v[30:33]
	v_mfma_f32_16x16x32_bf16 v[22:25], v[160:163], v[216:219], v[22:25]
	v_mfma_f32_16x16x32_bf16 v[14:17], v[168:171], v[216:219], v[14:17]
	s_setprio 0
	s_setprio 1
	v_mfma_f32_16x16x32_bf16 v[50:53], v[172:175], v[188:191], v[50:53]
	v_mfma_f32_16x16x32_bf16 v[42:45], v[180:183], v[188:191], v[42:45]
	v_mfma_f32_16x16x32_bf16 v[34:37], v[172:175], v[196:199], v[34:37]
	v_mfma_f32_16x16x32_bf16 v[26:29], v[180:183], v[196:199], v[26:29]
	v_mfma_f32_16x16x32_bf16 v[18:21], v[172:175], v[204:207], v[18:21]
	v_mfma_f32_16x16x32_bf16 v[10:13], v[180:183], v[204:207], v[10:13]
	v_mfma_f32_16x16x32_bf16 v[6:9], v[172:175], v[212:215], v[6:9]
	v_mfma_f32_16x16x32_bf16 v[2:5], v[180:183], v[212:215], v[2:5]
	v_mfma_f32_16x16x32_bf16 v[50:53], v[176:179], v[192:195], v[50:53]
	v_mfma_f32_16x16x32_bf16 v[42:45], v[184:187], v[192:195], v[42:45]
	v_mfma_f32_16x16x32_bf16 v[34:37], v[176:179], v[200:203], v[34:37]
	v_mfma_f32_16x16x32_bf16 v[26:29], v[184:187], v[200:203], v[26:29]
	v_mfma_f32_16x16x32_bf16 v[18:21], v[176:179], v[208:211], v[18:21]
	v_mfma_f32_16x16x32_bf16 v[10:13], v[184:187], v[208:211], v[10:13]
	v_mfma_f32_16x16x32_bf16 v[6:9], v[176:179], v[216:219], v[6:9]
	v_mfma_f32_16x16x32_bf16 v[2:5], v[184:187], v[216:219], v[2:5]
	s_nop 3
	s_barrier
	s_setprio 0
	s_add_i32 s48, 0, 0x18000
	v_add_u32_e32 v140, s48, v154
	s_add_i32 s49, 0, 0x1c000
	ds_read_b128 v[150:153], v140
	ds_read_b128 v[160:163], v140 offset:1024
	ds_read_b128 v[164:167], v140 offset:2048
	ds_read_b128 v[168:171], v140 offset:3072
	v_add_u32_e32 v140, s49, v154
	ds_read_b128 v[172:175], v140
	ds_read_b128 v[176:179], v140 offset:1024
	ds_read_b128 v[180:183], v140 offset:2048
	ds_read_b128 v[184:187], v140 offset:3072
	s_add_u32 s24, s24, 0x80000
	s_addc_u32 s25, s25, 0
	s_mov_b32 m0, s34
	v_lshl_add_u64 v[230:231], s[24:25], 0, v[138:139]
	ds_read_b128 v[188:191], v158 offset:32768
	ds_read_b128 v[192:195], v158 offset:33792
	ds_read_b128 v[196:199], v158 offset:34816
	ds_read_b128 v[200:203], v158 offset:35840
	ds_read_b128 v[204:207], v158 offset:36864
	ds_read_b128 v[208:211], v158 offset:37888
	ds_read_b128 v[212:215], v158 offset:38912
	ds_read_b128 v[216:219], v158 offset:39936
	global_load_lds_dwordx4 v[230:231], off
	v_lshl_add_u64 v[230:231], s[24:25], 0, v[134:135]
	s_mov_b32 m0, s35
	s_nop 0
	global_load_lds_dwordx4 v[230:231], off
	s_waitcnt vmcnt(8)
	s_waitcnt lgkmcnt(0)
	s_setprio 1
	s_barrier
	v_mfma_f32_16x16x32_bf16 v[126:129], v[150:153], v[188:191], v[126:129]
	v_mfma_f32_16x16x32_bf16 v[122:125], v[164:167], v[188:191], v[122:125]
	v_mfma_f32_16x16x32_bf16 v[118:121], v[150:153], v[196:199], v[118:121]
	v_mfma_f32_16x16x32_bf16 v[110:113], v[164:167], v[196:199], v[110:113]
	v_mfma_f32_16x16x32_bf16 v[102:105], v[150:153], v[204:207], v[102:105]
	v_mfma_f32_16x16x32_bf16 v[94:97], v[164:167], v[204:207], v[94:97]
	v_mfma_f32_16x16x32_bf16 v[86:89], v[150:153], v[212:215], v[86:89]
	v_mfma_f32_16x16x32_bf16 v[78:81], v[164:167], v[212:215], v[78:81]
	v_mfma_f32_16x16x32_bf16 v[126:129], v[160:163], v[192:195], v[126:129]
	v_mfma_f32_16x16x32_bf16 v[122:125], v[168:171], v[192:195], v[122:125]
	v_mfma_f32_16x16x32_bf16 v[118:121], v[160:163], v[200:203], v[118:121]
	v_mfma_f32_16x16x32_bf16 v[110:113], v[168:171], v[200:203], v[110:113]
	v_mfma_f32_16x16x32_bf16 v[102:105], v[160:163], v[208:211], v[102:105]
	v_mfma_f32_16x16x32_bf16 v[94:97], v[168:171], v[208:211], v[94:97]
	v_mfma_f32_16x16x32_bf16 v[86:89], v[160:163], v[216:219], v[86:89]
	v_mfma_f32_16x16x32_bf16 v[78:81], v[168:171], v[216:219], v[78:81]
	s_setprio 0
	s_setprio 1
	v_mfma_f32_16x16x32_bf16 v[114:117], v[172:175], v[188:191], v[114:117]
	v_mfma_f32_16x16x32_bf16 v[106:109], v[180:183], v[188:191], v[106:109]
	v_mfma_f32_16x16x32_bf16 v[98:101], v[172:175], v[196:199], v[98:101]
	v_mfma_f32_16x16x32_bf16 v[90:93], v[180:183], v[196:199], v[90:93]
	v_mfma_f32_16x16x32_bf16 v[82:85], v[172:175], v[204:207], v[82:85]
	v_mfma_f32_16x16x32_bf16 v[74:77], v[180:183], v[204:207], v[74:77]
	v_mfma_f32_16x16x32_bf16 v[70:73], v[172:175], v[212:215], v[70:73]
	v_mfma_f32_16x16x32_bf16 v[66:69], v[180:183], v[212:215], v[66:69]
	v_mfma_f32_16x16x32_bf16 v[114:117], v[176:179], v[192:195], v[114:117]
	v_mfma_f32_16x16x32_bf16 v[106:109], v[184:187], v[192:195], v[106:109]
	v_mfma_f32_16x16x32_bf16 v[98:101], v[176:179], v[200:203], v[98:101]
	v_mfma_f32_16x16x32_bf16 v[90:93], v[184:187], v[200:203], v[90:93]
	v_mfma_f32_16x16x32_bf16 v[82:85], v[176:179], v[208:211], v[82:85]
	v_mfma_f32_16x16x32_bf16 v[74:77], v[184:187], v[208:211], v[74:77]
	v_mfma_f32_16x16x32_bf16 v[70:73], v[176:179], v[216:219], v[70:73]
	v_mfma_f32_16x16x32_bf16 v[66:69], v[184:187], v[216:219], v[66:69]
	s_nop 3
	s_barrier
; #define PG8_STAGE(bufoff, gbase, voff) do { _Pragma("unroll") for (int _i = 0; _i < 2; ++_i) \
;         __builtin_amdgcn_global_load_lds((const unsigned*)((const char*)(gbase) + (voff)[_i]), (PG8_LAS unsigned*)(lds + (bufoff) + ldsw + _i * 8192), 16, 0, 0); } while (0)
; #define PG8_WAIT_V(n) asm volatile("s_waitcnt vmcnt(" #n ")" ::: "memory")
; #define PG8_WAIT_L(n) asm volatile("s_waitcnt lgkmcnt(" #n ")" ::: "memory")
; #define PG8_BAR __builtin_amdgcn_s_barrier()
; #define PG8_SCHED __builtin_amdgcn_sched_barrier(0)
; template <class Epi, class Sched, bool ALIGN_EPI = true, bool SP2 = true>
; __device__ __forceinline__ void gemm_phase(PG8_LAS unsigned char* lds, const int K  , const Sched& S, const Epi& E) {
;     ...
;             PG8_LDA(At, 1, 1); PG8_STAGE(PG8_SB(1, 0), b3, voffB); PG8_STAGE(PG8_SB(1, 1), b3 + hstep, voffB); PG8_STAGE(PG8_SA(1, 0), a3, voffA);
;             PG8_WAIT_V(8); PG8_WAIT_L(0); PG8_BAR; PG8_MMA(1, 0, At, B0); PG8_MMA(1, 1, At, B1); PG8_BAR; PG8_SCHED;
	s_setprio 0
	s_add_i32 s24, s48, s29
	v_lshl_add_u64 v[220:221], v[220:221], 0, s[6:7]
	s_mov_b32 m0, s24
	ds_read_b128 v[188:191], v158 offset:49152
	ds_read_b128 v[192:195], v158 offset:50176
	ds_read_b128 v[196:199], v158 offset:51200
	ds_read_b128 v[200:203], v158 offset:52224
	ds_read_b128 v[204:207], v158 offset:53248
	ds_read_b128 v[208:211], v158 offset:54272
	ds_read_b128 v[212:215], v158 offset:55296
	ds_read_b128 v[216:219], v158 offset:56320
	global_load_lds_dwordx4 v[220:221], off
	s_add_i32 m0, s24, 0x2000
	s_add_u32 s22, s22, 0x80080
	v_lshl_add_u64 v[220:221], v[222:223], 0, s[6:7]
	s_addc_u32 s23, s23, 0
	s_add_i32 s24, s49, s29
	global_load_lds_dwordx4 v[220:221], off
	v_lshl_add_u64 v[220:221], s[22:23], 0, v[136:137]
	s_mov_b32 m0, s24
	s_nop 0
	global_load_lds_dwordx4 v[220:221], off
	v_lshl_add_u64 v[220:221], s[22:23], 0, v[132:133]
	s_add_i32 m0, s24, 0x2000
	s_nop 0
	global_load_lds_dwordx4 v[220:221], off
	v_lshl_add_u64 v[220:221], v[224:225], 0, s[6:7]
	s_mov_b32 m0, s37
	s_nop 0
	global_load_lds_dwordx4 v[220:221], off
	v_lshl_add_u64 v[220:221], v[226:227], 0, s[6:7]
	s_mov_b32 m0, s38
	s_nop 0
	global_load_lds_dwordx4 v[220:221], off
	s_waitcnt vmcnt(8)
	s_waitcnt lgkmcnt(0)
	s_setprio 1
	s_barrier
	v_mfma_f32_16x16x32_bf16 v[62:65], v[150:153], v[188:191], v[62:65]
	v_mfma_f32_16x16x32_bf16 v[58:61], v[164:167], v[188:191], v[58:61]
	v_mfma_f32_16x16x32_bf16 v[54:57], v[150:153], v[196:199], v[54:57]
	v_mfma_f32_16x16x32_bf16 v[46:49], v[164:167], v[196:199], v[46:49]
	v_mfma_f32_16x16x32_bf16 v[38:41], v[150:153], v[204:207], v[38:41]
	v_mfma_f32_16x16x32_bf16 v[30:33], v[164:167], v[204:207], v[30:33]
	v_mfma_f32_16x16x32_bf16 v[22:25], v[150:153], v[212:215], v[22:25]
	v_mfma_f32_16x16x32_bf16 v[14:17], v[164:167], v[212:215], v[14:17]
	v_mfma_f32_16x16x32_bf16 v[62:65], v[160:163], v[192:195], v[62:65]
	v_mfma_f32_16x16x32_bf16 v[58:61], v[168:171], v[192:195], v[58:61]
	v_mfma_f32_16x16x32_bf16 v[54:57], v[160:163], v[200:203], v[54:57]
	v_mfma_f32_16x16x32_bf16 v[46:49], v[168:171], v[200:203], v[46:49]
	v_mfma_f32_16x16x32_bf16 v[38:41], v[160:163], v[208:211], v[38:41]
	v_mfma_f32_16x16x32_bf16 v[30:33], v[168:171], v[208:211], v[30:33]
	v_mfma_f32_16x16x32_bf16 v[22:25], v[160:163], v[216:219], v[22:25]
	v_mfma_f32_16x16x32_bf16 v[14:17], v[168:171], v[216:219], v[14:17]
	s_setprio 0
	s_setprio 1
	v_mfma_f32_16x16x32_bf16 v[50:53], v[172:175], v[188:191], v[50:53]
	v_mfma_f32_16x16x32_bf16 v[42:45], v[180:183], v[188:191], v[42:45]
	v_mfma_f32_16x16x32_bf16 v[34:37], v[172:175], v[196:199], v[34:37]
	v_mfma_f32_16x16x32_bf16 v[26:29], v[180:183], v[196:199], v[26:29]
	v_mfma_f32_16x16x32_bf16 v[18:21], v[172:175], v[204:207], v[18:21]
	v_mfma_f32_16x16x32_bf16 v[10:13], v[180:183], v[204:207], v[10:13]
	v_mfma_f32_16x16x32_bf16 v[6:9], v[172:175], v[212:215], v[6:9]
	v_mfma_f32_16x16x32_bf16 v[2:5], v[180:183], v[212:215], v[2:5]
	v_mfma_f32_16x16x32_bf16 v[50:53], v[176:179], v[192:195], v[50:53]
	v_mfma_f32_16x16x32_bf16 v[42:45], v[184:187], v[192:195], v[42:45]
	v_mfma_f32_16x16x32_bf16 v[34:37], v[176:179], v[200:203], v[34:37]
	v_mfma_f32_16x16x32_bf16 v[26:29], v[184:187], v[200:203], v[26:29]
	v_mfma_f32_16x16x32_bf16 v[18:21], v[176:179], v[208:211], v[18:21]
	v_mfma_f32_16x16x32_bf16 v[10:13], v[184:187], v[208:211], v[10:13]
	v_mfma_f32_16x16x32_bf16 v[6:9], v[176:179], v[216:219], v[6:9]
	v_mfma_f32_16x16x32_bf16 v[2:5], v[184:187], v[216:219], v[2:5]
	s_nop 3
	s_barrier
	s_setprio 0
	s_add_i32 s47, s47, 2
	s_add_u32 s20, s20, 0x100
	s_addc_u32 s21, s21, 0
	s_add_u32 s45, s45, 0x100
	s_addc_u32 s46, s46, 0
	s_cmp_gt_u32 s47, 29
	s_cbranch_scc0 .LBB0_537
	s_and_b64 vcc, exec, s[8:9]
	s_cbranch_vccz .LBB0_540
	s_barrier

; #define PG8_STAGE(bufoff, gbase, voff) do { _Pragma("unroll") for (int _i = 0; _i < 2; ++_i) \
;         __builtin_amdgcn_global_load_lds((const unsigned*)((const char*)(gbase) + (voff)[_i]), (PG8_LAS unsigned*)(lds + (bufoff) + ldsw + _i * 8192), 16, 0, 0); } while (0)
; #define PG8_WAIT_V(n) asm volatile("s_waitcnt vmcnt(" #n ")" ::: "memory")
; #define PG8_WAIT_L(n) asm volatile("s_waitcnt lgkmcnt(" #n ")" ::: "memory")
; #define PG8_BAR __builtin_amdgcn_s_barrier()
; #define PG8_SCHED __builtin_amdgcn_sched_barrier(0)
; template <class Epi, class Sched, bool ALIGN_EPI = true, bool SP2 = true>
; __device__ __forceinline__ void gemm_phase(PG8_LAS unsigned char* lds, const int K  , const Sched& S, const Epi& E) {
;     ...
;             PG8_LDB(B0, 0, 0); PG8_LDB(B1, 0, 1); PG8_SCHED; PG8_LDA(At, 0, 0); PG8_STAGE(PG8_SA(1, 1), a1 + hstep, voffA);
;             PG8_WAIT_V(8); PG8_WAIT_L(0); PG8_BAR; PG8_MMA(0, 0, At, B0); PG8_MMA(0, 1, At, B1); PG8_BAR; PG8_SCHED;
;             PG8_LDA(At, 0, 1); PG8_STAGE(PG8_SB(0, 0), b2, voffB); PG8_STAGE(PG8_SB(0, 1), b2 + hstep, voffB); PG8_STAGE(PG8_SA(0, 0), a2, voffA);
.LBB0_955:
	s_waitcnt vmcnt(0)
	ds_read_b128 v[130:133], v232
	ds_read_b128 v[134:137], v232 offset:1024
	ds_read_b128 v[138:141], v232 offset:2048
	ds_read_b128 v[142:145], v232 offset:3072
	ds_read_b128 v[146:149], v233
	ds_read_b128 v[150:153], v233 offset:1024
	ds_read_b128 v[154:157], v233 offset:2048
	ds_read_b128 v[158:161], v233 offset:3072
	s_add_i32 s73, s28, 2
	s_add_u32 s26, s24, 0xfff80080
	s_addc_u32 s27, s25, -1
	s_cmp_eq_u32 s13, s28
	s_cselect_b32 s28, s16, s26
	s_cselect_b32 s29, s17, s27
	s_cselect_b32 s27, s19, s21
	s_cselect_b32 s26, s18, s15
	v_lshl_add_u64 v[194:195], s[24:25], 0, v[214:215]
	s_add_i32 m0, s23, 0xc000
	ds_read_b128 v[162:165], v234
	ds_read_b128 v[166:169], v234 offset:1024
	ds_read_b128 v[170:173], v234 offset:2048
	ds_read_b128 v[174:177], v234 offset:3072
	ds_read_b128 v[178:181], v234 offset:4096
	ds_read_b128 v[182:185], v234 offset:5120
	ds_read_b128 v[186:189], v234 offset:6144
	ds_read_b128 v[190:193], v234 offset:7168
	global_load_lds_dwordx4 v[194:195], off
	v_lshl_add_u64 v[194:195], s[24:25], 0, v[216:217]
	s_add_i32 m0, s23, 0xe000
	s_nop 0
	global_load_lds_dwordx4 v[194:195], off
	s_waitcnt vmcnt(8)
	s_waitcnt lgkmcnt(0)
	s_setprio 1
	s_barrier
	v_mfma_f32_16x16x32_bf16 v[126:129], v[130:133], v[162:165], v[126:129]
	v_mfma_f32_16x16x32_bf16 v[122:125], v[138:141], v[162:165], v[122:125]
	v_mfma_f32_16x16x32_bf16 v[118:121], v[130:133], v[170:173], v[118:121]
	v_mfma_f32_16x16x32_bf16 v[110:113], v[138:141], v[170:173], v[110:113]
	v_mfma_f32_16x16x32_bf16 v[102:105], v[130:133], v[178:181], v[102:105]
	v_mfma_f32_16x16x32_bf16 v[94:97], v[138:141], v[178:181], v[94:97]
	v_mfma_f32_16x16x32_bf16 v[86:89], v[130:133], v[186:189], v[86:89]
	v_mfma_f32_16x16x32_bf16 v[78:81], v[138:141], v[186:189], v[78:81]
	v_mfma_f32_16x16x32_bf16 v[126:129], v[134:137], v[166:169], v[126:129]
	v_mfma_f32_16x16x32_bf16 v[122:125], v[142:145], v[166:169], v[122:125]
	v_mfma_f32_16x16x32_bf16 v[118:121], v[134:137], v[174:177], v[118:121]
	v_mfma_f32_16x16x32_bf16 v[110:113], v[142:145], v[174:177], v[110:113]
	v_mfma_f32_16x16x32_bf16 v[102:105], v[134:137], v[182:185], v[102:105]
	v_mfma_f32_16x16x32_bf16 v[94:97], v[142:145], v[182:185], v[94:97]
	v_mfma_f32_16x16x32_bf16 v[86:89], v[134:137], v[190:193], v[86:89]
	v_mfma_f32_16x16x32_bf16 v[78:81], v[142:145], v[190:193], v[78:81]
	s_setprio 0
	s_setprio 1
	v_mfma_f32_16x16x32_bf16 v[114:117], v[146:149], v[162:165], v[114:117]
	v_mfma_f32_16x16x32_bf16 v[106:109], v[154:157], v[162:165], v[106:109]
	v_mfma_f32_16x16x32_bf16 v[98:101], v[146:149], v[170:173], v[98:101]
	v_mfma_f32_16x16x32_bf16 v[90:93], v[154:157], v[170:173], v[90:93]
	v_mfma_f32_16x16x32_bf16 v[82:85], v[146:149], v[178:181], v[82:85]
	v_mfma_f32_16x16x32_bf16 v[74:77], v[154:157], v[178:181], v[74:77]
	v_mfma_f32_16x16x32_bf16 v[70:73], v[146:149], v[186:189], v[70:73]
	v_mfma_f32_16x16x32_bf16 v[66:69], v[154:157], v[186:189], v[66:69]
	v_mfma_f32_16x16x32_bf16 v[114:117], v[150:153], v[166:169], v[114:117]
	v_mfma_f32_16x16x32_bf16 v[106:109], v[158:161], v[166:169], v[106:109]
	v_mfma_f32_16x16x32_bf16 v[98:101], v[150:153], v[174:177], v[98:101]
	v_mfma_f32_16x16x32_bf16 v[90:93], v[158:161], v[174:177], v[90:93]
	v_mfma_f32_16x16x32_bf16 v[82:85], v[150:153], v[182:185], v[82:85]
	v_mfma_f32_16x16x32_bf16 v[74:77], v[158:161], v[182:185], v[74:77]
	v_mfma_f32_16x16x32_bf16 v[70:73], v[150:153], v[190:193], v[70:73]
	v_mfma_f32_16x16x32_bf16 v[66:69], v[158:161], v[190:193], v[66:69]
	s_nop 3
	s_barrier
	s_setprio 0
	s_add_i32 s74, s47, s33
	v_lshl_add_u64 v[194:195], s[26:27], 0, v[208:209]
	s_mov_b32 m0, s74
	ds_read_b128 v[162:165], v234 offset:16384
	ds_read_b128 v[166:169], v234 offset:17408
	ds_read_b128 v[170:173], v234 offset:18432
	ds_read_b128 v[174:177], v234 offset:19456
	ds_read_b128 v[178:181], v234 offset:20480
	ds_read_b128 v[182:185], v234 offset:21504
	ds_read_b128 v[186:189], v234 offset:22528
	ds_read_b128 v[190:193], v234 offset:23552
	global_load_lds_dwordx4 v[194:195], off
	s_add_i32 m0, s74, 0x2000
	s_add_u32 s74, s26, 0x80000
	v_lshl_add_u64 v[196:197], s[26:27], 0, v[212:213]
	s_addc_u32 s75, s27, 0
	s_add_i32 s76, s48, s33
	global_load_lds_dwordx4 v[196:197], off
	v_lshl_add_u64 v[198:199], s[74:75], 0, v[208:209]
	s_mov_b32 m0, s76
	v_lshl_add_u64 v[200:201], s[28:29], 0, v[210:211]
	global_load_lds_dwordx4 v[198:199], off
	v_lshl_add_u64 v[198:199], s[74:75], 0, v[212:213]
	s_add_i32 m0, s76, 0x2000
	s_nop 0
	global_load_lds_dwordx4 v[198:199], off
	v_lshl_add_u64 v[198:199], s[28:29], 0, v[206:207]
	s_mov_b32 m0, s23
	s_nop 0
	global_load_lds_dwordx4 v[198:199], off
	s_mov_b32 m0, s34
	s_nop 0
	global_load_lds_dwordx4 v[200:201], off
	s_waitcnt vmcnt(8)
	s_waitcnt lgkmcnt(0)
	s_setprio 1
	s_barrier
; #define PG8_STAGE(bufoff, gbase, voff) do { _Pragma("unroll") for (int _i = 0; _i < 2; ++_i) \
;         __builtin_amdgcn_global_load_lds((const unsigned*)((const char*)(gbase) + (voff)[_i]), (PG8_LAS unsigned*)(lds + (bufoff) + ldsw + _i * 8192), 16, 0, 0); } while (0)
; #define PG8_WAIT_V(n) asm volatile("s_waitcnt vmcnt(" #n ")" ::: "memory")
; #define PG8_WAIT_L(n) asm volatile("s_waitcnt lgkmcnt(" #n ")" ::: "memory")
; #define PG8_BAR __builtin_amdgcn_s_barrier()
; #define PG8_SCHED __builtin_amdgcn_sched_barrier(0)
; template <class Epi, class Sched, bool ALIGN_EPI = true, bool SP2 = true>
; __device__ __forceinline__ void gemm_phase(PG8_LAS unsigned char* lds, const int K  , const Sched& S, const Epi& E) {
;     ...
;             PG8_WAIT_V(8); PG8_WAIT_L(0); PG8_BAR; PG8_MMA(1, 0, At, B0); PG8_MMA(1, 1, At, B1); PG8_BAR; PG8_SCHED;
;             PG8_LDB(B0, 1, 0); PG8_LDB(B1, 1, 1); PG8_SCHED; PG8_LDA(At, 1, 0); PG8_STAGE(PG8_SA(0, 1), a2 + hstep, voffA);
;             PG8_WAIT_V(8); PG8_WAIT_L(0); PG8_BAR; PG8_MMA(0, 0, At, B0); PG8_MMA(0, 1, At, B1); PG8_BAR; PG8_SCHED;
	v_mfma_f32_16x16x32_bf16 v[62:65], v[130:133], v[162:165], v[62:65]
	v_mfma_f32_16x16x32_bf16 v[58:61], v[138:141], v[162:165], v[58:61]
	v_mfma_f32_16x16x32_bf16 v[54:57], v[130:133], v[170:173], v[54:57]
	v_mfma_f32_16x16x32_bf16 v[46:49], v[138:141], v[170:173], v[46:49]
	v_mfma_f32_16x16x32_bf16 v[38:41], v[130:133], v[178:181], v[38:41]
	v_mfma_f32_16x16x32_bf16 v[30:33], v[138:141], v[178:181], v[30:33]
	v_mfma_f32_16x16x32_bf16 v[22:25], v[130:133], v[186:189], v[22:25]
	v_mfma_f32_16x16x32_bf16 v[14:17], v[138:141], v[186:189], v[14:17]
	v_mfma_f32_16x16x32_bf16 v[62:65], v[134:137], v[166:169], v[62:65]
	v_mfma_f32_16x16x32_bf16 v[58:61], v[142:145], v[166:169], v[58:61]
	v_mfma_f32_16x16x32_bf16 v[54:57], v[134:137], v[174:177], v[54:57]
	v_mfma_f32_16x16x32_bf16 v[46:49], v[142:145], v[174:177], v[46:49]
	v_mfma_f32_16x16x32_bf16 v[38:41], v[134:137], v[182:185], v[38:41]
	v_mfma_f32_16x16x32_bf16 v[30:33], v[142:145], v[182:185], v[30:33]
	v_mfma_f32_16x16x32_bf16 v[22:25], v[134:137], v[190:193], v[22:25]
	v_mfma_f32_16x16x32_bf16 v[14:17], v[142:145], v[190:193], v[14:17]
	s_setprio 0
	s_setprio 1
	v_mfma_f32_16x16x32_bf16 v[50:53], v[146:149], v[162:165], v[50:53]
	v_mfma_f32_16x16x32_bf16 v[42:45], v[154:157], v[162:165], v[42:45]
	v_mfma_f32_16x16x32_bf16 v[34:37], v[146:149], v[170:173], v[34:37]
	v_mfma_f32_16x16x32_bf16 v[26:29], v[154:157], v[170:173], v[26:29]
	v_mfma_f32_16x16x32_bf16 v[18:21], v[146:149], v[178:181], v[18:21]
	v_mfma_f32_16x16x32_bf16 v[10:13], v[154:157], v[178:181], v[10:13]
	v_mfma_f32_16x16x32_bf16 v[6:9], v[146:149], v[186:189], v[6:9]
	v_mfma_f32_16x16x32_bf16 v[2:5], v[154:157], v[186:189], v[2:5]
	v_mfma_f32_16x16x32_bf16 v[50:53], v[150:153], v[166:169], v[50:53]
	v_mfma_f32_16x16x32_bf16 v[42:45], v[158:161], v[166:169], v[42:45]
	v_mfma_f32_16x16x32_bf16 v[34:37], v[150:153], v[174:177], v[34:37]
	v_mfma_f32_16x16x32_bf16 v[26:29], v[158:161], v[174:177], v[26:29]
	v_mfma_f32_16x16x32_bf16 v[18:21], v[150:153], v[182:185], v[18:21]
	v_mfma_f32_16x16x32_bf16 v[10:13], v[158:161], v[182:185], v[10:13]
	v_mfma_f32_16x16x32_bf16 v[6:9], v[150:153], v[190:193], v[6:9]
	v_mfma_f32_16x16x32_bf16 v[2:5], v[158:161], v[190:193], v[2:5]
	s_nop 3
	s_barrier
	s_setprio 0
	s_add_i32 s74, 0, 0x18000
	s_add_i32 s75, 0, 0x1c000
	v_add_u32_e32 v142, s74, v230
	v_add_u32_e32 v158, s75, v230
	ds_read_b128 v[130:133], v142
	ds_read_b128 v[134:137], v142 offset:1024
	ds_read_b128 v[138:141], v142 offset:2048
	ds_read_b128 v[142:145], v142 offset:3072
	ds_read_b128 v[146:149], v158
	ds_read_b128 v[150:153], v158 offset:1024
	ds_read_b128 v[154:157], v158 offset:2048
	ds_read_b128 v[158:161], v158 offset:3072
	s_add_u32 s28, s28, 0x80000
	s_addc_u32 s29, s29, 0
	s_mov_b32 m0, s35
	v_lshl_add_u64 v[202:203], s[28:29], 0, v[206:207]
	ds_read_b128 v[162:165], v234 offset:32768
	ds_read_b128 v[166:169], v234 offset:33792
	ds_read_b128 v[170:173], v234 offset:34816
	ds_read_b128 v[174:177], v234 offset:35840
	ds_read_b128 v[178:181], v234 offset:36864
	ds_read_b128 v[182:185], v234 offset:37888
	ds_read_b128 v[186:189], v234 offset:38912
	ds_read_b128 v[190:193], v234 offset:39936
	global_load_lds_dwordx4 v[202:203], off
	v_lshl_add_u64 v[202:203], s[28:29], 0, v[210:211]
	s_mov_b32 m0, s36
	s_nop 0
	global_load_lds_dwordx4 v[202:203], off
	s_waitcnt vmcnt(8)
	s_waitcnt lgkmcnt(0)
	s_setprio 1
	s_barrier
	v_mfma_f32_16x16x32_bf16 v[126:129], v[130:133], v[162:165], v[126:129]
	v_mfma_f32_16x16x32_bf16 v[122:125], v[138:141], v[162:165], v[122:125]
	v_mfma_f32_16x16x32_bf16 v[118:121], v[130:133], v[170:173], v[118:121]
	v_mfma_f32_16x16x32_bf16 v[110:113], v[138:141], v[170:173], v[110:113]
	v_mfma_f32_16x16x32_bf16 v[102:105], v[130:133], v[178:181], v[102:105]
	v_mfma_f32_16x16x32_bf16 v[94:97], v[138:141], v[178:181], v[94:97]
	v_mfma_f32_16x16x32_bf16 v[86:89], v[130:133], v[186:189], v[86:89]
	v_mfma_f32_16x16x32_bf16 v[78:81], v[138:141], v[186:189], v[78:81]
	v_mfma_f32_16x16x32_bf16 v[126:129], v[134:137], v[166:169], v[126:129]
	v_mfma_f32_16x16x32_bf16 v[122:125], v[142:145], v[166:169], v[122:125]
	v_mfma_f32_16x16x32_bf16 v[118:121], v[134:137], v[174:177], v[118:121]
	v_mfma_f32_16x16x32_bf16 v[110:113], v[142:145], v[174:177], v[110:113]
	v_mfma_f32_16x16x32_bf16 v[102:105], v[134:137], v[182:185], v[102:105]
	v_mfma_f32_16x16x32_bf16 v[94:97], v[142:145], v[182:185], v[94:97]
	v_mfma_f32_16x16x32_bf16 v[86:89], v[134:137], v[190:193], v[86:89]
	v_mfma_f32_16x16x32_bf16 v[78:81], v[142:145], v[190:193], v[78:81]
	s_setprio 0
	s_setprio 1
	v_mfma_f32_16x16x32_bf16 v[114:117], v[146:149], v[162:165], v[114:117]
	v_mfma_f32_16x16x32_bf16 v[106:109], v[154:157], v[162:165], v[106:109]
	v_mfma_f32_16x16x32_bf16 v[98:101], v[146:149], v[170:173], v[98:101]
	v_mfma_f32_16x16x32_bf16 v[90:93], v[154:157], v[170:173], v[90:93]
	v_mfma_f32_16x16x32_bf16 v[82:85], v[146:149], v[178:181], v[82:85]
	v_mfma_f32_16x16x32_bf16 v[74:77], v[154:157], v[178:181], v[74:77]
	v_mfma_f32_16x16x32_bf16 v[70:73], v[146:149], v[186:189], v[70:73]
	v_mfma_f32_16x16x32_bf16 v[66:69], v[154:157], v[186:189], v[66:69]
	v_mfma_f32_16x16x32_bf16 v[114:117], v[150:153], v[166:169], v[114:117]
	v_mfma_f32_16x16x32_bf16 v[106:109], v[158:161], v[166:169], v[106:109]
	v_mfma_f32_16x16x32_bf16 v[98:101], v[150:153], v[174:177], v[98:101]
	v_mfma_f32_16x16x32_bf16 v[90:93], v[158:161], v[174:177], v[90:93]
	v_mfma_f32_16x16x32_bf16 v[82:85], v[150:153], v[182:185], v[82:85]
	v_mfma_f32_16x16x32_bf16 v[74:77], v[158:161], v[182:185], v[74:77]
	v_mfma_f32_16x16x32_bf16 v[70:73], v[150:153], v[190:193], v[70:73]
	v_mfma_f32_16x16x32_bf16 v[66:69], v[158:161], v[190:193], v[66:69]
	s_nop 3
	s_barrier
; #define PG8_STAGE(bufoff, gbase, voff) do { _Pragma("unroll") for (int _i = 0; _i < 2; ++_i) \
;         __builtin_amdgcn_global_load_lds((const unsigned*)((const char*)(gbase) + (voff)[_i]), (PG8_LAS unsigned*)(lds + (bufoff) + ldsw + _i * 8192), 16, 0, 0); } while (0)
; #define PG8_WAIT_V(n) asm volatile("s_waitcnt vmcnt(" #n ")" ::: "memory")
; #define PG8_WAIT_L(n) asm volatile("s_waitcnt lgkmcnt(" #n ")" ::: "memory")
; #define PG8_BAR __builtin_amdgcn_s_barrier()
; #define PG8_SCHED __builtin_amdgcn_sched_barrier(0)
; template <class Epi, class Sched, bool ALIGN_EPI = true, bool SP2 = true>
; __device__ __forceinline__ void gemm_phase(PG8_LAS unsigned char* lds, const int K  , const Sched& S, const Epi& E) {
;     ...
;             PG8_LDA(At, 1, 1); PG8_STAGE(PG8_SB(1, 0), b3, voffB); PG8_STAGE(PG8_SB(1, 1), b3 + hstep, voffB); PG8_STAGE(PG8_SA(1, 0), a3, voffA);
;             PG8_WAIT_V(8); PG8_WAIT_L(0); PG8_BAR; PG8_MMA(1, 0, At, B0); PG8_MMA(1, 1, At, B1); PG8_BAR; PG8_SCHED;
	s_setprio 0
	s_add_i32 s28, s74, s33
	v_lshl_add_u64 v[194:195], v[194:195], 0, s[8:9]
	s_mov_b32 m0, s28
	ds_read_b128 v[162:165], v234 offset:49152
	ds_read_b128 v[166:169], v234 offset:50176
	ds_read_b128 v[170:173], v234 offset:51200
	ds_read_b128 v[174:177], v234 offset:52224
	ds_read_b128 v[178:181], v234 offset:53248
	ds_read_b128 v[182:185], v234 offset:54272
	ds_read_b128 v[186:189], v234 offset:55296
	ds_read_b128 v[190:193], v234 offset:56320
	global_load_lds_dwordx4 v[194:195], off
	s_add_i32 m0, s28, 0x2000
	s_add_u32 s26, s26, 0x80080
	v_lshl_add_u64 v[194:195], v[196:197], 0, s[8:9]
	s_addc_u32 s27, s27, 0
	s_add_i32 s28, s75, s33
	global_load_lds_dwordx4 v[194:195], off
	v_lshl_add_u64 v[194:195], s[26:27], 0, v[208:209]
	s_mov_b32 m0, s28
	s_nop 0
	global_load_lds_dwordx4 v[194:195], off
	v_lshl_add_u64 v[194:195], s[26:27], 0, v[212:213]
	s_add_i32 m0, s28, 0x2000
	s_nop 0
	global_load_lds_dwordx4 v[194:195], off
	v_lshl_add_u64 v[194:195], v[198:199], 0, s[8:9]
	s_mov_b32 m0, s42
	s_nop 0
	global_load_lds_dwordx4 v[194:195], off
	v_lshl_add_u64 v[194:195], v[200:201], 0, s[8:9]
	s_mov_b32 m0, s43
	s_nop 0
	global_load_lds_dwordx4 v[194:195], off
	s_waitcnt vmcnt(8)
	s_waitcnt lgkmcnt(0)
	s_setprio 1
	s_barrier
	v_mfma_f32_16x16x32_bf16 v[62:65], v[130:133], v[162:165], v[62:65]
	v_mfma_f32_16x16x32_bf16 v[58:61], v[138:141], v[162:165], v[58:61]
	v_mfma_f32_16x16x32_bf16 v[54:57], v[130:133], v[170:173], v[54:57]
	v_mfma_f32_16x16x32_bf16 v[46:49], v[138:141], v[170:173], v[46:49]
	v_mfma_f32_16x16x32_bf16 v[38:41], v[130:133], v[178:181], v[38:41]
	v_mfma_f32_16x16x32_bf16 v[30:33], v[138:141], v[178:181], v[30:33]
	v_mfma_f32_16x16x32_bf16 v[22:25], v[130:133], v[186:189], v[22:25]
	v_mfma_f32_16x16x32_bf16 v[14:17], v[138:141], v[186:189], v[14:17]
	v_mfma_f32_16x16x32_bf16 v[62:65], v[134:137], v[166:169], v[62:65]
	v_mfma_f32_16x16x32_bf16 v[58:61], v[142:145], v[166:169], v[58:61]
	v_mfma_f32_16x16x32_bf16 v[54:57], v[134:137], v[174:177], v[54:57]
	v_mfma_f32_16x16x32_bf16 v[46:49], v[142:145], v[174:177], v[46:49]
	v_mfma_f32_16x16x32_bf16 v[38:41], v[134:137], v[182:185], v[38:41]
	v_mfma_f32_16x16x32_bf16 v[30:33], v[142:145], v[182:185], v[30:33]
	v_mfma_f32_16x16x32_bf16 v[22:25], v[134:137], v[190:193], v[22:25]
	v_mfma_f32_16x16x32_bf16 v[14:17], v[142:145], v[190:193], v[14:17]
	s_setprio 0
	s_setprio 1
	v_mfma_f32_16x16x32_bf16 v[50:53], v[146:149], v[162:165], v[50:53]
	v_mfma_f32_16x16x32_bf16 v[42:45], v[154:157], v[162:165], v[42:45]
	v_mfma_f32_16x16x32_bf16 v[34:37], v[146:149], v[170:173], v[34:37]
	v_mfma_f32_16x16x32_bf16 v[26:29], v[154:157], v[170:173], v[26:29]
	v_mfma_f32_16x16x32_bf16 v[18:21], v[146:149], v[178:181], v[18:21]
	v_mfma_f32_16x16x32_bf16 v[10:13], v[154:157], v[178:181], v[10:13]
	v_mfma_f32_16x16x32_bf16 v[6:9], v[146:149], v[186:189], v[6:9]
	v_mfma_f32_16x16x32_bf16 v[2:5], v[154:157], v[186:189], v[2:5]
	v_mfma_f32_16x16x32_bf16 v[50:53], v[150:153], v[166:169], v[50:53]
	v_mfma_f32_16x16x32_bf16 v[42:45], v[158:161], v[166:169], v[42:45]
	v_mfma_f32_16x16x32_bf16 v[34:37], v[150:153], v[174:177], v[34:37]
	v_mfma_f32_16x16x32_bf16 v[26:29], v[158:161], v[174:177], v[26:29]
	v_mfma_f32_16x16x32_bf16 v[18:21], v[150:153], v[182:185], v[18:21]
	v_mfma_f32_16x16x32_bf16 v[10:13], v[158:161], v[182:185], v[10:13]
	v_mfma_f32_16x16x32_bf16 v[6:9], v[150:153], v[190:193], v[6:9]
	v_mfma_f32_16x16x32_bf16 v[2:5], v[158:161], v[190:193], v[2:5]
	s_nop 3
	s_barrier
	s_setprio 0
	s_add_u32 s24, s24, 0x100
	s_addc_u32 s25, s25, 0
	s_add_u32 s15, s15, 0x100
	s_addc_u32 s21, s21, 0
	s_cmp_ge_u32 s73, s4
	s_mov_b32 s28, s73
	s_cbranch_scc0 .LBB0_955
	s_and_b64 vcc, exec, s[10:11]
	s_cbranch_vccz .LBB0_958
	s_barrier

; #define PG8_STAGE(bufoff, gbase, voff) do { _Pragma("unroll") for (int _i = 0; _i < 2; ++_i) \
;         __builtin_amdgcn_global_load_lds((const unsigned*)((const char*)(gbase) + (voff)[_i]), (PG8_LAS unsigned*)(lds + (bufoff) + ldsw + _i * 8192), 16, 0, 0); } while (0)
; #define PG8_WAIT_V(n) asm volatile("s_waitcnt vmcnt(" #n ")" ::: "memory")
; #define PG8_WAIT_L(n) asm volatile("s_waitcnt lgkmcnt(" #n ")" ::: "memory")
; #define PG8_BAR __builtin_amdgcn_s_barrier()
; #define PG8_SCHED __builtin_amdgcn_sched_barrier(0)
; template <class Epi, class Sched, bool ALIGN_EPI = true, bool SP2 = true>
; __device__ __forceinline__ void gemm_phase(PG8_LAS unsigned char* lds, const int K  , const Sched& S, const Epi& E) {
;     ...
;             PG8_LDB(B0, 0, 0); PG8_LDB(B1, 0, 1); PG8_SCHED; PG8_LDA(At, 0, 0); PG8_STAGE(PG8_SA(1, 1), a1 + hstep, voffA);
;             PG8_WAIT_V(8); PG8_WAIT_L(0); PG8_BAR; PG8_MMA(0, 0, At, B0); PG8_MMA(0, 1, At, B1); PG8_BAR; PG8_SCHED;
;             PG8_LDA(At, 0, 1); PG8_STAGE(PG8_SB(0, 0), b2, voffB); PG8_STAGE(PG8_SB(0, 1), b2 + hstep, voffB); PG8_STAGE(PG8_SA(0, 0), a2, voffA);
.LBB0_1099:
	ds_read_b128 v[148:151], v154
	ds_read_b128 v[160:163], v154 offset:1024
	ds_read_b128 v[164:167], v154 offset:2048
	ds_read_b128 v[168:171], v154 offset:3072
	ds_read_b128 v[172:175], v155
	ds_read_b128 v[176:179], v155 offset:1024
	ds_read_b128 v[180:183], v155 offset:2048
	ds_read_b128 v[184:187], v155 offset:3072
	s_add_u32 s24, s22, 0xfff80080
	s_addc_u32 s25, s23, -1
	s_cmp_eq_u32 s48, 28
	s_cselect_b32 s27, s15, s25
	s_cselect_b32 s26, s44, s24
	s_cselect_b32 s25, s11, s47
	s_cselect_b32 s24, s45, s46
	v_lshl_add_u64 v[220:221], s[22:23], 0, v[140:141]
	s_add_i32 m0, s21, 0xc000
	ds_read_b128 v[188:191], v156
	ds_read_b128 v[192:195], v156 offset:1024
	ds_read_b128 v[196:199], v156 offset:2048
	ds_read_b128 v[200:203], v156 offset:3072
	ds_read_b128 v[204:207], v156 offset:4096
	ds_read_b128 v[208:211], v156 offset:5120
	ds_read_b128 v[212:215], v156 offset:6144
	ds_read_b128 v[216:219], v156 offset:7168
	global_load_lds_dwordx4 v[220:221], off
	v_lshl_add_u64 v[220:221], s[22:23], 0, v[142:143]
	s_add_i32 m0, s21, 0xe000
	s_nop 0
	global_load_lds_dwordx4 v[220:221], off
	s_waitcnt vmcnt(8)
	s_waitcnt lgkmcnt(0)
	s_setprio 1
	s_barrier
	v_mfma_f32_16x16x32_bf16 v[126:129], v[148:151], v[188:191], v[126:129]
	v_mfma_f32_16x16x32_bf16 v[118:121], v[164:167], v[188:191], v[118:121]
	v_mfma_f32_16x16x32_bf16 v[110:113], v[148:151], v[196:199], v[110:113]
	v_mfma_f32_16x16x32_bf16 v[102:105], v[164:167], v[196:199], v[102:105]
	v_mfma_f32_16x16x32_bf16 v[94:97], v[148:151], v[204:207], v[94:97]
	v_mfma_f32_16x16x32_bf16 v[86:89], v[164:167], v[204:207], v[86:89]
	v_mfma_f32_16x16x32_bf16 v[78:81], v[148:151], v[212:215], v[78:81]
	v_mfma_f32_16x16x32_bf16 v[70:73], v[164:167], v[212:215], v[70:73]
	v_mfma_f32_16x16x32_bf16 v[126:129], v[160:163], v[192:195], v[126:129]
	v_mfma_f32_16x16x32_bf16 v[118:121], v[168:171], v[192:195], v[118:121]
	v_mfma_f32_16x16x32_bf16 v[110:113], v[160:163], v[200:203], v[110:113]
	v_mfma_f32_16x16x32_bf16 v[102:105], v[168:171], v[200:203], v[102:105]
	v_mfma_f32_16x16x32_bf16 v[94:97], v[160:163], v[208:211], v[94:97]
	v_mfma_f32_16x16x32_bf16 v[86:89], v[168:171], v[208:211], v[86:89]
	v_mfma_f32_16x16x32_bf16 v[78:81], v[160:163], v[216:219], v[78:81]
	v_mfma_f32_16x16x32_bf16 v[70:73], v[168:171], v[216:219], v[70:73]
	s_setprio 0
	s_setprio 1
	v_mfma_f32_16x16x32_bf16 v[122:125], v[172:175], v[188:191], v[122:125]
	v_mfma_f32_16x16x32_bf16 v[114:117], v[180:183], v[188:191], v[114:117]
	v_mfma_f32_16x16x32_bf16 v[106:109], v[172:175], v[196:199], v[106:109]
	v_mfma_f32_16x16x32_bf16 v[98:101], v[180:183], v[196:199], v[98:101]
	v_mfma_f32_16x16x32_bf16 v[90:93], v[172:175], v[204:207], v[90:93]
	v_mfma_f32_16x16x32_bf16 v[82:85], v[180:183], v[204:207], v[82:85]
	v_mfma_f32_16x16x32_bf16 v[74:77], v[172:175], v[212:215], v[74:77]
	v_mfma_f32_16x16x32_bf16 v[66:69], v[180:183], v[212:215], v[66:69]
	v_mfma_f32_16x16x32_bf16 v[122:125], v[176:179], v[192:195], v[122:125]
	v_mfma_f32_16x16x32_bf16 v[114:117], v[184:187], v[192:195], v[114:117]
	v_mfma_f32_16x16x32_bf16 v[106:109], v[176:179], v[200:203], v[106:109]
	v_mfma_f32_16x16x32_bf16 v[98:101], v[184:187], v[200:203], v[98:101]
	v_mfma_f32_16x16x32_bf16 v[90:93], v[176:179], v[208:211], v[90:93]
	v_mfma_f32_16x16x32_bf16 v[82:85], v[184:187], v[208:211], v[82:85]
	v_mfma_f32_16x16x32_bf16 v[74:77], v[176:179], v[216:219], v[74:77]
	v_mfma_f32_16x16x32_bf16 v[66:69], v[184:187], v[216:219], v[66:69]
	s_nop 3
	s_barrier
	s_setprio 0
	s_add_i32 s49, s39, s29
	v_lshl_add_u64 v[220:221], s[24:25], 0, v[136:137]
	s_mov_b32 m0, s49
	ds_read_b128 v[188:191], v156 offset:16384
	ds_read_b128 v[192:195], v156 offset:17408
	ds_read_b128 v[196:199], v156 offset:18432
	ds_read_b128 v[200:203], v156 offset:19456
	ds_read_b128 v[204:207], v156 offset:20480
	ds_read_b128 v[208:211], v156 offset:21504
	ds_read_b128 v[212:215], v156 offset:22528
	ds_read_b128 v[216:219], v156 offset:23552
	global_load_lds_dwordx4 v[220:221], off
	s_add_i32 m0, s49, 0x2000
	s_add_u32 s50, s24, 0x80000
	v_lshl_add_u64 v[222:223], s[24:25], 0, v[132:133]
	s_addc_u32 s51, s25, 0
	s_add_i32 s49, s40, s29
	global_load_lds_dwordx4 v[222:223], off
	v_lshl_add_u64 v[224:225], s[50:51], 0, v[136:137]
	s_mov_b32 m0, s49
	v_lshl_add_u64 v[226:227], s[26:27], 0, v[134:135]
	global_load_lds_dwordx4 v[224:225], off
	v_lshl_add_u64 v[224:225], s[50:51], 0, v[132:133]
	s_add_i32 m0, s49, 0x2000
	s_nop 0
	global_load_lds_dwordx4 v[224:225], off
	v_lshl_add_u64 v[224:225], s[26:27], 0, v[138:139]
	s_mov_b32 m0, s21
	s_nop 0
	global_load_lds_dwordx4 v[224:225], off
	s_mov_b32 m0, s31
	s_nop 0
	global_load_lds_dwordx4 v[226:227], off
	s_waitcnt vmcnt(8)
	s_waitcnt lgkmcnt(0)
	s_setprio 1
	s_barrier
; #define PG8_STAGE(bufoff, gbase, voff) do { _Pragma("unroll") for (int _i = 0; _i < 2; ++_i) \
;         __builtin_amdgcn_global_load_lds((const unsigned*)((const char*)(gbase) + (voff)[_i]), (PG8_LAS unsigned*)(lds + (bufoff) + ldsw + _i * 8192), 16, 0, 0); } while (0)
; #define PG8_WAIT_V(n) asm volatile("s_waitcnt vmcnt(" #n ")" ::: "memory")
; #define PG8_WAIT_L(n) asm volatile("s_waitcnt lgkmcnt(" #n ")" ::: "memory")
; #define PG8_BAR __builtin_amdgcn_s_barrier()
; #define PG8_SCHED __builtin_amdgcn_sched_barrier(0)
; template <class Epi, class Sched, bool ALIGN_EPI = true, bool SP2 = true>
; __device__ __forceinline__ void gemm_phase(PG8_LAS unsigned char* lds, const int K  , const Sched& S, const Epi& E) {
;     ...
;             PG8_WAIT_V(8); PG8_WAIT_L(0); PG8_BAR; PG8_MMA(1, 0, At, B0); PG8_MMA(1, 1, At, B1); PG8_BAR; PG8_SCHED;
;             PG8_LDB(B0, 1, 0); PG8_LDB(B1, 1, 1); PG8_SCHED; PG8_LDA(At, 1, 0); PG8_STAGE(PG8_SA(0, 1), a2 + hstep, voffA);
;             PG8_WAIT_V(8); PG8_WAIT_L(0); PG8_BAR; PG8_MMA(0, 0, At, B0); PG8_MMA(0, 1, At, B1); PG8_BAR; PG8_SCHED;
	v_mfma_f32_16x16x32_bf16 v[62:65], v[148:151], v[188:191], v[62:65]
	v_mfma_f32_16x16x32_bf16 v[54:57], v[164:167], v[188:191], v[54:57]
	v_mfma_f32_16x16x32_bf16 v[46:49], v[148:151], v[196:199], v[46:49]
	v_mfma_f32_16x16x32_bf16 v[38:41], v[164:167], v[196:199], v[38:41]
	v_mfma_f32_16x16x32_bf16 v[30:33], v[148:151], v[204:207], v[30:33]
	v_mfma_f32_16x16x32_bf16 v[22:25], v[164:167], v[204:207], v[22:25]
	v_mfma_f32_16x16x32_bf16 v[14:17], v[148:151], v[212:215], v[14:17]
	v_mfma_f32_16x16x32_bf16 v[6:9], v[164:167], v[212:215], v[6:9]
	v_mfma_f32_16x16x32_bf16 v[62:65], v[160:163], v[192:195], v[62:65]
	v_mfma_f32_16x16x32_bf16 v[54:57], v[168:171], v[192:195], v[54:57]
	v_mfma_f32_16x16x32_bf16 v[46:49], v[160:163], v[200:203], v[46:49]
	v_mfma_f32_16x16x32_bf16 v[38:41], v[168:171], v[200:203], v[38:41]
	v_mfma_f32_16x16x32_bf16 v[30:33], v[160:163], v[208:211], v[30:33]
	v_mfma_f32_16x16x32_bf16 v[22:25], v[168:171], v[208:211], v[22:25]
	v_mfma_f32_16x16x32_bf16 v[14:17], v[160:163], v[216:219], v[14:17]
	v_mfma_f32_16x16x32_bf16 v[6:9], v[168:171], v[216:219], v[6:9]
	s_setprio 0
	s_setprio 1
	v_mfma_f32_16x16x32_bf16 v[58:61], v[172:175], v[188:191], v[58:61]
	v_mfma_f32_16x16x32_bf16 v[50:53], v[180:183], v[188:191], v[50:53]
	v_mfma_f32_16x16x32_bf16 v[42:45], v[172:175], v[196:199], v[42:45]
	v_mfma_f32_16x16x32_bf16 v[34:37], v[180:183], v[196:199], v[34:37]
	v_mfma_f32_16x16x32_bf16 v[26:29], v[172:175], v[204:207], v[26:29]
	v_mfma_f32_16x16x32_bf16 v[18:21], v[180:183], v[204:207], v[18:21]
	v_mfma_f32_16x16x32_bf16 v[10:13], v[172:175], v[212:215], v[10:13]
	v_mfma_f32_16x16x32_bf16 v[2:5], v[180:183], v[212:215], v[2:5]
	v_mfma_f32_16x16x32_bf16 v[58:61], v[176:179], v[192:195], v[58:61]
	v_mfma_f32_16x16x32_bf16 v[50:53], v[184:187], v[192:195], v[50:53]
	v_mfma_f32_16x16x32_bf16 v[42:45], v[176:179], v[200:203], v[42:45]
	v_mfma_f32_16x16x32_bf16 v[34:37], v[184:187], v[200:203], v[34:37]
	v_mfma_f32_16x16x32_bf16 v[26:29], v[176:179], v[208:211], v[26:29]
	v_mfma_f32_16x16x32_bf16 v[18:21], v[184:187], v[208:211], v[18:21]
	v_mfma_f32_16x16x32_bf16 v[10:13], v[176:179], v[216:219], v[10:13]
	v_mfma_f32_16x16x32_bf16 v[2:5], v[184:187], v[216:219], v[2:5]
	s_nop 3
	s_barrier
	s_setprio 0
	s_add_i32 s49, 0, 0x18000
	v_add_u32_e32 v159, s49, v152
	s_add_i32 s50, 0, 0x1c000
	ds_read_b128 v[148:151], v159
	ds_read_b128 v[160:163], v159 offset:1024
	ds_read_b128 v[164:167], v159 offset:2048
	ds_read_b128 v[168:171], v159 offset:3072
	v_add_u32_e32 v159, s50, v152
	ds_read_b128 v[172:175], v159
	ds_read_b128 v[176:179], v159 offset:1024
	ds_read_b128 v[180:183], v159 offset:2048
	ds_read_b128 v[184:187], v159 offset:3072
	s_add_u32 s26, s26, 0x80000
	s_addc_u32 s27, s27, 0
	s_mov_b32 m0, s33
	v_lshl_add_u64 v[230:231], s[26:27], 0, v[138:139]
	ds_read_b128 v[188:191], v156 offset:32768
	ds_read_b128 v[192:195], v156 offset:33792
	ds_read_b128 v[196:199], v156 offset:34816
	ds_read_b128 v[200:203], v156 offset:35840
	ds_read_b128 v[204:207], v156 offset:36864
	ds_read_b128 v[208:211], v156 offset:37888
	ds_read_b128 v[212:215], v156 offset:38912
	ds_read_b128 v[216:219], v156 offset:39936
	global_load_lds_dwordx4 v[230:231], off
	v_lshl_add_u64 v[230:231], s[26:27], 0, v[134:135]
	s_mov_b32 m0, s34
	s_nop 0
	global_load_lds_dwordx4 v[230:231], off
	s_waitcnt vmcnt(8)
	s_waitcnt lgkmcnt(0)
	s_setprio 1
	s_barrier
	v_mfma_f32_16x16x32_bf16 v[126:129], v[148:151], v[188:191], v[126:129]
	v_mfma_f32_16x16x32_bf16 v[118:121], v[164:167], v[188:191], v[118:121]
	v_mfma_f32_16x16x32_bf16 v[110:113], v[148:151], v[196:199], v[110:113]
	v_mfma_f32_16x16x32_bf16 v[102:105], v[164:167], v[196:199], v[102:105]
	v_mfma_f32_16x16x32_bf16 v[94:97], v[148:151], v[204:207], v[94:97]
	v_mfma_f32_16x16x32_bf16 v[86:89], v[164:167], v[204:207], v[86:89]
	v_mfma_f32_16x16x32_bf16 v[78:81], v[148:151], v[212:215], v[78:81]
	v_mfma_f32_16x16x32_bf16 v[70:73], v[164:167], v[212:215], v[70:73]
	v_mfma_f32_16x16x32_bf16 v[126:129], v[160:163], v[192:195], v[126:129]
	v_mfma_f32_16x16x32_bf16 v[118:121], v[168:171], v[192:195], v[118:121]
	v_mfma_f32_16x16x32_bf16 v[110:113], v[160:163], v[200:203], v[110:113]
	v_mfma_f32_16x16x32_bf16 v[102:105], v[168:171], v[200:203], v[102:105]
	v_mfma_f32_16x16x32_bf16 v[94:97], v[160:163], v[208:211], v[94:97]
	v_mfma_f32_16x16x32_bf16 v[86:89], v[168:171], v[208:211], v[86:89]
	v_mfma_f32_16x16x32_bf16 v[78:81], v[160:163], v[216:219], v[78:81]
	v_mfma_f32_16x16x32_bf16 v[70:73], v[168:171], v[216:219], v[70:73]
	s_setprio 0
	s_setprio 1
	v_mfma_f32_16x16x32_bf16 v[122:125], v[172:175], v[188:191], v[122:125]
	v_mfma_f32_16x16x32_bf16 v[114:117], v[180:183], v[188:191], v[114:117]
	v_mfma_f32_16x16x32_bf16 v[106:109], v[172:175], v[196:199], v[106:109]
	v_mfma_f32_16x16x32_bf16 v[98:101], v[180:183], v[196:199], v[98:101]
	v_mfma_f32_16x16x32_bf16 v[90:93], v[172:175], v[204:207], v[90:93]
	v_mfma_f32_16x16x32_bf16 v[82:85], v[180:183], v[204:207], v[82:85]
	v_mfma_f32_16x16x32_bf16 v[74:77], v[172:175], v[212:215], v[74:77]
	v_mfma_f32_16x16x32_bf16 v[66:69], v[180:183], v[212:215], v[66:69]
	v_mfma_f32_16x16x32_bf16 v[122:125], v[176:179], v[192:195], v[122:125]
	v_mfma_f32_16x16x32_bf16 v[114:117], v[184:187], v[192:195], v[114:117]
	v_mfma_f32_16x16x32_bf16 v[106:109], v[176:179], v[200:203], v[106:109]
	v_mfma_f32_16x16x32_bf16 v[98:101], v[184:187], v[200:203], v[98:101]
	v_mfma_f32_16x16x32_bf16 v[90:93], v[176:179], v[208:211], v[90:93]
	v_mfma_f32_16x16x32_bf16 v[82:85], v[184:187], v[208:211], v[82:85]
	v_mfma_f32_16x16x32_bf16 v[74:77], v[176:179], v[216:219], v[74:77]
	v_mfma_f32_16x16x32_bf16 v[66:69], v[184:187], v[216:219], v[66:69]
	s_nop 3
	s_barrier
; #define PG8_STAGE(bufoff, gbase, voff) do { _Pragma("unroll") for (int _i = 0; _i < 2; ++_i) \
;         __builtin_amdgcn_global_load_lds((const unsigned*)((const char*)(gbase) + (voff)[_i]), (PG8_LAS unsigned*)(lds + (bufoff) + ldsw + _i * 8192), 16, 0, 0); } while (0)
; #define PG8_WAIT_V(n) asm volatile("s_waitcnt vmcnt(" #n ")" ::: "memory")
; #define PG8_WAIT_L(n) asm volatile("s_waitcnt lgkmcnt(" #n ")" ::: "memory")
; #define PG8_BAR __builtin_amdgcn_s_barrier()
; #define PG8_SCHED __builtin_amdgcn_sched_barrier(0)
; template <class Epi, class Sched, bool ALIGN_EPI = true, bool SP2 = true>
; __device__ __forceinline__ void gemm_phase(PG8_LAS unsigned char* lds, const int K  , const Sched& S, const Epi& E) {
;     ...
;             PG8_LDA(At, 1, 1); PG8_STAGE(PG8_SB(1, 0), b3, voffB); PG8_STAGE(PG8_SB(1, 1), b3 + hstep, voffB); PG8_STAGE(PG8_SA(1, 0), a3, voffA);
;             PG8_WAIT_V(8); PG8_WAIT_L(0); PG8_BAR; PG8_MMA(1, 0, At, B0); PG8_MMA(1, 1, At, B1); PG8_BAR; PG8_SCHED;
	s_setprio 0
	s_add_i32 s26, s49, s29
	v_lshl_add_u64 v[220:221], v[220:221], 0, s[4:5]
	s_mov_b32 m0, s26
	ds_read_b128 v[188:191], v156 offset:49152
	ds_read_b128 v[192:195], v156 offset:50176
	ds_read_b128 v[196:199], v156 offset:51200
	ds_read_b128 v[200:203], v156 offset:52224
	ds_read_b128 v[204:207], v156 offset:53248
	ds_read_b128 v[208:211], v156 offset:54272
	ds_read_b128 v[212:215], v156 offset:55296
	ds_read_b128 v[216:219], v156 offset:56320
	global_load_lds_dwordx4 v[220:221], off
	s_add_i32 m0, s26, 0x2000
	s_add_u32 s24, s24, 0x80080
	v_lshl_add_u64 v[220:221], v[222:223], 0, s[4:5]
	s_addc_u32 s25, s25, 0
	s_add_i32 s26, s50, s29
	global_load_lds_dwordx4 v[220:221], off
	v_lshl_add_u64 v[220:221], s[24:25], 0, v[136:137]
	s_mov_b32 m0, s26
	s_nop 0
	global_load_lds_dwordx4 v[220:221], off
	v_lshl_add_u64 v[220:221], s[24:25], 0, v[132:133]
	s_add_i32 m0, s26, 0x2000
	s_nop 0
	global_load_lds_dwordx4 v[220:221], off
	v_lshl_add_u64 v[220:221], v[224:225], 0, s[4:5]
	s_mov_b32 m0, s36
	s_nop 0
	global_load_lds_dwordx4 v[220:221], off
	v_lshl_add_u64 v[220:221], v[226:227], 0, s[4:5]
	s_mov_b32 m0, s37
	s_nop 0
	global_load_lds_dwordx4 v[220:221], off
	s_waitcnt vmcnt(8)
	s_waitcnt lgkmcnt(0)
	s_setprio 1
	s_barrier
	v_mfma_f32_16x16x32_bf16 v[62:65], v[148:151], v[188:191], v[62:65]
	v_mfma_f32_16x16x32_bf16 v[54:57], v[164:167], v[188:191], v[54:57]
	v_mfma_f32_16x16x32_bf16 v[46:49], v[148:151], v[196:199], v[46:49]
	v_mfma_f32_16x16x32_bf16 v[38:41], v[164:167], v[196:199], v[38:41]
	v_mfma_f32_16x16x32_bf16 v[30:33], v[148:151], v[204:207], v[30:33]
	v_mfma_f32_16x16x32_bf16 v[22:25], v[164:167], v[204:207], v[22:25]
	v_mfma_f32_16x16x32_bf16 v[14:17], v[148:151], v[212:215], v[14:17]
	v_mfma_f32_16x16x32_bf16 v[6:9], v[164:167], v[212:215], v[6:9]
	v_mfma_f32_16x16x32_bf16 v[62:65], v[160:163], v[192:195], v[62:65]
	v_mfma_f32_16x16x32_bf16 v[54:57], v[168:171], v[192:195], v[54:57]
	v_mfma_f32_16x16x32_bf16 v[46:49], v[160:163], v[200:203], v[46:49]
	v_mfma_f32_16x16x32_bf16 v[38:41], v[168:171], v[200:203], v[38:41]
	v_mfma_f32_16x16x32_bf16 v[30:33], v[160:163], v[208:211], v[30:33]
	v_mfma_f32_16x16x32_bf16 v[22:25], v[168:171], v[208:211], v[22:25]
	v_mfma_f32_16x16x32_bf16 v[14:17], v[160:163], v[216:219], v[14:17]
	v_mfma_f32_16x16x32_bf16 v[6:9], v[168:171], v[216:219], v[6:9]
	s_setprio 0
	s_setprio 1
	v_mfma_f32_16x16x32_bf16 v[58:61], v[172:175], v[188:191], v[58:61]
	v_mfma_f32_16x16x32_bf16 v[50:53], v[180:183], v[188:191], v[50:53]
	v_mfma_f32_16x16x32_bf16 v[42:45], v[172:175], v[196:199], v[42:45]
	v_mfma_f32_16x16x32_bf16 v[34:37], v[180:183], v[196:199], v[34:37]
	v_mfma_f32_16x16x32_bf16 v[26:29], v[172:175], v[204:207], v[26:29]
	v_mfma_f32_16x16x32_bf16 v[18:21], v[180:183], v[204:207], v[18:21]
	v_mfma_f32_16x16x32_bf16 v[10:13], v[172:175], v[212:215], v[10:13]
	v_mfma_f32_16x16x32_bf16 v[2:5], v[180:183], v[212:215], v[2:5]
	v_mfma_f32_16x16x32_bf16 v[58:61], v[176:179], v[192:195], v[58:61]
	v_mfma_f32_16x16x32_bf16 v[50:53], v[184:187], v[192:195], v[50:53]
	v_mfma_f32_16x16x32_bf16 v[42:45], v[176:179], v[200:203], v[42:45]
	v_mfma_f32_16x16x32_bf16 v[34:37], v[184:187], v[200:203], v[34:37]
	v_mfma_f32_16x16x32_bf16 v[26:29], v[176:179], v[208:211], v[26:29]
	v_mfma_f32_16x16x32_bf16 v[18:21], v[184:187], v[208:211], v[18:21]
	v_mfma_f32_16x16x32_bf16 v[10:13], v[176:179], v[216:219], v[10:13]
	v_mfma_f32_16x16x32_bf16 v[2:5], v[184:187], v[216:219], v[2:5]
	s_nop 3
	s_barrier
	s_setprio 0
	s_add_i32 s48, s48, 2
	s_add_u32 s22, s22, 0x100
	s_addc_u32 s23, s23, 0
	s_add_u32 s46, s46, 0x100
	s_addc_u32 s47, s47, 0
	s_cmp_gt_u32 s48, 29
	s_cbranch_scc0 .LBB0_1099
	s_and_b64 vcc, exec, s[8:9]
	s_cbranch_vccz .LBB0_1102
	s_barrier

; #define PG8_STAGE(bufoff, gbase, voff) do { _Pragma("unroll") for (int _i = 0; _i < 2; ++_i) \
;         __builtin_amdgcn_global_load_lds((const unsigned*)((const char*)(gbase) + (voff)[_i]), (PG8_LAS unsigned*)(lds + (bufoff) + ldsw + _i * 8192), 16, 0, 0); } while (0)
; #define PG8_WAIT_V(n) asm volatile("s_waitcnt vmcnt(" #n ")" ::: "memory")
; #define PG8_WAIT_L(n) asm volatile("s_waitcnt lgkmcnt(" #n ")" ::: "memory")
; #define PG8_BAR __builtin_amdgcn_s_barrier()
; #define PG8_SCHED __builtin_amdgcn_sched_barrier(0)
; template <class Epi, class Sched, bool ALIGN_EPI = true, bool SP2 = true>
; __device__ __forceinline__ void gemm_phase(PG8_LAS unsigned char* lds, const int K  , const Sched& S, const Epi& E) {
;     ...
;             PG8_LDB(B0, 0, 0); PG8_LDB(B1, 0, 1); PG8_SCHED; PG8_LDA(At, 0, 0); PG8_STAGE(PG8_SA(1, 1), a1 + hstep, voffA);
;             PG8_WAIT_V(8); PG8_WAIT_L(0); PG8_BAR; PG8_MMA(0, 0, At, B0); PG8_MMA(0, 1, At, B1); PG8_BAR; PG8_SCHED;
;             PG8_LDA(At, 0, 1); PG8_STAGE(PG8_SB(0, 0), b2, voffB); PG8_STAGE(PG8_SB(0, 1), b2 + hstep, voffB); PG8_STAGE(PG8_SA(0, 0), a2, voffA);
;             PG8_WAIT_V(8); PG8_WAIT_L(0); PG8_BAR; PG8_MMA(1, 0, At, B0); PG8_MMA(1, 1, At, B1); PG8_BAR; PG8_SCHED;
.LBB0_1304:
	ds_read_b128 v[18:21], v233
	ds_read_b128 v[22:25], v233 offset:1024
	ds_read_b128 v[26:29], v233 offset:2048
	ds_read_b128 v[30:33], v233 offset:3072
	ds_read_b128 v[2:5], v234
	ds_read_b128 v[6:9], v234 offset:1024
	ds_read_b128 v[10:13], v234 offset:2048
	ds_read_b128 v[14:17], v234 offset:3072
	s_add_i32 s74, s22, 2
	s_add_u32 s20, s18, 0xfff50080
	s_addc_u32 s21, s19, -1
	s_cmp_eq_u32 s71, s22
	s_cselect_b32 s22, s14, s20
	s_cselect_b32 s23, s15, s21
	s_cselect_b32 s21, s17, s73
	s_cselect_b32 s20, s16, s72
	v_lshl_add_u64 v[186:187], s[18:19], 0, v[198:199]
	s_add_i32 m0, s26, 0xc000
	ds_read_b128 v[162:165], v235
	ds_read_b128 v[166:169], v235 offset:1024
	ds_read_b128 v[170:173], v235 offset:2048
	ds_read_b128 v[174:177], v235 offset:3072
	ds_read_b128 v[178:181], v235 offset:4096
	ds_read_b128 v[182:185], v235 offset:5120
	ds_read_b128 v[206:209], v235 offset:6144
	ds_read_b128 v[210:213], v235 offset:7168
	global_load_lds_dwordx4 v[186:187], off
	v_lshl_add_u64 v[186:187], s[18:19], 0, v[200:201]
	s_add_i32 m0, s26, 0xe000
	s_nop 0
	global_load_lds_dwordx4 v[186:187], off
	s_waitcnt vmcnt(8)
	s_waitcnt lgkmcnt(0)
	s_setprio 1
	s_barrier
	v_mfma_scale_f32_16x16x128_f8f6f4 v[158:161], v[18:25], v[162:169], v[158:161], v229, v229 op_sel_hi:[0,0,0]
	v_mfma_scale_f32_16x16x128_f8f6f4 v[154:157], v[26:33], v[162:169], v[154:157], v229, v229 op_sel_hi:[0,0,0]
	v_mfma_scale_f32_16x16x128_f8f6f4 v[150:153], v[18:25], v[170:177], v[150:153], v229, v229 op_sel_hi:[0,0,0]
	v_mfma_scale_f32_16x16x128_f8f6f4 v[142:145], v[26:33], v[170:177], v[142:145], v229, v229 op_sel_hi:[0,0,0]
	v_mfma_scale_f32_16x16x128_f8f6f4 v[134:137], v[18:25], v[178:185], v[134:137], v229, v229 op_sel_hi:[0,0,0]
	v_mfma_scale_f32_16x16x128_f8f6f4 v[126:129], v[26:33], v[178:185], v[126:129], v229, v229 op_sel_hi:[0,0,0]
	v_mfma_scale_f32_16x16x128_f8f6f4 v[118:121], v[18:25], v[206:213], v[118:121], v229, v229 op_sel_hi:[0,0,0]
	v_mfma_scale_f32_16x16x128_f8f6f4 v[110:113], v[26:33], v[206:213], v[110:113], v229, v229 op_sel_hi:[0,0,0]
	s_setprio 0
	s_setprio 1
	v_mfma_scale_f32_16x16x128_f8f6f4 v[146:149], v[2:9], v[162:169], v[146:149], v229, v229 op_sel_hi:[0,0,0]
	v_mfma_scale_f32_16x16x128_f8f6f4 v[138:141], v[10:17], v[162:169], v[138:141], v229, v229 op_sel_hi:[0,0,0]
	v_mfma_scale_f32_16x16x128_f8f6f4 v[130:133], v[2:9], v[170:177], v[130:133], v229, v229 op_sel_hi:[0,0,0]
	v_mfma_scale_f32_16x16x128_f8f6f4 v[122:125], v[10:17], v[170:177], v[122:125], v229, v229 op_sel_hi:[0,0,0]
	v_mfma_scale_f32_16x16x128_f8f6f4 v[114:117], v[2:9], v[178:185], v[114:117], v229, v229 op_sel_hi:[0,0,0]
	v_mfma_scale_f32_16x16x128_f8f6f4 v[106:109], v[10:17], v[178:185], v[106:109], v229, v229 op_sel_hi:[0,0,0]
	v_mfma_scale_f32_16x16x128_f8f6f4 v[102:105], v[2:9], v[206:213], v[102:105], v229, v229 op_sel_hi:[0,0,0]
	v_mfma_scale_f32_16x16x128_f8f6f4 v[98:101], v[10:17], v[206:213], v[98:101], v229, v229 op_sel_hi:[0,0,0]
	s_nop 3
	s_barrier
	s_setprio 0
	s_add_i32 s75, s40, s25
	v_lshl_add_u64 v[162:163], s[20:21], 0, v[192:193]
	s_mov_b32 m0, s75
	ds_read_b128 v[170:173], v235 offset:16384
	ds_read_b128 v[174:177], v235 offset:17408
	ds_read_b128 v[178:181], v235 offset:18432
	ds_read_b128 v[182:185], v235 offset:19456
	ds_read_b128 v[206:209], v235 offset:20480
	ds_read_b128 v[210:213], v235 offset:21504
	ds_read_b128 v[214:217], v235 offset:22528
	ds_read_b128 v[218:221], v235 offset:23552
	global_load_lds_dwordx4 v[162:163], off
	s_add_i32 m0, s75, 0x2000
	s_add_u32 s76, s20, 0xb0000
	v_lshl_add_u64 v[164:165], s[20:21], 0, v[196:197]
	s_addc_u32 s77, s21, 0
	s_add_i32 s75, s41, s25
	global_load_lds_dwordx4 v[164:165], off
	v_lshl_add_u64 v[166:167], s[76:77], 0, v[192:193]
	s_mov_b32 m0, s75
	v_lshl_add_u64 v[168:169], s[22:23], 0, v[194:195]
	global_load_lds_dwordx4 v[166:167], off
	v_lshl_add_u64 v[166:167], s[76:77], 0, v[196:197]
	s_add_i32 m0, s75, 0x2000
	s_nop 0
	global_load_lds_dwordx4 v[166:167], off
	v_lshl_add_u64 v[166:167], s[22:23], 0, v[190:191]
	s_mov_b32 m0, s26
	s_nop 0
	global_load_lds_dwordx4 v[166:167], off
	s_mov_b32 m0, s27
	s_nop 0
	global_load_lds_dwordx4 v[168:169], off
	s_waitcnt vmcnt(8)
	s_waitcnt lgkmcnt(0)
	s_setprio 1
	s_barrier
	v_mfma_scale_f32_16x16x128_f8f6f4 v[94:97], v[18:25], v[170:177], v[94:97], v229, v229 op_sel_hi:[0,0,0]
	v_mfma_scale_f32_16x16x128_f8f6f4 v[90:93], v[26:33], v[170:177], v[90:93], v229, v229 op_sel_hi:[0,0,0]
	v_mfma_scale_f32_16x16x128_f8f6f4 v[86:89], v[18:25], v[178:185], v[86:89], v229, v229 op_sel_hi:[0,0,0]
	v_mfma_scale_f32_16x16x128_f8f6f4 v[78:81], v[26:33], v[178:185], v[78:81], v229, v229 op_sel_hi:[0,0,0]
	v_mfma_scale_f32_16x16x128_f8f6f4 v[70:73], v[18:25], v[206:213], v[70:73], v229, v229 op_sel_hi:[0,0,0]
	v_mfma_scale_f32_16x16x128_f8f6f4 v[62:65], v[26:33], v[206:213], v[62:65], v229, v229 op_sel_hi:[0,0,0]
	v_mfma_scale_f32_16x16x128_f8f6f4 v[54:57], v[18:25], v[214:221], v[54:57], v229, v229 op_sel_hi:[0,0,0]
	v_mfma_scale_f32_16x16x128_f8f6f4 v[46:49], v[26:33], v[214:221], v[46:49], v229, v229 op_sel_hi:[0,0,0]
	s_setprio 0
	s_setprio 1
	v_mfma_scale_f32_16x16x128_f8f6f4 v[82:85], v[2:9], v[170:177], v[82:85], v229, v229 op_sel_hi:[0,0,0]
	v_mfma_scale_f32_16x16x128_f8f6f4 v[74:77], v[10:17], v[170:177], v[74:77], v229, v229 op_sel_hi:[0,0,0]
	v_mfma_scale_f32_16x16x128_f8f6f4 v[66:69], v[2:9], v[178:185], v[66:69], v229, v229 op_sel_hi:[0,0,0]
	v_mfma_scale_f32_16x16x128_f8f6f4 v[58:61], v[10:17], v[178:185], v[58:61], v229, v229 op_sel_hi:[0,0,0]
	v_mfma_scale_f32_16x16x128_f8f6f4 v[50:53], v[2:9], v[206:213], v[50:53], v229, v229 op_sel_hi:[0,0,0]
	v_mfma_scale_f32_16x16x128_f8f6f4 v[42:45], v[10:17], v[206:213], v[42:45], v229, v229 op_sel_hi:[0,0,0]
	v_mfma_scale_f32_16x16x128_f8f6f4 v[38:41], v[2:9], v[214:221], v[38:41], v229, v229 op_sel_hi:[0,0,0]
	v_mfma_scale_f32_16x16x128_f8f6f4 v[34:37], v[10:17], v[214:221], v[34:37], v229, v229 op_sel_hi:[0,0,0]
	s_nop 3
	s_barrier
; #define PG8_STAGE(bufoff, gbase, voff) do { _Pragma("unroll") for (int _i = 0; _i < 2; ++_i) \
;         __builtin_amdgcn_global_load_lds((const unsigned*)((const char*)(gbase) + (voff)[_i]), (PG8_LAS unsigned*)(lds + (bufoff) + ldsw + _i * 8192), 16, 0, 0); } while (0)
; #define PG8_WAIT_V(n) asm volatile("s_waitcnt vmcnt(" #n ")" ::: "memory")
; #define PG8_WAIT_L(n) asm volatile("s_waitcnt lgkmcnt(" #n ")" ::: "memory")
; #define PG8_BAR __builtin_amdgcn_s_barrier()
; #define PG8_SCHED __builtin_amdgcn_sched_barrier(0)
; template <class Epi, class Sched, bool ALIGN_EPI = true, bool SP2 = true>
; __device__ __forceinline__ void gemm_phase(PG8_LAS unsigned char* lds, const int K  , const Sched& S, const Epi& E) {
;     ...
;             PG8_LDB(B0, 1, 0); PG8_LDB(B1, 1, 1); PG8_SCHED; PG8_LDA(At, 1, 0); PG8_STAGE(PG8_SA(0, 1), a2 + hstep, voffA);
;             PG8_WAIT_V(8); PG8_WAIT_L(0); PG8_BAR; PG8_MMA(0, 0, At, B0); PG8_MMA(0, 1, At, B1); PG8_BAR; PG8_SCHED;
;             PG8_LDA(At, 1, 1); PG8_STAGE(PG8_SB(1, 0), b3, voffB); PG8_STAGE(PG8_SB(1, 1), b3 + hstep, voffB); PG8_STAGE(PG8_SA(1, 0), a3, voffA);
;             PG8_WAIT_V(8); PG8_WAIT_L(0); PG8_BAR; PG8_MMA(1, 0, At, B0); PG8_MMA(1, 1, At, B1); PG8_BAR; PG8_SCHED;
;     ...
;         if constexpr (Epi::FP8) asm volatile("s_nop 15\n\ts_nop 15\n\ts_nop 15\n\ts_nop 15\n\ts_nop 15" ::: "memory");
	s_setprio 0
	s_add_i32 s75, 0, 0x18000
	s_add_i32 s76, 0, 0x1c000
	v_add_u32_e32 v14, s75, v231
	v_add_u32_e32 v30, s76, v231
	ds_read_b128 v[2:5], v14
	ds_read_b128 v[6:9], v14 offset:1024
	ds_read_b128 v[10:13], v14 offset:2048
	ds_read_b128 v[14:17], v14 offset:3072
	ds_read_b128 v[18:21], v30
	ds_read_b128 v[22:25], v30 offset:1024
	ds_read_b128 v[26:29], v30 offset:2048
	ds_read_b128 v[30:33], v30 offset:3072
	s_add_u32 s22, s22, 0xb0000
	s_addc_u32 s23, s23, 0
	s_mov_b32 m0, s28
	v_lshl_add_u64 v[186:187], s[22:23], 0, v[190:191]
	ds_read_b128 v[170:173], v235 offset:32768
	ds_read_b128 v[174:177], v235 offset:33792
	ds_read_b128 v[178:181], v235 offset:34816
	ds_read_b128 v[182:185], v235 offset:35840
	ds_read_b128 v[206:209], v235 offset:36864
	ds_read_b128 v[210:213], v235 offset:37888
	ds_read_b128 v[214:217], v235 offset:38912
	ds_read_b128 v[218:221], v235 offset:39936
	global_load_lds_dwordx4 v[186:187], off
	v_lshl_add_u64 v[186:187], s[22:23], 0, v[194:195]
	s_mov_b32 m0, s29
	s_nop 0
	global_load_lds_dwordx4 v[186:187], off
	s_waitcnt vmcnt(8)
	s_waitcnt lgkmcnt(0)
	s_setprio 1
	s_barrier
	v_mfma_scale_f32_16x16x128_f8f6f4 v[158:161], v[2:9], v[170:177], v[158:161], v229, v229 op_sel_hi:[0,0,0]
	v_mfma_scale_f32_16x16x128_f8f6f4 v[154:157], v[10:17], v[170:177], v[154:157], v229, v229 op_sel_hi:[0,0,0]
	v_mfma_scale_f32_16x16x128_f8f6f4 v[150:153], v[2:9], v[178:185], v[150:153], v229, v229 op_sel_hi:[0,0,0]
	v_mfma_scale_f32_16x16x128_f8f6f4 v[142:145], v[10:17], v[178:185], v[142:145], v229, v229 op_sel_hi:[0,0,0]
	v_mfma_scale_f32_16x16x128_f8f6f4 v[134:137], v[2:9], v[206:213], v[134:137], v229, v229 op_sel_hi:[0,0,0]
	v_mfma_scale_f32_16x16x128_f8f6f4 v[126:129], v[10:17], v[206:213], v[126:129], v229, v229 op_sel_hi:[0,0,0]
	v_mfma_scale_f32_16x16x128_f8f6f4 v[118:121], v[2:9], v[214:221], v[118:121], v229, v229 op_sel_hi:[0,0,0]
	v_mfma_scale_f32_16x16x128_f8f6f4 v[110:113], v[10:17], v[214:221], v[110:113], v229, v229 op_sel_hi:[0,0,0]
	s_setprio 0
	s_setprio 1
	v_mfma_scale_f32_16x16x128_f8f6f4 v[146:149], v[18:25], v[170:177], v[146:149], v229, v229 op_sel_hi:[0,0,0]
	v_mfma_scale_f32_16x16x128_f8f6f4 v[138:141], v[26:33], v[170:177], v[138:141], v229, v229 op_sel_hi:[0,0,0]
	v_mfma_scale_f32_16x16x128_f8f6f4 v[130:133], v[18:25], v[178:185], v[130:133], v229, v229 op_sel_hi:[0,0,0]
	v_mfma_scale_f32_16x16x128_f8f6f4 v[122:125], v[26:33], v[178:185], v[122:125], v229, v229 op_sel_hi:[0,0,0]
	v_mfma_scale_f32_16x16x128_f8f6f4 v[114:117], v[18:25], v[206:213], v[114:117], v229, v229 op_sel_hi:[0,0,0]
	v_mfma_scale_f32_16x16x128_f8f6f4 v[106:109], v[26:33], v[206:213], v[106:109], v229, v229 op_sel_hi:[0,0,0]
	v_mfma_scale_f32_16x16x128_f8f6f4 v[102:105], v[18:25], v[214:221], v[102:105], v229, v229 op_sel_hi:[0,0,0]
	v_mfma_scale_f32_16x16x128_f8f6f4 v[98:101], v[26:33], v[214:221], v[98:101], v229, v229 op_sel_hi:[0,0,0]
	s_nop 3
	s_barrier
	s_setprio 0
	s_add_i32 s22, s75, s25
	v_lshl_add_u64 v[162:163], v[162:163], 0, s[8:9]
	s_mov_b32 m0, s22
	ds_read_b128 v[170:173], v235 offset:49152
	ds_read_b128 v[174:177], v235 offset:50176
	ds_read_b128 v[178:181], v235 offset:51200
	ds_read_b128 v[182:185], v235 offset:52224
	ds_read_b128 v[206:209], v235 offset:53248
	ds_read_b128 v[210:213], v235 offset:54272
	ds_read_b128 v[214:217], v235 offset:55296
	ds_read_b128 v[218:221], v235 offset:56320
	global_load_lds_dwordx4 v[162:163], off
	s_add_i32 m0, s22, 0x2000
	s_add_u32 s20, s20, 0xb0080
	v_lshl_add_u64 v[162:163], v[164:165], 0, s[8:9]
	s_addc_u32 s21, s21, 0
	s_add_i32 s22, s76, s25
	global_load_lds_dwordx4 v[162:163], off
	v_lshl_add_u64 v[162:163], s[20:21], 0, v[192:193]
	s_mov_b32 m0, s22
	s_nop 0
	global_load_lds_dwordx4 v[162:163], off
	v_lshl_add_u64 v[162:163], s[20:21], 0, v[196:197]
	s_add_i32 m0, s22, 0x2000
	s_nop 0
	global_load_lds_dwordx4 v[162:163], off
	v_lshl_add_u64 v[162:163], v[166:167], 0, s[8:9]
	s_mov_b32 m0, s36
	s_nop 0
	global_load_lds_dwordx4 v[162:163], off
	v_lshl_add_u64 v[162:163], v[168:169], 0, s[8:9]
	s_mov_b32 m0, s37
	s_nop 0
	global_load_lds_dwordx4 v[162:163], off
	s_waitcnt vmcnt(8)
	s_waitcnt lgkmcnt(0)
	s_setprio 1
	s_barrier
	v_mfma_scale_f32_16x16x128_f8f6f4 v[94:97], v[2:9], v[170:177], v[94:97], v229, v229 op_sel_hi:[0,0,0]
	v_mfma_scale_f32_16x16x128_f8f6f4 v[90:93], v[10:17], v[170:177], v[90:93], v229, v229 op_sel_hi:[0,0,0]
	v_mfma_scale_f32_16x16x128_f8f6f4 v[86:89], v[2:9], v[178:185], v[86:89], v229, v229 op_sel_hi:[0,0,0]
	v_mfma_scale_f32_16x16x128_f8f6f4 v[78:81], v[10:17], v[178:185], v[78:81], v229, v229 op_sel_hi:[0,0,0]
	v_mfma_scale_f32_16x16x128_f8f6f4 v[70:73], v[2:9], v[206:213], v[70:73], v229, v229 op_sel_hi:[0,0,0]
	v_mfma_scale_f32_16x16x128_f8f6f4 v[62:65], v[10:17], v[206:213], v[62:65], v229, v229 op_sel_hi:[0,0,0]
	v_mfma_scale_f32_16x16x128_f8f6f4 v[54:57], v[2:9], v[214:221], v[54:57], v229, v229 op_sel_hi:[0,0,0]
	v_mfma_scale_f32_16x16x128_f8f6f4 v[46:49], v[10:17], v[214:221], v[46:49], v229, v229 op_sel_hi:[0,0,0]
	s_setprio 0
	s_setprio 1
	v_mfma_scale_f32_16x16x128_f8f6f4 v[82:85], v[18:25], v[170:177], v[82:85], v229, v229 op_sel_hi:[0,0,0]
	v_mfma_scale_f32_16x16x128_f8f6f4 v[74:77], v[26:33], v[170:177], v[74:77], v229, v229 op_sel_hi:[0,0,0]
	v_mfma_scale_f32_16x16x128_f8f6f4 v[66:69], v[18:25], v[178:185], v[66:69], v229, v229 op_sel_hi:[0,0,0]
	v_mfma_scale_f32_16x16x128_f8f6f4 v[58:61], v[26:33], v[178:185], v[58:61], v229, v229 op_sel_hi:[0,0,0]
	v_mfma_scale_f32_16x16x128_f8f6f4 v[50:53], v[18:25], v[206:213], v[50:53], v229, v229 op_sel_hi:[0,0,0]
	v_mfma_scale_f32_16x16x128_f8f6f4 v[42:45], v[26:33], v[206:213], v[42:45], v229, v229 op_sel_hi:[0,0,0]
	v_mfma_scale_f32_16x16x128_f8f6f4 v[38:41], v[18:25], v[214:221], v[38:41], v229, v229 op_sel_hi:[0,0,0]
	v_mfma_scale_f32_16x16x128_f8f6f4 v[34:37], v[26:33], v[214:221], v[34:37], v229, v229 op_sel_hi:[0,0,0]
	s_nop 3
	s_barrier
	s_setprio 0
	s_add_u32 s18, s18, 0x100
	s_addc_u32 s19, s19, 0
	s_add_u32 s72, s72, 0x100
	s_addc_u32 s73, s73, 0
	s_cmp_ge_u32 s74, s4
	s_mov_b32 s22, s74
	s_cbranch_scc0 .LBB0_1304
	s_nop 15
	s_nop 15
	s_nop 15
	s_nop 15
	s_nop 15
	s_and_b64 vcc, exec, s[10:11]
	s_cbranch_vccz .LBB0_1307
	s_barrier

; #define PG8_STAGE(bufoff, gbase, voff) do { _Pragma("unroll") for (int _i = 0; _i < 2; ++_i) \
;         __builtin_amdgcn_global_load_lds((const unsigned*)((const char*)(gbase) + (voff)[_i]), (PG8_LAS unsigned*)(lds + (bufoff) + ldsw + _i * 8192), 16, 0, 0); } while (0)
; #define PG8_WAIT_V(n) asm volatile("s_waitcnt vmcnt(" #n ")" ::: "memory")
; #define PG8_WAIT_L(n) asm volatile("s_waitcnt lgkmcnt(" #n ")" ::: "memory")
; #define PG8_BAR __builtin_amdgcn_s_barrier()
; #define PG8_SCHED __builtin_amdgcn_sched_barrier(0)
; template <class Epi, class Sched, bool ALIGN_EPI = true, bool SP2 = true>
; __device__ __forceinline__ void gemm_phase(PG8_LAS unsigned char* lds, const int K  , const Sched& S, const Epi& E) {
;     ...
;             PG8_LDB(B0, 0, 0); PG8_LDB(B1, 0, 1); PG8_SCHED; PG8_LDA(At, 0, 0); PG8_STAGE(PG8_SA(1, 1), a1 + hstep, voffA);
;             PG8_WAIT_V(8); PG8_WAIT_L(0); PG8_BAR; PG8_MMA(0, 0, At, B0); PG8_MMA(0, 1, At, B1); PG8_BAR; PG8_SCHED;
;             PG8_LDA(At, 0, 1); PG8_STAGE(PG8_SB(0, 0), b2, voffB); PG8_STAGE(PG8_SB(0, 1), b2 + hstep, voffB); PG8_STAGE(PG8_SA(0, 0), a2, voffA);
.LBB0_1448:
	ds_read_b128 v[148:151], v154
	ds_read_b128 v[160:163], v154 offset:1024
	ds_read_b128 v[164:167], v154 offset:2048
	ds_read_b128 v[168:171], v154 offset:3072
	ds_read_b128 v[172:175], v155
	ds_read_b128 v[176:179], v155 offset:1024
	ds_read_b128 v[180:183], v155 offset:2048
	ds_read_b128 v[184:187], v155 offset:3072
	s_add_u32 s26, s24, 0xfff80080
	s_addc_u32 s27, s25, -1
	s_cmp_eq_u32 s50, 28
	s_cselect_b32 s29, s17, s27
	s_cselect_b32 s28, s46, s26
	s_cselect_b32 s27, s11, s49
	s_cselect_b32 s26, s47, s48
	v_lshl_add_u64 v[220:221], s[24:25], 0, v[140:141]
	s_add_i32 m0, s23, 0xc000
	ds_read_b128 v[188:191], v156
	ds_read_b128 v[192:195], v156 offset:1024
	ds_read_b128 v[196:199], v156 offset:2048
	ds_read_b128 v[200:203], v156 offset:3072
	ds_read_b128 v[204:207], v156 offset:4096
	ds_read_b128 v[208:211], v156 offset:5120
	ds_read_b128 v[212:215], v156 offset:6144
	ds_read_b128 v[216:219], v156 offset:7168
	global_load_lds_dwordx4 v[220:221], off
	v_lshl_add_u64 v[220:221], s[24:25], 0, v[142:143]
	s_add_i32 m0, s23, 0xe000
	s_nop 0
	global_load_lds_dwordx4 v[220:221], off
	s_waitcnt vmcnt(8)
	s_waitcnt lgkmcnt(0)
	s_setprio 1
	s_barrier
	v_mfma_f32_16x16x32_bf16 v[126:129], v[148:151], v[188:191], v[126:129]
	v_mfma_f32_16x16x32_bf16 v[118:121], v[164:167], v[188:191], v[118:121]
	v_mfma_f32_16x16x32_bf16 v[110:113], v[148:151], v[196:199], v[110:113]
	v_mfma_f32_16x16x32_bf16 v[102:105], v[164:167], v[196:199], v[102:105]
	v_mfma_f32_16x16x32_bf16 v[94:97], v[148:151], v[204:207], v[94:97]
	v_mfma_f32_16x16x32_bf16 v[86:89], v[164:167], v[204:207], v[86:89]
	v_mfma_f32_16x16x32_bf16 v[78:81], v[148:151], v[212:215], v[78:81]
	v_mfma_f32_16x16x32_bf16 v[70:73], v[164:167], v[212:215], v[70:73]
	v_mfma_f32_16x16x32_bf16 v[126:129], v[160:163], v[192:195], v[126:129]
	v_mfma_f32_16x16x32_bf16 v[118:121], v[168:171], v[192:195], v[118:121]
	v_mfma_f32_16x16x32_bf16 v[110:113], v[160:163], v[200:203], v[110:113]
	v_mfma_f32_16x16x32_bf16 v[102:105], v[168:171], v[200:203], v[102:105]
	v_mfma_f32_16x16x32_bf16 v[94:97], v[160:163], v[208:211], v[94:97]
	v_mfma_f32_16x16x32_bf16 v[86:89], v[168:171], v[208:211], v[86:89]
	v_mfma_f32_16x16x32_bf16 v[78:81], v[160:163], v[216:219], v[78:81]
	v_mfma_f32_16x16x32_bf16 v[70:73], v[168:171], v[216:219], v[70:73]
	s_setprio 0
	s_setprio 1
	v_mfma_f32_16x16x32_bf16 v[122:125], v[172:175], v[188:191], v[122:125]
	v_mfma_f32_16x16x32_bf16 v[114:117], v[180:183], v[188:191], v[114:117]
	v_mfma_f32_16x16x32_bf16 v[106:109], v[172:175], v[196:199], v[106:109]
	v_mfma_f32_16x16x32_bf16 v[98:101], v[180:183], v[196:199], v[98:101]
	v_mfma_f32_16x16x32_bf16 v[90:93], v[172:175], v[204:207], v[90:93]
	v_mfma_f32_16x16x32_bf16 v[82:85], v[180:183], v[204:207], v[82:85]
	v_mfma_f32_16x16x32_bf16 v[74:77], v[172:175], v[212:215], v[74:77]
	v_mfma_f32_16x16x32_bf16 v[66:69], v[180:183], v[212:215], v[66:69]
	v_mfma_f32_16x16x32_bf16 v[122:125], v[176:179], v[192:195], v[122:125]
	v_mfma_f32_16x16x32_bf16 v[114:117], v[184:187], v[192:195], v[114:117]
	v_mfma_f32_16x16x32_bf16 v[106:109], v[176:179], v[200:203], v[106:109]
	v_mfma_f32_16x16x32_bf16 v[98:101], v[184:187], v[200:203], v[98:101]
	v_mfma_f32_16x16x32_bf16 v[90:93], v[176:179], v[208:211], v[90:93]
	v_mfma_f32_16x16x32_bf16 v[82:85], v[184:187], v[208:211], v[82:85]
	v_mfma_f32_16x16x32_bf16 v[74:77], v[176:179], v[216:219], v[74:77]
	v_mfma_f32_16x16x32_bf16 v[66:69], v[184:187], v[216:219], v[66:69]
	s_nop 3
	s_barrier
	s_setprio 0
	s_add_i32 s51, s41, s31
	v_lshl_add_u64 v[220:221], s[26:27], 0, v[136:137]
	s_mov_b32 m0, s51
	ds_read_b128 v[188:191], v156 offset:16384
	ds_read_b128 v[192:195], v156 offset:17408
	ds_read_b128 v[196:199], v156 offset:18432
	ds_read_b128 v[200:203], v156 offset:19456
	ds_read_b128 v[204:207], v156 offset:20480
	ds_read_b128 v[208:211], v156 offset:21504
	ds_read_b128 v[212:215], v156 offset:22528
	ds_read_b128 v[216:219], v156 offset:23552
	global_load_lds_dwordx4 v[220:221], off
	s_add_i32 m0, s51, 0x2000
	s_add_u32 s68, s26, 0x80000
	v_lshl_add_u64 v[222:223], s[26:27], 0, v[132:133]
	s_addc_u32 s69, s27, 0
	s_add_i32 s51, s42, s31
	global_load_lds_dwordx4 v[222:223], off
	v_lshl_add_u64 v[224:225], s[68:69], 0, v[136:137]
	s_mov_b32 m0, s51
	v_lshl_add_u64 v[226:227], s[28:29], 0, v[134:135]
	global_load_lds_dwordx4 v[224:225], off
	v_lshl_add_u64 v[224:225], s[68:69], 0, v[132:133]
	s_add_i32 m0, s51, 0x2000
	s_nop 0
	global_load_lds_dwordx4 v[224:225], off
	v_lshl_add_u64 v[224:225], s[28:29], 0, v[138:139]
	s_mov_b32 m0, s23
	s_nop 0
	global_load_lds_dwordx4 v[224:225], off
	s_mov_b32 m0, s34
	s_nop 0
	global_load_lds_dwordx4 v[226:227], off
	s_waitcnt vmcnt(8)
	s_waitcnt lgkmcnt(0)
	s_setprio 1
	s_barrier
; #define PG8_STAGE(bufoff, gbase, voff) do { _Pragma("unroll") for (int _i = 0; _i < 2; ++_i) \
;         __builtin_amdgcn_global_load_lds((const unsigned*)((const char*)(gbase) + (voff)[_i]), (PG8_LAS unsigned*)(lds + (bufoff) + ldsw + _i * 8192), 16, 0, 0); } while (0)
; #define PG8_WAIT_V(n) asm volatile("s_waitcnt vmcnt(" #n ")" ::: "memory")
; #define PG8_WAIT_L(n) asm volatile("s_waitcnt lgkmcnt(" #n ")" ::: "memory")
; #define PG8_BAR __builtin_amdgcn_s_barrier()
; #define PG8_SCHED __builtin_amdgcn_sched_barrier(0)
; template <class Epi, class Sched, bool ALIGN_EPI = true, bool SP2 = true>
; __device__ __forceinline__ void gemm_phase(PG8_LAS unsigned char* lds, const int K  , const Sched& S, const Epi& E) {
;     ...
;             PG8_WAIT_V(8); PG8_WAIT_L(0); PG8_BAR; PG8_MMA(1, 0, At, B0); PG8_MMA(1, 1, At, B1); PG8_BAR; PG8_SCHED;
;             PG8_LDB(B0, 1, 0); PG8_LDB(B1, 1, 1); PG8_SCHED; PG8_LDA(At, 1, 0); PG8_STAGE(PG8_SA(0, 1), a2 + hstep, voffA);
;             PG8_WAIT_V(8); PG8_WAIT_L(0); PG8_BAR; PG8_MMA(0, 0, At, B0); PG8_MMA(0, 1, At, B1); PG8_BAR; PG8_SCHED;
	v_mfma_f32_16x16x32_bf16 v[62:65], v[148:151], v[188:191], v[62:65]
	v_mfma_f32_16x16x32_bf16 v[54:57], v[164:167], v[188:191], v[54:57]
	v_mfma_f32_16x16x32_bf16 v[46:49], v[148:151], v[196:199], v[46:49]
	v_mfma_f32_16x16x32_bf16 v[38:41], v[164:167], v[196:199], v[38:41]
	v_mfma_f32_16x16x32_bf16 v[30:33], v[148:151], v[204:207], v[30:33]
	v_mfma_f32_16x16x32_bf16 v[22:25], v[164:167], v[204:207], v[22:25]
	v_mfma_f32_16x16x32_bf16 v[14:17], v[148:151], v[212:215], v[14:17]
	v_mfma_f32_16x16x32_bf16 v[6:9], v[164:167], v[212:215], v[6:9]
	v_mfma_f32_16x16x32_bf16 v[62:65], v[160:163], v[192:195], v[62:65]
	v_mfma_f32_16x16x32_bf16 v[54:57], v[168:171], v[192:195], v[54:57]
	v_mfma_f32_16x16x32_bf16 v[46:49], v[160:163], v[200:203], v[46:49]
	v_mfma_f32_16x16x32_bf16 v[38:41], v[168:171], v[200:203], v[38:41]
	v_mfma_f32_16x16x32_bf16 v[30:33], v[160:163], v[208:211], v[30:33]
	v_mfma_f32_16x16x32_bf16 v[22:25], v[168:171], v[208:211], v[22:25]
	v_mfma_f32_16x16x32_bf16 v[14:17], v[160:163], v[216:219], v[14:17]
	v_mfma_f32_16x16x32_bf16 v[6:9], v[168:171], v[216:219], v[6:9]
	s_setprio 0
	s_setprio 1
	v_mfma_f32_16x16x32_bf16 v[58:61], v[172:175], v[188:191], v[58:61]
	v_mfma_f32_16x16x32_bf16 v[50:53], v[180:183], v[188:191], v[50:53]
	v_mfma_f32_16x16x32_bf16 v[42:45], v[172:175], v[196:199], v[42:45]
	v_mfma_f32_16x16x32_bf16 v[34:37], v[180:183], v[196:199], v[34:37]
	v_mfma_f32_16x16x32_bf16 v[26:29], v[172:175], v[204:207], v[26:29]
	v_mfma_f32_16x16x32_bf16 v[18:21], v[180:183], v[204:207], v[18:21]
	v_mfma_f32_16x16x32_bf16 v[10:13], v[172:175], v[212:215], v[10:13]
	v_mfma_f32_16x16x32_bf16 v[2:5], v[180:183], v[212:215], v[2:5]
	v_mfma_f32_16x16x32_bf16 v[58:61], v[176:179], v[192:195], v[58:61]
	v_mfma_f32_16x16x32_bf16 v[50:53], v[184:187], v[192:195], v[50:53]
	v_mfma_f32_16x16x32_bf16 v[42:45], v[176:179], v[200:203], v[42:45]
	v_mfma_f32_16x16x32_bf16 v[34:37], v[184:187], v[200:203], v[34:37]
	v_mfma_f32_16x16x32_bf16 v[26:29], v[176:179], v[208:211], v[26:29]
	v_mfma_f32_16x16x32_bf16 v[18:21], v[184:187], v[208:211], v[18:21]
	v_mfma_f32_16x16x32_bf16 v[10:13], v[176:179], v[216:219], v[10:13]
	v_mfma_f32_16x16x32_bf16 v[2:5], v[184:187], v[216:219], v[2:5]
	s_nop 3
	s_barrier
	s_setprio 0
	s_add_i32 s51, 0, 0x18000
	v_add_u32_e32 v159, s51, v152
	s_add_i32 s68, 0, 0x1c000
	ds_read_b128 v[148:151], v159
	ds_read_b128 v[160:163], v159 offset:1024
	ds_read_b128 v[164:167], v159 offset:2048
	ds_read_b128 v[168:171], v159 offset:3072
	v_add_u32_e32 v159, s68, v152
	ds_read_b128 v[172:175], v159
	ds_read_b128 v[176:179], v159 offset:1024
	ds_read_b128 v[180:183], v159 offset:2048
	ds_read_b128 v[184:187], v159 offset:3072
	s_add_u32 s28, s28, 0x80000
	s_addc_u32 s29, s29, 0
	s_mov_b32 m0, s35
	v_lshl_add_u64 v[230:231], s[28:29], 0, v[138:139]
	ds_read_b128 v[188:191], v156 offset:32768
	ds_read_b128 v[192:195], v156 offset:33792
	ds_read_b128 v[196:199], v156 offset:34816
	ds_read_b128 v[200:203], v156 offset:35840
	ds_read_b128 v[204:207], v156 offset:36864
	ds_read_b128 v[208:211], v156 offset:37888
	ds_read_b128 v[212:215], v156 offset:38912
	ds_read_b128 v[216:219], v156 offset:39936
	global_load_lds_dwordx4 v[230:231], off
	v_lshl_add_u64 v[230:231], s[28:29], 0, v[134:135]
	s_mov_b32 m0, s36
	s_nop 0
	global_load_lds_dwordx4 v[230:231], off
	s_waitcnt vmcnt(8)
	s_waitcnt lgkmcnt(0)
	s_setprio 1
	s_barrier
	v_mfma_f32_16x16x32_bf16 v[126:129], v[148:151], v[188:191], v[126:129]
	v_mfma_f32_16x16x32_bf16 v[118:121], v[164:167], v[188:191], v[118:121]
	v_mfma_f32_16x16x32_bf16 v[110:113], v[148:151], v[196:199], v[110:113]
	v_mfma_f32_16x16x32_bf16 v[102:105], v[164:167], v[196:199], v[102:105]
	v_mfma_f32_16x16x32_bf16 v[94:97], v[148:151], v[204:207], v[94:97]
	v_mfma_f32_16x16x32_bf16 v[86:89], v[164:167], v[204:207], v[86:89]
	v_mfma_f32_16x16x32_bf16 v[78:81], v[148:151], v[212:215], v[78:81]
	v_mfma_f32_16x16x32_bf16 v[70:73], v[164:167], v[212:215], v[70:73]
	v_mfma_f32_16x16x32_bf16 v[126:129], v[160:163], v[192:195], v[126:129]
	v_mfma_f32_16x16x32_bf16 v[118:121], v[168:171], v[192:195], v[118:121]
	v_mfma_f32_16x16x32_bf16 v[110:113], v[160:163], v[200:203], v[110:113]
	v_mfma_f32_16x16x32_bf16 v[102:105], v[168:171], v[200:203], v[102:105]
	v_mfma_f32_16x16x32_bf16 v[94:97], v[160:163], v[208:211], v[94:97]
	v_mfma_f32_16x16x32_bf16 v[86:89], v[168:171], v[208:211], v[86:89]
	v_mfma_f32_16x16x32_bf16 v[78:81], v[160:163], v[216:219], v[78:81]
	v_mfma_f32_16x16x32_bf16 v[70:73], v[168:171], v[216:219], v[70:73]
	s_setprio 0
	s_setprio 1
	v_mfma_f32_16x16x32_bf16 v[122:125], v[172:175], v[188:191], v[122:125]
	v_mfma_f32_16x16x32_bf16 v[114:117], v[180:183], v[188:191], v[114:117]
	v_mfma_f32_16x16x32_bf16 v[106:109], v[172:175], v[196:199], v[106:109]
	v_mfma_f32_16x16x32_bf16 v[98:101], v[180:183], v[196:199], v[98:101]
	v_mfma_f32_16x16x32_bf16 v[90:93], v[172:175], v[204:207], v[90:93]
	v_mfma_f32_16x16x32_bf16 v[82:85], v[180:183], v[204:207], v[82:85]
	v_mfma_f32_16x16x32_bf16 v[74:77], v[172:175], v[212:215], v[74:77]
	v_mfma_f32_16x16x32_bf16 v[66:69], v[180:183], v[212:215], v[66:69]
	v_mfma_f32_16x16x32_bf16 v[122:125], v[176:179], v[192:195], v[122:125]
	v_mfma_f32_16x16x32_bf16 v[114:117], v[184:187], v[192:195], v[114:117]
	v_mfma_f32_16x16x32_bf16 v[106:109], v[176:179], v[200:203], v[106:109]
	v_mfma_f32_16x16x32_bf16 v[98:101], v[184:187], v[200:203], v[98:101]
	v_mfma_f32_16x16x32_bf16 v[90:93], v[176:179], v[208:211], v[90:93]
	v_mfma_f32_16x16x32_bf16 v[82:85], v[184:187], v[208:211], v[82:85]
	v_mfma_f32_16x16x32_bf16 v[74:77], v[176:179], v[216:219], v[74:77]
	v_mfma_f32_16x16x32_bf16 v[66:69], v[184:187], v[216:219], v[66:69]
	s_nop 3
	s_barrier
; #define PG8_STAGE(bufoff, gbase, voff) do { _Pragma("unroll") for (int _i = 0; _i < 2; ++_i) \
;         __builtin_amdgcn_global_load_lds((const unsigned*)((const char*)(gbase) + (voff)[_i]), (PG8_LAS unsigned*)(lds + (bufoff) + ldsw + _i * 8192), 16, 0, 0); } while (0)
; #define PG8_WAIT_V(n) asm volatile("s_waitcnt vmcnt(" #n ")" ::: "memory")
; #define PG8_WAIT_L(n) asm volatile("s_waitcnt lgkmcnt(" #n ")" ::: "memory")
; #define PG8_BAR __builtin_amdgcn_s_barrier()
; #define PG8_SCHED __builtin_amdgcn_sched_barrier(0)
; template <class Epi, class Sched, bool ALIGN_EPI = true, bool SP2 = true>
; __device__ __forceinline__ void gemm_phase(PG8_LAS unsigned char* lds, const int K  , const Sched& S, const Epi& E) {
;     ...
;             PG8_LDA(At, 1, 1); PG8_STAGE(PG8_SB(1, 0), b3, voffB); PG8_STAGE(PG8_SB(1, 1), b3 + hstep, voffB); PG8_STAGE(PG8_SA(1, 0), a3, voffA);
;             PG8_WAIT_V(8); PG8_WAIT_L(0); PG8_BAR; PG8_MMA(1, 0, At, B0); PG8_MMA(1, 1, At, B1); PG8_BAR; PG8_SCHED;
	s_setprio 0
	s_add_i32 s28, s51, s31
	v_lshl_add_u64 v[220:221], v[220:221], 0, s[4:5]
	s_mov_b32 m0, s28
	ds_read_b128 v[188:191], v156 offset:49152
	ds_read_b128 v[192:195], v156 offset:50176
	ds_read_b128 v[196:199], v156 offset:51200
	ds_read_b128 v[200:203], v156 offset:52224
	ds_read_b128 v[204:207], v156 offset:53248
	ds_read_b128 v[208:211], v156 offset:54272
	ds_read_b128 v[212:215], v156 offset:55296
	ds_read_b128 v[216:219], v156 offset:56320
	global_load_lds_dwordx4 v[220:221], off
	s_add_i32 m0, s28, 0x2000
	s_add_u32 s26, s26, 0x80080
	v_lshl_add_u64 v[220:221], v[222:223], 0, s[4:5]
	s_addc_u32 s27, s27, 0
	s_add_i32 s28, s68, s31
	global_load_lds_dwordx4 v[220:221], off
	v_lshl_add_u64 v[220:221], s[26:27], 0, v[136:137]
	s_mov_b32 m0, s28
	s_nop 0
	global_load_lds_dwordx4 v[220:221], off
	v_lshl_add_u64 v[220:221], s[26:27], 0, v[132:133]
	s_add_i32 m0, s28, 0x2000
	s_nop 0
	global_load_lds_dwordx4 v[220:221], off
	v_lshl_add_u64 v[220:221], v[224:225], 0, s[4:5]
	s_mov_b32 m0, s38
	s_nop 0
	global_load_lds_dwordx4 v[220:221], off
	v_lshl_add_u64 v[220:221], v[226:227], 0, s[4:5]
	s_mov_b32 m0, s39
	s_nop 0
	global_load_lds_dwordx4 v[220:221], off
	s_waitcnt vmcnt(8)
	s_waitcnt lgkmcnt(0)
	s_setprio 1
	s_barrier
	v_mfma_f32_16x16x32_bf16 v[62:65], v[148:151], v[188:191], v[62:65]
	v_mfma_f32_16x16x32_bf16 v[54:57], v[164:167], v[188:191], v[54:57]
	v_mfma_f32_16x16x32_bf16 v[46:49], v[148:151], v[196:199], v[46:49]
	v_mfma_f32_16x16x32_bf16 v[38:41], v[164:167], v[196:199], v[38:41]
	v_mfma_f32_16x16x32_bf16 v[30:33], v[148:151], v[204:207], v[30:33]
	v_mfma_f32_16x16x32_bf16 v[22:25], v[164:167], v[204:207], v[22:25]
	v_mfma_f32_16x16x32_bf16 v[14:17], v[148:151], v[212:215], v[14:17]
	v_mfma_f32_16x16x32_bf16 v[6:9], v[164:167], v[212:215], v[6:9]
	v_mfma_f32_16x16x32_bf16 v[62:65], v[160:163], v[192:195], v[62:65]
	v_mfma_f32_16x16x32_bf16 v[54:57], v[168:171], v[192:195], v[54:57]
	v_mfma_f32_16x16x32_bf16 v[46:49], v[160:163], v[200:203], v[46:49]
	v_mfma_f32_16x16x32_bf16 v[38:41], v[168:171], v[200:203], v[38:41]
	v_mfma_f32_16x16x32_bf16 v[30:33], v[160:163], v[208:211], v[30:33]
	v_mfma_f32_16x16x32_bf16 v[22:25], v[168:171], v[208:211], v[22:25]
	v_mfma_f32_16x16x32_bf16 v[14:17], v[160:163], v[216:219], v[14:17]
	v_mfma_f32_16x16x32_bf16 v[6:9], v[168:171], v[216:219], v[6:9]
	s_setprio 0
	s_setprio 1
	v_mfma_f32_16x16x32_bf16 v[58:61], v[172:175], v[188:191], v[58:61]
	v_mfma_f32_16x16x32_bf16 v[50:53], v[180:183], v[188:191], v[50:53]
	v_mfma_f32_16x16x32_bf16 v[42:45], v[172:175], v[196:199], v[42:45]
	v_mfma_f32_16x16x32_bf16 v[34:37], v[180:183], v[196:199], v[34:37]
	v_mfma_f32_16x16x32_bf16 v[26:29], v[172:175], v[204:207], v[26:29]
	v_mfma_f32_16x16x32_bf16 v[18:21], v[180:183], v[204:207], v[18:21]
	v_mfma_f32_16x16x32_bf16 v[10:13], v[172:175], v[212:215], v[10:13]
	v_mfma_f32_16x16x32_bf16 v[2:5], v[180:183], v[212:215], v[2:5]
	v_mfma_f32_16x16x32_bf16 v[58:61], v[176:179], v[192:195], v[58:61]
	v_mfma_f32_16x16x32_bf16 v[50:53], v[184:187], v[192:195], v[50:53]
	v_mfma_f32_16x16x32_bf16 v[42:45], v[176:179], v[200:203], v[42:45]
	v_mfma_f32_16x16x32_bf16 v[34:37], v[184:187], v[200:203], v[34:37]
	v_mfma_f32_16x16x32_bf16 v[26:29], v[176:179], v[208:211], v[26:29]
	v_mfma_f32_16x16x32_bf16 v[18:21], v[184:187], v[208:211], v[18:21]
	v_mfma_f32_16x16x32_bf16 v[10:13], v[176:179], v[216:219], v[10:13]
	v_mfma_f32_16x16x32_bf16 v[2:5], v[184:187], v[216:219], v[2:5]
	s_nop 3
	s_barrier
	s_setprio 0
	s_add_i32 s50, s50, 2
	s_add_u32 s24, s24, 0x100
	s_addc_u32 s25, s25, 0
	s_add_u32 s48, s48, 0x100
	s_addc_u32 s49, s49, 0
	s_cmp_gt_u32 s50, 29
	s_cbranch_scc0 .LBB0_1448
	s_and_b64 vcc, exec, s[8:9]
	s_cbranch_vccz .LBB0_1451
	s_barrier

; #define PG8_STAGE(bufoff, gbase, voff) do { _Pragma("unroll") for (int _i = 0; _i < 2; ++_i) \
;         __builtin_amdgcn_global_load_lds((const unsigned*)((const char*)(gbase) + (voff)[_i]), (PG8_LAS unsigned*)(lds + (bufoff) + ldsw + _i * 8192), 16, 0, 0); } while (0)
; #define PG8_WAIT_V(n) asm volatile("s_waitcnt vmcnt(" #n ")" ::: "memory")
; #define PG8_WAIT_L(n) asm volatile("s_waitcnt lgkmcnt(" #n ")" ::: "memory")
; #define PG8_BAR __builtin_amdgcn_s_barrier()
; #define PG8_SCHED __builtin_amdgcn_sched_barrier(0)
; template <class Epi, class Sched, bool ALIGN_EPI = true, bool SP2 = true>
; __device__ __forceinline__ void gemm_phase(PG8_LAS unsigned char* lds, const int K  , const Sched& S, const Epi& E) {
;     ...
;             PG8_LDB(B0, 0, 0); PG8_LDB(B1, 0, 1); PG8_SCHED; PG8_LDA(At, 0, 0); PG8_STAGE(PG8_SA(1, 1), a1 + hstep, voffA);
;             PG8_WAIT_V(8); PG8_WAIT_L(0); PG8_BAR; PG8_MMA(0, 0, At, B0); PG8_MMA(0, 1, At, B1); PG8_BAR; PG8_SCHED;
;             PG8_LDA(At, 0, 1); PG8_STAGE(PG8_SB(0, 0), b2, voffB); PG8_STAGE(PG8_SB(0, 1), b2 + hstep, voffB); PG8_STAGE(PG8_SA(0, 0), a2, voffA);
;             PG8_WAIT_V(8); PG8_WAIT_L(0); PG8_BAR; PG8_MMA(1, 0, At, B0); PG8_MMA(1, 1, At, B1); PG8_BAR; PG8_SCHED;
.LBB0_1695:
	ds_read_b128 v[18:21], v233
	ds_read_b128 v[22:25], v233 offset:1024
	ds_read_b128 v[26:29], v233 offset:2048
	ds_read_b128 v[30:33], v233 offset:3072
	ds_read_b128 v[2:5], v234
	ds_read_b128 v[6:9], v234 offset:1024
	ds_read_b128 v[10:13], v234 offset:2048
	ds_read_b128 v[14:17], v234 offset:3072
	s_add_i32 s74, s24, 2
	s_add_u32 s22, s20, 0xfff50080
	s_addc_u32 s23, s21, -1
	s_cmp_eq_u32 s71, s24
	s_cselect_b32 s24, s16, s22
	s_cselect_b32 s25, s17, s23
	s_cselect_b32 s23, s19, s73
	s_cselect_b32 s22, s18, s72
	v_lshl_add_u64 v[186:187], s[20:21], 0, v[198:199]
	s_add_i32 m0, s28, 0xc000
	ds_read_b128 v[162:165], v235
	ds_read_b128 v[166:169], v235 offset:1024
	ds_read_b128 v[170:173], v235 offset:2048
	ds_read_b128 v[174:177], v235 offset:3072
	ds_read_b128 v[178:181], v235 offset:4096
	ds_read_b128 v[182:185], v235 offset:5120
	ds_read_b128 v[206:209], v235 offset:6144
	ds_read_b128 v[210:213], v235 offset:7168
	global_load_lds_dwordx4 v[186:187], off
	v_lshl_add_u64 v[186:187], s[20:21], 0, v[200:201]
	s_add_i32 m0, s28, 0xe000
	s_nop 0
	global_load_lds_dwordx4 v[186:187], off
	s_waitcnt vmcnt(8)
	s_waitcnt lgkmcnt(0)
	s_setprio 1
	s_barrier
	v_mfma_scale_f32_16x16x128_f8f6f4 v[158:161], v[18:25], v[162:169], v[158:161], v229, v229 op_sel_hi:[0,0,0]
	v_mfma_scale_f32_16x16x128_f8f6f4 v[154:157], v[26:33], v[162:169], v[154:157], v229, v229 op_sel_hi:[0,0,0]
	v_mfma_scale_f32_16x16x128_f8f6f4 v[150:153], v[18:25], v[170:177], v[150:153], v229, v229 op_sel_hi:[0,0,0]
	v_mfma_scale_f32_16x16x128_f8f6f4 v[142:145], v[26:33], v[170:177], v[142:145], v229, v229 op_sel_hi:[0,0,0]
	v_mfma_scale_f32_16x16x128_f8f6f4 v[134:137], v[18:25], v[178:185], v[134:137], v229, v229 op_sel_hi:[0,0,0]
	v_mfma_scale_f32_16x16x128_f8f6f4 v[126:129], v[26:33], v[178:185], v[126:129], v229, v229 op_sel_hi:[0,0,0]
	v_mfma_scale_f32_16x16x128_f8f6f4 v[118:121], v[18:25], v[206:213], v[118:121], v229, v229 op_sel_hi:[0,0,0]
	v_mfma_scale_f32_16x16x128_f8f6f4 v[110:113], v[26:33], v[206:213], v[110:113], v229, v229 op_sel_hi:[0,0,0]
	s_setprio 0
	s_setprio 1
	v_mfma_scale_f32_16x16x128_f8f6f4 v[146:149], v[2:9], v[162:169], v[146:149], v229, v229 op_sel_hi:[0,0,0]
	v_mfma_scale_f32_16x16x128_f8f6f4 v[138:141], v[10:17], v[162:169], v[138:141], v229, v229 op_sel_hi:[0,0,0]
	v_mfma_scale_f32_16x16x128_f8f6f4 v[130:133], v[2:9], v[170:177], v[130:133], v229, v229 op_sel_hi:[0,0,0]
	v_mfma_scale_f32_16x16x128_f8f6f4 v[122:125], v[10:17], v[170:177], v[122:125], v229, v229 op_sel_hi:[0,0,0]
	v_mfma_scale_f32_16x16x128_f8f6f4 v[114:117], v[2:9], v[178:185], v[114:117], v229, v229 op_sel_hi:[0,0,0]
	v_mfma_scale_f32_16x16x128_f8f6f4 v[106:109], v[10:17], v[178:185], v[106:109], v229, v229 op_sel_hi:[0,0,0]
	v_mfma_scale_f32_16x16x128_f8f6f4 v[102:105], v[2:9], v[206:213], v[102:105], v229, v229 op_sel_hi:[0,0,0]
	v_mfma_scale_f32_16x16x128_f8f6f4 v[98:101], v[10:17], v[206:213], v[98:101], v229, v229 op_sel_hi:[0,0,0]
	s_nop 3
	s_barrier
	s_setprio 0
	s_add_i32 s75, s40, s27
	v_lshl_add_u64 v[162:163], s[22:23], 0, v[192:193]
	s_mov_b32 m0, s75
	ds_read_b128 v[170:173], v235 offset:16384
	ds_read_b128 v[174:177], v235 offset:17408
	ds_read_b128 v[178:181], v235 offset:18432
	ds_read_b128 v[182:185], v235 offset:19456
	ds_read_b128 v[206:209], v235 offset:20480
	ds_read_b128 v[210:213], v235 offset:21504
	ds_read_b128 v[214:217], v235 offset:22528
	ds_read_b128 v[218:221], v235 offset:23552
	global_load_lds_dwordx4 v[162:163], off
	s_add_i32 m0, s75, 0x2000
	s_add_u32 s78, s22, 0xb0000
	v_lshl_add_u64 v[164:165], s[22:23], 0, v[196:197]
	s_addc_u32 s79, s23, 0
	s_add_i32 s75, s41, s27
	global_load_lds_dwordx4 v[164:165], off
	v_lshl_add_u64 v[166:167], s[78:79], 0, v[192:193]
	s_mov_b32 m0, s75
	v_lshl_add_u64 v[168:169], s[24:25], 0, v[194:195]
	global_load_lds_dwordx4 v[166:167], off
	v_lshl_add_u64 v[166:167], s[78:79], 0, v[196:197]
	s_add_i32 m0, s75, 0x2000
	s_nop 0
	global_load_lds_dwordx4 v[166:167], off
	v_lshl_add_u64 v[166:167], s[24:25], 0, v[190:191]
	s_mov_b32 m0, s28
	s_nop 0
	global_load_lds_dwordx4 v[166:167], off
	s_mov_b32 m0, s29
	s_nop 0
	global_load_lds_dwordx4 v[168:169], off
	s_waitcnt vmcnt(8)
	s_waitcnt lgkmcnt(0)
	s_setprio 1
	s_barrier
	v_mfma_scale_f32_16x16x128_f8f6f4 v[94:97], v[18:25], v[170:177], v[94:97], v229, v229 op_sel_hi:[0,0,0]
	v_mfma_scale_f32_16x16x128_f8f6f4 v[90:93], v[26:33], v[170:177], v[90:93], v229, v229 op_sel_hi:[0,0,0]
	v_mfma_scale_f32_16x16x128_f8f6f4 v[86:89], v[18:25], v[178:185], v[86:89], v229, v229 op_sel_hi:[0,0,0]
	v_mfma_scale_f32_16x16x128_f8f6f4 v[78:81], v[26:33], v[178:185], v[78:81], v229, v229 op_sel_hi:[0,0,0]
	v_mfma_scale_f32_16x16x128_f8f6f4 v[70:73], v[18:25], v[206:213], v[70:73], v229, v229 op_sel_hi:[0,0,0]
	v_mfma_scale_f32_16x16x128_f8f6f4 v[62:65], v[26:33], v[206:213], v[62:65], v229, v229 op_sel_hi:[0,0,0]
	v_mfma_scale_f32_16x16x128_f8f6f4 v[54:57], v[18:25], v[214:221], v[54:57], v229, v229 op_sel_hi:[0,0,0]
	v_mfma_scale_f32_16x16x128_f8f6f4 v[46:49], v[26:33], v[214:221], v[46:49], v229, v229 op_sel_hi:[0,0,0]
	s_setprio 0
	s_setprio 1
	v_mfma_scale_f32_16x16x128_f8f6f4 v[82:85], v[2:9], v[170:177], v[82:85], v229, v229 op_sel_hi:[0,0,0]
	v_mfma_scale_f32_16x16x128_f8f6f4 v[74:77], v[10:17], v[170:177], v[74:77], v229, v229 op_sel_hi:[0,0,0]
	v_mfma_scale_f32_16x16x128_f8f6f4 v[66:69], v[2:9], v[178:185], v[66:69], v229, v229 op_sel_hi:[0,0,0]
	v_mfma_scale_f32_16x16x128_f8f6f4 v[58:61], v[10:17], v[178:185], v[58:61], v229, v229 op_sel_hi:[0,0,0]
	v_mfma_scale_f32_16x16x128_f8f6f4 v[50:53], v[2:9], v[206:213], v[50:53], v229, v229 op_sel_hi:[0,0,0]
	v_mfma_scale_f32_16x16x128_f8f6f4 v[42:45], v[10:17], v[206:213], v[42:45], v229, v229 op_sel_hi:[0,0,0]
	v_mfma_scale_f32_16x16x128_f8f6f4 v[38:41], v[2:9], v[214:221], v[38:41], v229, v229 op_sel_hi:[0,0,0]
	v_mfma_scale_f32_16x16x128_f8f6f4 v[34:37], v[10:17], v[214:221], v[34:37], v229, v229 op_sel_hi:[0,0,0]
	s_nop 3
	s_barrier
; #define PG8_STAGE(bufoff, gbase, voff) do { _Pragma("unroll") for (int _i = 0; _i < 2; ++_i) \
;         __builtin_amdgcn_global_load_lds((const unsigned*)((const char*)(gbase) + (voff)[_i]), (PG8_LAS unsigned*)(lds + (bufoff) + ldsw + _i * 8192), 16, 0, 0); } while (0)
; #define PG8_WAIT_V(n) asm volatile("s_waitcnt vmcnt(" #n ")" ::: "memory")
; #define PG8_WAIT_L(n) asm volatile("s_waitcnt lgkmcnt(" #n ")" ::: "memory")
; #define PG8_BAR __builtin_amdgcn_s_barrier()
; #define PG8_SCHED __builtin_amdgcn_sched_barrier(0)
; template <class Epi, class Sched, bool ALIGN_EPI = true, bool SP2 = true>
; __device__ __forceinline__ void gemm_phase(PG8_LAS unsigned char* lds, const int K  , const Sched& S, const Epi& E) {
;     ...
;             PG8_LDB(B0, 1, 0); PG8_LDB(B1, 1, 1); PG8_SCHED; PG8_LDA(At, 1, 0); PG8_STAGE(PG8_SA(0, 1), a2 + hstep, voffA);
;             PG8_WAIT_V(8); PG8_WAIT_L(0); PG8_BAR; PG8_MMA(0, 0, At, B0); PG8_MMA(0, 1, At, B1); PG8_BAR; PG8_SCHED;
;             PG8_LDA(At, 1, 1); PG8_STAGE(PG8_SB(1, 0), b3, voffB); PG8_STAGE(PG8_SB(1, 1), b3 + hstep, voffB); PG8_STAGE(PG8_SA(1, 0), a3, voffA);
;             PG8_WAIT_V(8); PG8_WAIT_L(0); PG8_BAR; PG8_MMA(1, 0, At, B0); PG8_MMA(1, 1, At, B1); PG8_BAR; PG8_SCHED;
;     ...
;         if constexpr (Epi::FP8) asm volatile("s_nop 15\n\ts_nop 15\n\ts_nop 15\n\ts_nop 15\n\ts_nop 15" ::: "memory");
	s_setprio 0
	s_add_i32 s75, 0, 0x18000
	s_add_i32 s78, 0, 0x1c000
	v_add_u32_e32 v14, s75, v231
	v_add_u32_e32 v30, s78, v231
	ds_read_b128 v[2:5], v14
	ds_read_b128 v[6:9], v14 offset:1024
	ds_read_b128 v[10:13], v14 offset:2048
	ds_read_b128 v[14:17], v14 offset:3072
	ds_read_b128 v[18:21], v30
	ds_read_b128 v[22:25], v30 offset:1024
	ds_read_b128 v[26:29], v30 offset:2048
	ds_read_b128 v[30:33], v30 offset:3072
	s_add_u32 s24, s24, 0xb0000
	s_addc_u32 s25, s25, 0
	s_mov_b32 m0, s30
	v_lshl_add_u64 v[186:187], s[24:25], 0, v[190:191]
	ds_read_b128 v[170:173], v235 offset:32768
	ds_read_b128 v[174:177], v235 offset:33792
	ds_read_b128 v[178:181], v235 offset:34816
	ds_read_b128 v[182:185], v235 offset:35840
	ds_read_b128 v[206:209], v235 offset:36864
	ds_read_b128 v[210:213], v235 offset:37888
	ds_read_b128 v[214:217], v235 offset:38912
	ds_read_b128 v[218:221], v235 offset:39936
	global_load_lds_dwordx4 v[186:187], off
	v_lshl_add_u64 v[186:187], s[24:25], 0, v[194:195]
	s_mov_b32 m0, s31
	s_nop 0
	global_load_lds_dwordx4 v[186:187], off
	s_waitcnt vmcnt(8)
	s_waitcnt lgkmcnt(0)
	s_setprio 1
	s_barrier
	v_mfma_scale_f32_16x16x128_f8f6f4 v[158:161], v[2:9], v[170:177], v[158:161], v229, v229 op_sel_hi:[0,0,0]
	v_mfma_scale_f32_16x16x128_f8f6f4 v[154:157], v[10:17], v[170:177], v[154:157], v229, v229 op_sel_hi:[0,0,0]
	v_mfma_scale_f32_16x16x128_f8f6f4 v[150:153], v[2:9], v[178:185], v[150:153], v229, v229 op_sel_hi:[0,0,0]
	v_mfma_scale_f32_16x16x128_f8f6f4 v[142:145], v[10:17], v[178:185], v[142:145], v229, v229 op_sel_hi:[0,0,0]
	v_mfma_scale_f32_16x16x128_f8f6f4 v[134:137], v[2:9], v[206:213], v[134:137], v229, v229 op_sel_hi:[0,0,0]
	v_mfma_scale_f32_16x16x128_f8f6f4 v[126:129], v[10:17], v[206:213], v[126:129], v229, v229 op_sel_hi:[0,0,0]
	v_mfma_scale_f32_16x16x128_f8f6f4 v[118:121], v[2:9], v[214:221], v[118:121], v229, v229 op_sel_hi:[0,0,0]
	v_mfma_scale_f32_16x16x128_f8f6f4 v[110:113], v[10:17], v[214:221], v[110:113], v229, v229 op_sel_hi:[0,0,0]
	s_setprio 0
	s_setprio 1
	v_mfma_scale_f32_16x16x128_f8f6f4 v[146:149], v[18:25], v[170:177], v[146:149], v229, v229 op_sel_hi:[0,0,0]
	v_mfma_scale_f32_16x16x128_f8f6f4 v[138:141], v[26:33], v[170:177], v[138:141], v229, v229 op_sel_hi:[0,0,0]
	v_mfma_scale_f32_16x16x128_f8f6f4 v[130:133], v[18:25], v[178:185], v[130:133], v229, v229 op_sel_hi:[0,0,0]
	v_mfma_scale_f32_16x16x128_f8f6f4 v[122:125], v[26:33], v[178:185], v[122:125], v229, v229 op_sel_hi:[0,0,0]
	v_mfma_scale_f32_16x16x128_f8f6f4 v[114:117], v[18:25], v[206:213], v[114:117], v229, v229 op_sel_hi:[0,0,0]
	v_mfma_scale_f32_16x16x128_f8f6f4 v[106:109], v[26:33], v[206:213], v[106:109], v229, v229 op_sel_hi:[0,0,0]
	v_mfma_scale_f32_16x16x128_f8f6f4 v[102:105], v[18:25], v[214:221], v[102:105], v229, v229 op_sel_hi:[0,0,0]
	v_mfma_scale_f32_16x16x128_f8f6f4 v[98:101], v[26:33], v[214:221], v[98:101], v229, v229 op_sel_hi:[0,0,0]
	s_nop 3
	s_barrier
	s_setprio 0
	s_add_i32 s24, s75, s27
	v_lshl_add_u64 v[162:163], v[162:163], 0, s[10:11]
	s_mov_b32 m0, s24
	ds_read_b128 v[170:173], v235 offset:49152
	ds_read_b128 v[174:177], v235 offset:50176
	ds_read_b128 v[178:181], v235 offset:51200
	ds_read_b128 v[182:185], v235 offset:52224
	ds_read_b128 v[206:209], v235 offset:53248
	ds_read_b128 v[210:213], v235 offset:54272
	ds_read_b128 v[214:217], v235 offset:55296
	ds_read_b128 v[218:221], v235 offset:56320
	global_load_lds_dwordx4 v[162:163], off
	s_add_i32 m0, s24, 0x2000
	s_add_u32 s22, s22, 0xb0080
	v_lshl_add_u64 v[162:163], v[164:165], 0, s[10:11]
	s_addc_u32 s23, s23, 0
	s_add_i32 s24, s78, s27
	global_load_lds_dwordx4 v[162:163], off
	v_lshl_add_u64 v[162:163], s[22:23], 0, v[192:193]
	s_mov_b32 m0, s24
	s_nop 0
	global_load_lds_dwordx4 v[162:163], off
	v_lshl_add_u64 v[162:163], s[22:23], 0, v[196:197]
	s_add_i32 m0, s24, 0x2000
	s_nop 0
	global_load_lds_dwordx4 v[162:163], off
	v_lshl_add_u64 v[162:163], v[166:167], 0, s[10:11]
	s_mov_b32 m0, s36
	s_nop 0
	global_load_lds_dwordx4 v[162:163], off
	v_lshl_add_u64 v[162:163], v[168:169], 0, s[10:11]
	s_mov_b32 m0, s37
	s_nop 0
	global_load_lds_dwordx4 v[162:163], off
	s_waitcnt vmcnt(8)
	s_waitcnt lgkmcnt(0)
	s_setprio 1
	s_barrier
	v_mfma_scale_f32_16x16x128_f8f6f4 v[94:97], v[2:9], v[170:177], v[94:97], v229, v229 op_sel_hi:[0,0,0]
	v_mfma_scale_f32_16x16x128_f8f6f4 v[90:93], v[10:17], v[170:177], v[90:93], v229, v229 op_sel_hi:[0,0,0]
	v_mfma_scale_f32_16x16x128_f8f6f4 v[86:89], v[2:9], v[178:185], v[86:89], v229, v229 op_sel_hi:[0,0,0]
	v_mfma_scale_f32_16x16x128_f8f6f4 v[78:81], v[10:17], v[178:185], v[78:81], v229, v229 op_sel_hi:[0,0,0]
	v_mfma_scale_f32_16x16x128_f8f6f4 v[70:73], v[2:9], v[206:213], v[70:73], v229, v229 op_sel_hi:[0,0,0]
	v_mfma_scale_f32_16x16x128_f8f6f4 v[62:65], v[10:17], v[206:213], v[62:65], v229, v229 op_sel_hi:[0,0,0]
	v_mfma_scale_f32_16x16x128_f8f6f4 v[54:57], v[2:9], v[214:221], v[54:57], v229, v229 op_sel_hi:[0,0,0]
	v_mfma_scale_f32_16x16x128_f8f6f4 v[46:49], v[10:17], v[214:221], v[46:49], v229, v229 op_sel_hi:[0,0,0]
	s_setprio 0
	s_setprio 1
	v_mfma_scale_f32_16x16x128_f8f6f4 v[82:85], v[18:25], v[170:177], v[82:85], v229, v229 op_sel_hi:[0,0,0]
	v_mfma_scale_f32_16x16x128_f8f6f4 v[74:77], v[26:33], v[170:177], v[74:77], v229, v229 op_sel_hi:[0,0,0]
	v_mfma_scale_f32_16x16x128_f8f6f4 v[66:69], v[18:25], v[178:185], v[66:69], v229, v229 op_sel_hi:[0,0,0]
	v_mfma_scale_f32_16x16x128_f8f6f4 v[58:61], v[26:33], v[178:185], v[58:61], v229, v229 op_sel_hi:[0,0,0]
	v_mfma_scale_f32_16x16x128_f8f6f4 v[50:53], v[18:25], v[206:213], v[50:53], v229, v229 op_sel_hi:[0,0,0]
	v_mfma_scale_f32_16x16x128_f8f6f4 v[42:45], v[26:33], v[206:213], v[42:45], v229, v229 op_sel_hi:[0,0,0]
	v_mfma_scale_f32_16x16x128_f8f6f4 v[38:41], v[18:25], v[214:221], v[38:41], v229, v229 op_sel_hi:[0,0,0]
	v_mfma_scale_f32_16x16x128_f8f6f4 v[34:37], v[26:33], v[214:221], v[34:37], v229, v229 op_sel_hi:[0,0,0]
	s_nop 3
	s_barrier
	s_setprio 0
	s_add_u32 s20, s20, 0x100
	s_addc_u32 s21, s21, 0
	s_add_u32 s72, s72, 0x100
	s_addc_u32 s73, s73, 0
	s_cmp_ge_u32 s74, s4
	s_mov_b32 s24, s74
	s_cbranch_scc0 .LBB0_1695
	s_nop 15
	s_nop 15
	s_nop 15
	s_nop 15
	s_nop 15
	s_and_b64 vcc, exec, s[12:13]
	s_cbranch_vccz .LBB0_1698
	s_barrier

; #define PG8_STAGE(bufoff, gbase, voff) do { _Pragma("unroll") for (int _i = 0; _i < 2; ++_i) \
;         __builtin_amdgcn_global_load_lds((const unsigned*)((const char*)(gbase) + (voff)[_i]), (PG8_LAS unsigned*)(lds + (bufoff) + ldsw + _i * 8192), 16, 0, 0); } while (0)
; #define PG8_WAIT_V(n) asm volatile("s_waitcnt vmcnt(" #n ")" ::: "memory")
; #define PG8_WAIT_L(n) asm volatile("s_waitcnt lgkmcnt(" #n ")" ::: "memory")
; #define PG8_BAR __builtin_amdgcn_s_barrier()
; #define PG8_SCHED __builtin_amdgcn_sched_barrier(0)
; template <class Epi, class Sched, bool ALIGN_EPI = true, bool SP2 = true>
; __device__ __forceinline__ void gemm_phase(PG8_LAS unsigned char* lds, const int K  , const Sched& S, const Epi& E) {
;     ...
;             PG8_LDB(B0, 0, 0); PG8_LDB(B1, 0, 1); PG8_SCHED; PG8_LDA(At, 0, 0); PG8_STAGE(PG8_SA(1, 1), a1 + hstep, voffA);
;             PG8_WAIT_V(8); PG8_WAIT_L(0); PG8_BAR; PG8_MMA(0, 0, At, B0); PG8_MMA(0, 1, At, B1); PG8_BAR; PG8_SCHED;
;             PG8_LDA(At, 0, 1); PG8_STAGE(PG8_SB(0, 0), b2, voffB); PG8_STAGE(PG8_SB(0, 1), b2 + hstep, voffB); PG8_STAGE(PG8_SA(0, 0), a2, voffA);
.LBB0_1847:
	ds_read_b128 v[130:133], v176
	ds_read_b128 v[134:137], v176 offset:1024
	ds_read_b128 v[138:141], v176 offset:2048
	ds_read_b128 v[142:145], v176 offset:3072
	ds_read_b128 v[168:171], v177
	ds_read_b128 v[184:187], v177 offset:1024
	ds_read_b128 v[188:191], v177 offset:2048
	ds_read_b128 v[192:195], v177 offset:3072
	s_add_u32 s22, s0, 0xfff80080
	s_addc_u32 s23, s1, -1
	s_cmp_eq_u32 s51, 28
	s_cselect_b32 s25, s7, s23
	s_cselect_b32 s24, s47, s22
	s_cselect_b32 s23, s11, s50
	s_cselect_b32 s22, s48, s49
	v_lshl_add_u64 v[230:231], s[0:1], 0, v[160:161]
	s_add_i32 m0, s27, 0xc000
	ds_read_b128 v[196:199], v178
	ds_read_b128 v[200:203], v178 offset:1024
	ds_read_b128 v[204:207], v178 offset:2048
	ds_read_b128 v[208:211], v178 offset:3072
	ds_read_b128 v[212:215], v178 offset:4096
	ds_read_b128 v[216:219], v178 offset:5120
	ds_read_b128 v[220:223], v178 offset:6144
	ds_read_b128 v[224:227], v178 offset:7168
	global_load_lds_dwordx4 v[230:231], off
	v_lshl_add_u64 v[230:231], s[0:1], 0, v[162:163]
	s_add_i32 m0, s27, 0xe000
	s_nop 0
	global_load_lds_dwordx4 v[230:231], off
	s_waitcnt vmcnt(8)
	s_waitcnt lgkmcnt(0)
	s_setprio 1
	s_barrier
	v_mfma_f32_16x16x32_bf16 v[126:129], v[130:133], v[196:199], v[126:129]
	v_mfma_f32_16x16x32_bf16 v[122:125], v[138:141], v[196:199], v[122:125]
	v_mfma_f32_16x16x32_bf16 v[110:113], v[130:133], v[204:207], v[110:113]
	v_mfma_f32_16x16x32_bf16 v[106:109], v[138:141], v[204:207], v[106:109]
	v_mfma_f32_16x16x32_bf16 v[94:97], v[130:133], v[212:215], v[94:97]
	v_mfma_f32_16x16x32_bf16 v[90:93], v[138:141], v[212:215], v[90:93]
	v_mfma_f32_16x16x32_bf16 v[78:81], v[130:133], v[220:223], v[78:81]
	v_mfma_f32_16x16x32_bf16 v[74:77], v[138:141], v[220:223], v[74:77]
	v_mfma_f32_16x16x32_bf16 v[126:129], v[134:137], v[200:203], v[126:129]
	v_mfma_f32_16x16x32_bf16 v[122:125], v[142:145], v[200:203], v[122:125]
	v_mfma_f32_16x16x32_bf16 v[110:113], v[134:137], v[208:211], v[110:113]
	v_mfma_f32_16x16x32_bf16 v[106:109], v[142:145], v[208:211], v[106:109]
	v_mfma_f32_16x16x32_bf16 v[94:97], v[134:137], v[216:219], v[94:97]
	v_mfma_f32_16x16x32_bf16 v[90:93], v[142:145], v[216:219], v[90:93]
	v_mfma_f32_16x16x32_bf16 v[78:81], v[134:137], v[224:227], v[78:81]
	v_mfma_f32_16x16x32_bf16 v[74:77], v[142:145], v[224:227], v[74:77]
	s_setprio 0
	s_setprio 1
	v_mfma_f32_16x16x32_bf16 v[118:121], v[168:171], v[196:199], v[118:121]
	v_mfma_f32_16x16x32_bf16 v[114:117], v[188:191], v[196:199], v[114:117]
	v_mfma_f32_16x16x32_bf16 v[102:105], v[168:171], v[204:207], v[102:105]
	v_mfma_f32_16x16x32_bf16 v[98:101], v[188:191], v[204:207], v[98:101]
	v_mfma_f32_16x16x32_bf16 v[86:89], v[168:171], v[212:215], v[86:89]
	v_mfma_f32_16x16x32_bf16 v[82:85], v[188:191], v[212:215], v[82:85]
	v_mfma_f32_16x16x32_bf16 v[70:73], v[168:171], v[220:223], v[70:73]
	v_mfma_f32_16x16x32_bf16 v[66:69], v[188:191], v[220:223], v[66:69]
	v_mfma_f32_16x16x32_bf16 v[118:121], v[184:187], v[200:203], v[118:121]
	v_mfma_f32_16x16x32_bf16 v[114:117], v[192:195], v[200:203], v[114:117]
	v_mfma_f32_16x16x32_bf16 v[102:105], v[184:187], v[208:211], v[102:105]
	v_mfma_f32_16x16x32_bf16 v[98:101], v[192:195], v[208:211], v[98:101]
	v_mfma_f32_16x16x32_bf16 v[86:89], v[184:187], v[216:219], v[86:89]
	v_mfma_f32_16x16x32_bf16 v[82:85], v[192:195], v[216:219], v[82:85]
	v_mfma_f32_16x16x32_bf16 v[70:73], v[184:187], v[224:227], v[70:73]
	v_mfma_f32_16x16x32_bf16 v[66:69], v[192:195], v[224:227], v[66:69]
	s_nop 3
	s_barrier
	s_setprio 0
	s_add_i32 s68, s39, s26
	v_lshl_add_u64 v[230:231], s[22:23], 0, v[150:151]
	s_mov_b32 m0, s68
	ds_read_b128 v[196:199], v178 offset:16384
	ds_read_b128 v[200:203], v178 offset:17408
	ds_read_b128 v[204:207], v178 offset:18432
	ds_read_b128 v[208:211], v178 offset:19456
	ds_read_b128 v[212:215], v178 offset:20480
	ds_read_b128 v[216:219], v178 offset:21504
	ds_read_b128 v[220:223], v178 offset:22528
	ds_read_b128 v[224:227], v178 offset:23552
	global_load_lds_dwordx4 v[230:231], off
	s_add_i32 m0, s68, 0x2000
	s_add_u32 s68, s22, 0x80000
	v_lshl_add_u64 v[232:233], s[22:23], 0, v[154:155]
	s_addc_u32 s69, s23, 0
	s_add_i32 s70, s40, s26
	global_load_lds_dwordx4 v[232:233], off
	v_lshl_add_u64 v[234:235], s[68:69], 0, v[150:151]
	s_mov_b32 m0, s70
	v_lshl_add_u64 v[236:237], s[24:25], 0, v[152:153]
	global_load_lds_dwordx4 v[234:235], off
	v_lshl_add_u64 v[234:235], s[68:69], 0, v[154:155]
	s_add_i32 m0, s70, 0x2000
	s_nop 0
	global_load_lds_dwordx4 v[234:235], off
	v_lshl_add_u64 v[234:235], s[24:25], 0, v[148:149]
	s_mov_b32 m0, s27
	s_nop 0
	global_load_lds_dwordx4 v[234:235], off
	s_mov_b32 m0, s28
	s_nop 0
	global_load_lds_dwordx4 v[236:237], off
	s_waitcnt vmcnt(8)
	s_waitcnt lgkmcnt(0)
	s_setprio 1
	s_barrier
; #define PG8_STAGE(bufoff, gbase, voff) do { _Pragma("unroll") for (int _i = 0; _i < 2; ++_i) \
;         __builtin_amdgcn_global_load_lds((const unsigned*)((const char*)(gbase) + (voff)[_i]), (PG8_LAS unsigned*)(lds + (bufoff) + ldsw + _i * 8192), 16, 0, 0); } while (0)
; #define PG8_WAIT_V(n) asm volatile("s_waitcnt vmcnt(" #n ")" ::: "memory")
; #define PG8_WAIT_L(n) asm volatile("s_waitcnt lgkmcnt(" #n ")" ::: "memory")
; #define PG8_BAR __builtin_amdgcn_s_barrier()
; #define PG8_SCHED __builtin_amdgcn_sched_barrier(0)
; template <class Epi, class Sched, bool ALIGN_EPI = true, bool SP2 = true>
; __device__ __forceinline__ void gemm_phase(PG8_LAS unsigned char* lds, const int K  , const Sched& S, const Epi& E) {
;     ...
;             PG8_WAIT_V(8); PG8_WAIT_L(0); PG8_BAR; PG8_MMA(1, 0, At, B0); PG8_MMA(1, 1, At, B1); PG8_BAR; PG8_SCHED;
;             PG8_LDB(B0, 1, 0); PG8_LDB(B1, 1, 1); PG8_SCHED; PG8_LDA(At, 1, 0); PG8_STAGE(PG8_SA(0, 1), a2 + hstep, voffA);
;             PG8_WAIT_V(8); PG8_WAIT_L(0); PG8_BAR; PG8_MMA(0, 0, At, B0); PG8_MMA(0, 1, At, B1); PG8_BAR; PG8_SCHED;
	v_mfma_f32_16x16x32_bf16 v[62:65], v[130:133], v[196:199], v[62:65]
	v_mfma_f32_16x16x32_bf16 v[58:61], v[138:141], v[196:199], v[58:61]
	v_mfma_f32_16x16x32_bf16 v[46:49], v[130:133], v[204:207], v[46:49]
	v_mfma_f32_16x16x32_bf16 v[42:45], v[138:141], v[204:207], v[42:45]
	v_mfma_f32_16x16x32_bf16 v[30:33], v[130:133], v[212:215], v[30:33]
	v_mfma_f32_16x16x32_bf16 v[26:29], v[138:141], v[212:215], v[26:29]
	v_mfma_f32_16x16x32_bf16 v[14:17], v[130:133], v[220:223], v[14:17]
	v_mfma_f32_16x16x32_bf16 v[10:13], v[138:141], v[220:223], v[10:13]
	v_mfma_f32_16x16x32_bf16 v[62:65], v[134:137], v[200:203], v[62:65]
	v_mfma_f32_16x16x32_bf16 v[58:61], v[142:145], v[200:203], v[58:61]
	v_mfma_f32_16x16x32_bf16 v[46:49], v[134:137], v[208:211], v[46:49]
	v_mfma_f32_16x16x32_bf16 v[42:45], v[142:145], v[208:211], v[42:45]
	v_mfma_f32_16x16x32_bf16 v[30:33], v[134:137], v[216:219], v[30:33]
	v_mfma_f32_16x16x32_bf16 v[26:29], v[142:145], v[216:219], v[26:29]
	v_mfma_f32_16x16x32_bf16 v[14:17], v[134:137], v[224:227], v[14:17]
	v_mfma_f32_16x16x32_bf16 v[10:13], v[142:145], v[224:227], v[10:13]
	s_setprio 0
	s_setprio 1
	v_mfma_f32_16x16x32_bf16 v[54:57], v[168:171], v[196:199], v[54:57]
	v_mfma_f32_16x16x32_bf16 v[50:53], v[188:191], v[196:199], v[50:53]
	v_mfma_f32_16x16x32_bf16 v[38:41], v[168:171], v[204:207], v[38:41]
	v_mfma_f32_16x16x32_bf16 v[34:37], v[188:191], v[204:207], v[34:37]
	v_mfma_f32_16x16x32_bf16 v[22:25], v[168:171], v[212:215], v[22:25]
	v_mfma_f32_16x16x32_bf16 v[18:21], v[188:191], v[212:215], v[18:21]
	v_mfma_f32_16x16x32_bf16 v[6:9], v[168:171], v[220:223], v[6:9]
	v_mfma_f32_16x16x32_bf16 v[2:5], v[188:191], v[220:223], v[2:5]
	v_mfma_f32_16x16x32_bf16 v[54:57], v[184:187], v[200:203], v[54:57]
	v_mfma_f32_16x16x32_bf16 v[50:53], v[192:195], v[200:203], v[50:53]
	v_mfma_f32_16x16x32_bf16 v[38:41], v[184:187], v[208:211], v[38:41]
	v_mfma_f32_16x16x32_bf16 v[34:37], v[192:195], v[208:211], v[34:37]
	v_mfma_f32_16x16x32_bf16 v[22:25], v[184:187], v[216:219], v[22:25]
	v_mfma_f32_16x16x32_bf16 v[18:21], v[192:195], v[216:219], v[18:21]
	v_mfma_f32_16x16x32_bf16 v[6:9], v[184:187], v[224:227], v[6:9]
	v_mfma_f32_16x16x32_bf16 v[2:5], v[192:195], v[224:227], v[2:5]
	s_nop 3
	s_barrier
	s_setprio 0
	s_add_i32 s68, 0, 0x18000
	s_add_i32 s69, 0, 0x1c000
	v_add_u32_e32 v142, s68, v172
	v_add_u32_e32 v192, s69, v172
	ds_read_b128 v[130:133], v142
	ds_read_b128 v[134:137], v142 offset:1024
	ds_read_b128 v[138:141], v142 offset:2048
	ds_read_b128 v[142:145], v142 offset:3072
	ds_read_b128 v[168:171], v192
	ds_read_b128 v[184:187], v192 offset:1024
	ds_read_b128 v[188:191], v192 offset:2048
	ds_read_b128 v[192:195], v192 offset:3072
	s_add_u32 s24, s24, 0x80000
	s_addc_u32 s25, s25, 0
	s_mov_b32 m0, s29
	v_lshl_add_u64 v[238:239], s[24:25], 0, v[148:149]
	ds_read_b128 v[196:199], v178 offset:32768
	ds_read_b128 v[200:203], v178 offset:33792
	ds_read_b128 v[204:207], v178 offset:34816
	ds_read_b128 v[208:211], v178 offset:35840
	ds_read_b128 v[212:215], v178 offset:36864
	ds_read_b128 v[216:219], v178 offset:37888
	ds_read_b128 v[220:223], v178 offset:38912
	ds_read_b128 v[224:227], v178 offset:39936
	global_load_lds_dwordx4 v[238:239], off
	v_lshl_add_u64 v[238:239], s[24:25], 0, v[152:153]
	s_mov_b32 m0, s30
	s_nop 0
	global_load_lds_dwordx4 v[238:239], off
	s_waitcnt vmcnt(8)
	s_waitcnt lgkmcnt(0)
	s_setprio 1
	s_barrier
	v_mfma_f32_16x16x32_bf16 v[126:129], v[130:133], v[196:199], v[126:129]
	v_mfma_f32_16x16x32_bf16 v[122:125], v[138:141], v[196:199], v[122:125]
	v_mfma_f32_16x16x32_bf16 v[110:113], v[130:133], v[204:207], v[110:113]
	v_mfma_f32_16x16x32_bf16 v[106:109], v[138:141], v[204:207], v[106:109]
	v_mfma_f32_16x16x32_bf16 v[94:97], v[130:133], v[212:215], v[94:97]
	v_mfma_f32_16x16x32_bf16 v[90:93], v[138:141], v[212:215], v[90:93]
	v_mfma_f32_16x16x32_bf16 v[78:81], v[130:133], v[220:223], v[78:81]
	v_mfma_f32_16x16x32_bf16 v[74:77], v[138:141], v[220:223], v[74:77]
	v_mfma_f32_16x16x32_bf16 v[126:129], v[134:137], v[200:203], v[126:129]
	v_mfma_f32_16x16x32_bf16 v[122:125], v[142:145], v[200:203], v[122:125]
	v_mfma_f32_16x16x32_bf16 v[110:113], v[134:137], v[208:211], v[110:113]
	v_mfma_f32_16x16x32_bf16 v[106:109], v[142:145], v[208:211], v[106:109]
	v_mfma_f32_16x16x32_bf16 v[94:97], v[134:137], v[216:219], v[94:97]
	v_mfma_f32_16x16x32_bf16 v[90:93], v[142:145], v[216:219], v[90:93]
	v_mfma_f32_16x16x32_bf16 v[78:81], v[134:137], v[224:227], v[78:81]
	v_mfma_f32_16x16x32_bf16 v[74:77], v[142:145], v[224:227], v[74:77]
	s_setprio 0
	s_setprio 1
	v_mfma_f32_16x16x32_bf16 v[118:121], v[168:171], v[196:199], v[118:121]
	v_mfma_f32_16x16x32_bf16 v[114:117], v[188:191], v[196:199], v[114:117]
	v_mfma_f32_16x16x32_bf16 v[102:105], v[168:171], v[204:207], v[102:105]
	v_mfma_f32_16x16x32_bf16 v[98:101], v[188:191], v[204:207], v[98:101]
	v_mfma_f32_16x16x32_bf16 v[86:89], v[168:171], v[212:215], v[86:89]
	v_mfma_f32_16x16x32_bf16 v[82:85], v[188:191], v[212:215], v[82:85]
	v_mfma_f32_16x16x32_bf16 v[70:73], v[168:171], v[220:223], v[70:73]
	v_mfma_f32_16x16x32_bf16 v[66:69], v[188:191], v[220:223], v[66:69]
	v_mfma_f32_16x16x32_bf16 v[118:121], v[184:187], v[200:203], v[118:121]
	v_mfma_f32_16x16x32_bf16 v[114:117], v[192:195], v[200:203], v[114:117]
	v_mfma_f32_16x16x32_bf16 v[102:105], v[184:187], v[208:211], v[102:105]
	v_mfma_f32_16x16x32_bf16 v[98:101], v[192:195], v[208:211], v[98:101]
	v_mfma_f32_16x16x32_bf16 v[86:89], v[184:187], v[216:219], v[86:89]
	v_mfma_f32_16x16x32_bf16 v[82:85], v[192:195], v[216:219], v[82:85]
	v_mfma_f32_16x16x32_bf16 v[70:73], v[184:187], v[224:227], v[70:73]
	v_mfma_f32_16x16x32_bf16 v[66:69], v[192:195], v[224:227], v[66:69]
	s_nop 3
	s_barrier
; #define PG8_STAGE(bufoff, gbase, voff) do { _Pragma("unroll") for (int _i = 0; _i < 2; ++_i) \
;         __builtin_amdgcn_global_load_lds((const unsigned*)((const char*)(gbase) + (voff)[_i]), (PG8_LAS unsigned*)(lds + (bufoff) + ldsw + _i * 8192), 16, 0, 0); } while (0)
; #define PG8_WAIT_V(n) asm volatile("s_waitcnt vmcnt(" #n ")" ::: "memory")
; #define PG8_WAIT_L(n) asm volatile("s_waitcnt lgkmcnt(" #n ")" ::: "memory")
; #define PG8_BAR __builtin_amdgcn_s_barrier()
; #define PG8_SCHED __builtin_amdgcn_sched_barrier(0)
; template <class Epi, class Sched, bool ALIGN_EPI = true, bool SP2 = true>
; __device__ __forceinline__ void gemm_phase(PG8_LAS unsigned char* lds, const int K  , const Sched& S, const Epi& E) {
;     ...
;             PG8_LDA(At, 1, 1); PG8_STAGE(PG8_SB(1, 0), b3, voffB); PG8_STAGE(PG8_SB(1, 1), b3 + hstep, voffB); PG8_STAGE(PG8_SA(1, 0), a3, voffA);
;             PG8_WAIT_V(8); PG8_WAIT_L(0); PG8_BAR; PG8_MMA(1, 0, At, B0); PG8_MMA(1, 1, At, B1); PG8_BAR; PG8_SCHED;
	s_setprio 0
	s_add_i32 s24, s68, s26
	v_lshl_add_u64 v[230:231], v[230:231], 0, s[4:5]
	s_mov_b32 m0, s24
	ds_read_b128 v[196:199], v178 offset:49152
	ds_read_b128 v[200:203], v178 offset:50176
	ds_read_b128 v[204:207], v178 offset:51200
	ds_read_b128 v[208:211], v178 offset:52224
	ds_read_b128 v[212:215], v178 offset:53248
	ds_read_b128 v[216:219], v178 offset:54272
	ds_read_b128 v[220:223], v178 offset:55296
	ds_read_b128 v[224:227], v178 offset:56320
	global_load_lds_dwordx4 v[230:231], off
	s_add_i32 m0, s24, 0x2000
	s_add_u32 s22, s22, 0x80080
	v_lshl_add_u64 v[230:231], v[232:233], 0, s[4:5]
	s_addc_u32 s23, s23, 0
	s_add_i32 s24, s69, s26
	global_load_lds_dwordx4 v[230:231], off
	v_lshl_add_u64 v[230:231], s[22:23], 0, v[150:151]
	s_mov_b32 m0, s24
	s_nop 0
	global_load_lds_dwordx4 v[230:231], off
	v_lshl_add_u64 v[230:231], s[22:23], 0, v[154:155]
	s_add_i32 m0, s24, 0x2000
	s_nop 0
	global_load_lds_dwordx4 v[230:231], off
	v_lshl_add_u64 v[230:231], v[234:235], 0, s[4:5]
	s_mov_b32 m0, s35
	s_nop 0
	global_load_lds_dwordx4 v[230:231], off
	v_lshl_add_u64 v[230:231], v[236:237], 0, s[4:5]
	s_mov_b32 m0, s36
	s_nop 0
	global_load_lds_dwordx4 v[230:231], off
	s_waitcnt vmcnt(8)
	s_waitcnt lgkmcnt(0)
	s_setprio 1
	s_barrier
	v_mfma_f32_16x16x32_bf16 v[62:65], v[130:133], v[196:199], v[62:65]
	v_mfma_f32_16x16x32_bf16 v[58:61], v[138:141], v[196:199], v[58:61]
	v_mfma_f32_16x16x32_bf16 v[46:49], v[130:133], v[204:207], v[46:49]
	v_mfma_f32_16x16x32_bf16 v[42:45], v[138:141], v[204:207], v[42:45]
	v_mfma_f32_16x16x32_bf16 v[30:33], v[130:133], v[212:215], v[30:33]
	v_mfma_f32_16x16x32_bf16 v[26:29], v[138:141], v[212:215], v[26:29]
	v_mfma_f32_16x16x32_bf16 v[14:17], v[130:133], v[220:223], v[14:17]
	v_mfma_f32_16x16x32_bf16 v[10:13], v[138:141], v[220:223], v[10:13]
	v_mfma_f32_16x16x32_bf16 v[62:65], v[134:137], v[200:203], v[62:65]
	v_mfma_f32_16x16x32_bf16 v[58:61], v[142:145], v[200:203], v[58:61]
	v_mfma_f32_16x16x32_bf16 v[46:49], v[134:137], v[208:211], v[46:49]
	v_mfma_f32_16x16x32_bf16 v[42:45], v[142:145], v[208:211], v[42:45]
	v_mfma_f32_16x16x32_bf16 v[30:33], v[134:137], v[216:219], v[30:33]
	v_mfma_f32_16x16x32_bf16 v[26:29], v[142:145], v[216:219], v[26:29]
	v_mfma_f32_16x16x32_bf16 v[14:17], v[134:137], v[224:227], v[14:17]
	v_mfma_f32_16x16x32_bf16 v[10:13], v[142:145], v[224:227], v[10:13]
	s_setprio 0
	s_setprio 1
	v_mfma_f32_16x16x32_bf16 v[54:57], v[168:171], v[196:199], v[54:57]
	v_mfma_f32_16x16x32_bf16 v[50:53], v[188:191], v[196:199], v[50:53]
	v_mfma_f32_16x16x32_bf16 v[38:41], v[168:171], v[204:207], v[38:41]
	v_mfma_f32_16x16x32_bf16 v[34:37], v[188:191], v[204:207], v[34:37]
	v_mfma_f32_16x16x32_bf16 v[22:25], v[168:171], v[212:215], v[22:25]
	v_mfma_f32_16x16x32_bf16 v[18:21], v[188:191], v[212:215], v[18:21]
	v_mfma_f32_16x16x32_bf16 v[6:9], v[168:171], v[220:223], v[6:9]
	v_mfma_f32_16x16x32_bf16 v[2:5], v[188:191], v[220:223], v[2:5]
	v_mfma_f32_16x16x32_bf16 v[54:57], v[184:187], v[200:203], v[54:57]
	v_mfma_f32_16x16x32_bf16 v[50:53], v[192:195], v[200:203], v[50:53]
	v_mfma_f32_16x16x32_bf16 v[38:41], v[184:187], v[208:211], v[38:41]
	v_mfma_f32_16x16x32_bf16 v[34:37], v[192:195], v[208:211], v[34:37]
	v_mfma_f32_16x16x32_bf16 v[22:25], v[184:187], v[216:219], v[22:25]
	v_mfma_f32_16x16x32_bf16 v[18:21], v[192:195], v[216:219], v[18:21]
	v_mfma_f32_16x16x32_bf16 v[6:9], v[184:187], v[224:227], v[6:9]
	v_mfma_f32_16x16x32_bf16 v[2:5], v[192:195], v[224:227], v[2:5]
	s_nop 3
	s_barrier
	s_setprio 0
	s_add_i32 s51, s51, 2
	s_add_u32 s0, s0, 0x100
	s_addc_u32 s1, s1, 0
	s_add_u32 s49, s49, 0x100
	s_addc_u32 s50, s50, 0
	s_cmp_gt_u32 s51, 29
	s_cbranch_scc0 .LBB0_1847
	s_and_b64 vcc, exec, s[8:9]
	s_cbranch_vccz .LBB0_1850
	s_barrier

; #define PG8_STAGE(bufoff, gbase, voff) do { _Pragma("unroll") for (int _i = 0; _i < 2; ++_i) \
;         __builtin_amdgcn_global_load_lds((const unsigned*)((const char*)(gbase) + (voff)[_i]), (PG8_LAS unsigned*)(lds + (bufoff) + ldsw + _i * 8192), 16, 0, 0); } while (0)
; #define PG8_WAIT_V(n) asm volatile("s_waitcnt vmcnt(" #n ")" ::: "memory")
; #define PG8_WAIT_L(n) asm volatile("s_waitcnt lgkmcnt(" #n ")" ::: "memory")
; #define PG8_BAR __builtin_amdgcn_s_barrier()
; #define PG8_SCHED __builtin_amdgcn_sched_barrier(0)
; template <class Epi, class Sched, bool ALIGN_EPI = true, bool SP2 = true>
; __device__ __forceinline__ void gemm_phase(PG8_LAS unsigned char* lds, const int K  , const Sched& S, const Epi& E) {
;     ...
;             PG8_LDB(B0, 0, 0); PG8_LDB(B1, 0, 1); PG8_SCHED; PG8_LDA(At, 0, 0); PG8_STAGE(PG8_SA(1, 1), a1 + hstep, voffA);
;             PG8_WAIT_V(8); PG8_WAIT_L(0); PG8_BAR; PG8_MMA(0, 0, At, B0); PG8_MMA(0, 1, At, B1); PG8_BAR; PG8_SCHED;
;             PG8_LDA(At, 0, 1); PG8_STAGE(PG8_SB(0, 0), b2, voffB); PG8_STAGE(PG8_SB(0, 1), b2 + hstep, voffB); PG8_STAGE(PG8_SA(0, 0), a2, voffA);
.LBB0_2296:
	ds_read_b128 v[130:133], v203
	ds_read_b128 v[134:137], v203 offset:1024
	ds_read_b128 v[138:141], v203 offset:2048
	ds_read_b128 v[142:145], v203 offset:3072
	ds_read_b128 v[146:149], v204
	ds_read_b128 v[150:153], v204 offset:1024
	ds_read_b128 v[154:157], v204 offset:2048
	ds_read_b128 v[158:161], v204 offset:3072
	s_add_u32 s22, s20, 0xfff80080
	s_addc_u32 s23, s21, -1
	s_cmp_eq_u32 s54, 28
	s_cselect_b32 s25, s13, s23
	s_cselect_b32 s24, s50, s22
	s_cselect_b32 s23, s11, s53
	s_cselect_b32 s22, s51, s52
	v_lshl_add_u64 v[198:199], s[20:21], 0, v[190:191]
	s_add_i32 m0, s19, 0xc000
	ds_read_b128 v[162:165], v205
	ds_read_b128 v[166:169], v205 offset:1024
	ds_read_b128 v[170:173], v205 offset:2048
	ds_read_b128 v[174:177], v205 offset:3072
	ds_read_b128 v[178:181], v205 offset:4096
	ds_read_b128 v[206:209], v205 offset:5120
	ds_read_b128 v[210:213], v205 offset:6144
	ds_read_b128 v[214:217], v205 offset:7168
	global_load_lds_dwordx4 v[198:199], off
	v_lshl_add_u64 v[198:199], s[20:21], 0, v[192:193]
	s_add_i32 m0, s19, 0xe000
	s_nop 0
	global_load_lds_dwordx4 v[198:199], off
	s_waitcnt vmcnt(8)
	s_waitcnt lgkmcnt(0)
	s_setprio 1
	s_barrier
	v_mfma_f32_16x16x32_bf16 v[126:129], v[130:133], v[162:165], v[126:129]
	v_mfma_f32_16x16x32_bf16 v[122:125], v[138:141], v[162:165], v[122:125]
	v_mfma_f32_16x16x32_bf16 v[114:117], v[130:133], v[170:173], v[114:117]
	v_mfma_f32_16x16x32_bf16 v[106:109], v[138:141], v[170:173], v[106:109]
	v_mfma_f32_16x16x32_bf16 v[98:101], v[130:133], v[178:181], v[98:101]
	v_mfma_f32_16x16x32_bf16 v[90:93], v[138:141], v[178:181], v[90:93]
	v_mfma_f32_16x16x32_bf16 v[82:85], v[130:133], v[210:213], v[82:85]
	v_mfma_f32_16x16x32_bf16 v[74:77], v[138:141], v[210:213], v[74:77]
	v_mfma_f32_16x16x32_bf16 v[126:129], v[134:137], v[166:169], v[126:129]
	v_mfma_f32_16x16x32_bf16 v[122:125], v[142:145], v[166:169], v[122:125]
	v_mfma_f32_16x16x32_bf16 v[114:117], v[134:137], v[174:177], v[114:117]
	v_mfma_f32_16x16x32_bf16 v[106:109], v[142:145], v[174:177], v[106:109]
	v_mfma_f32_16x16x32_bf16 v[98:101], v[134:137], v[206:209], v[98:101]
	v_mfma_f32_16x16x32_bf16 v[90:93], v[142:145], v[206:209], v[90:93]
	v_mfma_f32_16x16x32_bf16 v[82:85], v[134:137], v[214:217], v[82:85]
	v_mfma_f32_16x16x32_bf16 v[74:77], v[142:145], v[214:217], v[74:77]
	s_setprio 0
	s_setprio 1
	v_mfma_f32_16x16x32_bf16 v[118:121], v[146:149], v[162:165], v[118:121]
	v_mfma_f32_16x16x32_bf16 v[110:113], v[154:157], v[162:165], v[110:113]
	v_mfma_f32_16x16x32_bf16 v[102:105], v[146:149], v[170:173], v[102:105]
	v_mfma_f32_16x16x32_bf16 v[94:97], v[154:157], v[170:173], v[94:97]
	v_mfma_f32_16x16x32_bf16 v[86:89], v[146:149], v[178:181], v[86:89]
	v_mfma_f32_16x16x32_bf16 v[78:81], v[154:157], v[178:181], v[78:81]
	v_mfma_f32_16x16x32_bf16 v[70:73], v[146:149], v[210:213], v[70:73]
	v_mfma_f32_16x16x32_bf16 v[66:69], v[154:157], v[210:213], v[66:69]
	v_mfma_f32_16x16x32_bf16 v[118:121], v[150:153], v[166:169], v[118:121]
	v_mfma_f32_16x16x32_bf16 v[110:113], v[158:161], v[166:169], v[110:113]
	v_mfma_f32_16x16x32_bf16 v[102:105], v[150:153], v[174:177], v[102:105]
	v_mfma_f32_16x16x32_bf16 v[94:97], v[158:161], v[174:177], v[94:97]
	v_mfma_f32_16x16x32_bf16 v[86:89], v[150:153], v[206:209], v[86:89]
	v_mfma_f32_16x16x32_bf16 v[78:81], v[158:161], v[206:209], v[78:81]
	v_mfma_f32_16x16x32_bf16 v[70:73], v[150:153], v[214:217], v[70:73]
	v_mfma_f32_16x16x32_bf16 v[66:69], v[158:161], v[214:217], v[66:69]
	s_nop 3
	s_barrier
	s_setprio 0
	s_add_i32 s55, s42, s29
	v_lshl_add_u64 v[198:199], s[22:23], 0, v[184:185]
	s_mov_b32 m0, s55
	ds_read_b128 v[162:165], v205 offset:16384
	ds_read_b128 v[166:169], v205 offset:17408
	ds_read_b128 v[170:173], v205 offset:18432
	ds_read_b128 v[174:177], v205 offset:19456
	ds_read_b128 v[178:181], v205 offset:20480
	ds_read_b128 v[206:209], v205 offset:21504
	ds_read_b128 v[210:213], v205 offset:22528
	ds_read_b128 v[214:217], v205 offset:23552
	global_load_lds_dwordx4 v[198:199], off
	s_add_i32 m0, s55, 0x2000
	s_add_u32 s56, s22, 0x80000
	v_lshl_add_u64 v[218:219], s[22:23], 0, v[188:189]
	s_addc_u32 s57, s23, 0
	s_add_i32 s55, s43, s29
	global_load_lds_dwordx4 v[218:219], off
	v_lshl_add_u64 v[220:221], s[56:57], 0, v[184:185]
	s_mov_b32 m0, s55
	v_lshl_add_u64 v[222:223], s[24:25], 0, v[186:187]
	global_load_lds_dwordx4 v[220:221], off
	v_lshl_add_u64 v[220:221], s[56:57], 0, v[188:189]
	s_add_i32 m0, s55, 0x2000
	s_nop 0
	global_load_lds_dwordx4 v[220:221], off
	v_lshl_add_u64 v[220:221], s[24:25], 0, v[182:183]
	s_mov_b32 m0, s19
	s_nop 0
	global_load_lds_dwordx4 v[220:221], off
	s_mov_b32 m0, s30
	s_nop 0
	global_load_lds_dwordx4 v[222:223], off
	s_waitcnt vmcnt(8)
	s_waitcnt lgkmcnt(0)
	s_setprio 1
	s_barrier
; #define PG8_STAGE(bufoff, gbase, voff) do { _Pragma("unroll") for (int _i = 0; _i < 2; ++_i) \
;         __builtin_amdgcn_global_load_lds((const unsigned*)((const char*)(gbase) + (voff)[_i]), (PG8_LAS unsigned*)(lds + (bufoff) + ldsw + _i * 8192), 16, 0, 0); } while (0)
; #define PG8_WAIT_V(n) asm volatile("s_waitcnt vmcnt(" #n ")" ::: "memory")
; #define PG8_WAIT_L(n) asm volatile("s_waitcnt lgkmcnt(" #n ")" ::: "memory")
; #define PG8_BAR __builtin_amdgcn_s_barrier()
; #define PG8_SCHED __builtin_amdgcn_sched_barrier(0)
; template <class Epi, class Sched, bool ALIGN_EPI = true, bool SP2 = true>
; __device__ __forceinline__ void gemm_phase(PG8_LAS unsigned char* lds, const int K  , const Sched& S, const Epi& E) {
;     ...
;             PG8_WAIT_V(8); PG8_WAIT_L(0); PG8_BAR; PG8_MMA(1, 0, At, B0); PG8_MMA(1, 1, At, B1); PG8_BAR; PG8_SCHED;
;             PG8_LDB(B0, 1, 0); PG8_LDB(B1, 1, 1); PG8_SCHED; PG8_LDA(At, 1, 0); PG8_STAGE(PG8_SA(0, 1), a2 + hstep, voffA);
;             PG8_WAIT_V(8); PG8_WAIT_L(0); PG8_BAR; PG8_MMA(0, 0, At, B0); PG8_MMA(0, 1, At, B1); PG8_BAR; PG8_SCHED;
	v_mfma_f32_16x16x32_bf16 v[62:65], v[130:133], v[162:165], v[62:65]
	v_mfma_f32_16x16x32_bf16 v[58:61], v[138:141], v[162:165], v[58:61]
	v_mfma_f32_16x16x32_bf16 v[50:53], v[130:133], v[170:173], v[50:53]
	v_mfma_f32_16x16x32_bf16 v[42:45], v[138:141], v[170:173], v[42:45]
	v_mfma_f32_16x16x32_bf16 v[34:37], v[130:133], v[178:181], v[34:37]
	v_mfma_f32_16x16x32_bf16 v[26:29], v[138:141], v[178:181], v[26:29]
	v_mfma_f32_16x16x32_bf16 v[18:21], v[130:133], v[210:213], v[18:21]
	v_mfma_f32_16x16x32_bf16 v[10:13], v[138:141], v[210:213], v[10:13]
	v_mfma_f32_16x16x32_bf16 v[62:65], v[134:137], v[166:169], v[62:65]
	v_mfma_f32_16x16x32_bf16 v[58:61], v[142:145], v[166:169], v[58:61]
	v_mfma_f32_16x16x32_bf16 v[50:53], v[134:137], v[174:177], v[50:53]
	v_mfma_f32_16x16x32_bf16 v[42:45], v[142:145], v[174:177], v[42:45]
	v_mfma_f32_16x16x32_bf16 v[34:37], v[134:137], v[206:209], v[34:37]
	v_mfma_f32_16x16x32_bf16 v[26:29], v[142:145], v[206:209], v[26:29]
	v_mfma_f32_16x16x32_bf16 v[18:21], v[134:137], v[214:217], v[18:21]
	v_mfma_f32_16x16x32_bf16 v[10:13], v[142:145], v[214:217], v[10:13]
	s_setprio 0
	s_setprio 1
	v_mfma_f32_16x16x32_bf16 v[54:57], v[146:149], v[162:165], v[54:57]
	v_mfma_f32_16x16x32_bf16 v[46:49], v[154:157], v[162:165], v[46:49]
	v_mfma_f32_16x16x32_bf16 v[38:41], v[146:149], v[170:173], v[38:41]
	v_mfma_f32_16x16x32_bf16 v[30:33], v[154:157], v[170:173], v[30:33]
	v_mfma_f32_16x16x32_bf16 v[22:25], v[146:149], v[178:181], v[22:25]
	v_mfma_f32_16x16x32_bf16 v[14:17], v[154:157], v[178:181], v[14:17]
	v_mfma_f32_16x16x32_bf16 v[6:9], v[146:149], v[210:213], v[6:9]
	v_mfma_f32_16x16x32_bf16 v[2:5], v[154:157], v[210:213], v[2:5]
	v_mfma_f32_16x16x32_bf16 v[54:57], v[150:153], v[166:169], v[54:57]
	v_mfma_f32_16x16x32_bf16 v[46:49], v[158:161], v[166:169], v[46:49]
	v_mfma_f32_16x16x32_bf16 v[38:41], v[150:153], v[174:177], v[38:41]
	v_mfma_f32_16x16x32_bf16 v[30:33], v[158:161], v[174:177], v[30:33]
	v_mfma_f32_16x16x32_bf16 v[22:25], v[150:153], v[206:209], v[22:25]
	v_mfma_f32_16x16x32_bf16 v[14:17], v[158:161], v[206:209], v[14:17]
	v_mfma_f32_16x16x32_bf16 v[6:9], v[150:153], v[214:217], v[6:9]
	v_mfma_f32_16x16x32_bf16 v[2:5], v[158:161], v[214:217], v[2:5]
	s_nop 3
	s_barrier
	s_setprio 0
	s_add_i32 s55, 0, 0x18000
	s_add_i32 s56, 0, 0x1c000
	v_add_u32_e32 v142, s55, v201
	v_add_u32_e32 v158, s56, v201
	ds_read_b128 v[130:133], v142
	ds_read_b128 v[134:137], v142 offset:1024
	ds_read_b128 v[138:141], v142 offset:2048
	ds_read_b128 v[142:145], v142 offset:3072
	ds_read_b128 v[146:149], v158
	ds_read_b128 v[150:153], v158 offset:1024
	ds_read_b128 v[154:157], v158 offset:2048
	ds_read_b128 v[158:161], v158 offset:3072
	s_add_u32 s24, s24, 0x80000
	s_addc_u32 s25, s25, 0
	s_mov_b32 m0, s31
	v_lshl_add_u64 v[224:225], s[24:25], 0, v[182:183]
	ds_read_b128 v[162:165], v205 offset:32768
	ds_read_b128 v[166:169], v205 offset:33792
	ds_read_b128 v[170:173], v205 offset:34816
	ds_read_b128 v[174:177], v205 offset:35840
	ds_read_b128 v[178:181], v205 offset:36864
	ds_read_b128 v[206:209], v205 offset:37888
	ds_read_b128 v[210:213], v205 offset:38912
	ds_read_b128 v[214:217], v205 offset:39936
	global_load_lds_dwordx4 v[224:225], off
	v_lshl_add_u64 v[224:225], s[24:25], 0, v[186:187]
	s_mov_b32 m0, s33
	s_nop 0
	global_load_lds_dwordx4 v[224:225], off
	s_waitcnt vmcnt(8)
	s_waitcnt lgkmcnt(0)
	s_setprio 1
	s_barrier
	v_mfma_f32_16x16x32_bf16 v[126:129], v[130:133], v[162:165], v[126:129]
	v_mfma_f32_16x16x32_bf16 v[122:125], v[138:141], v[162:165], v[122:125]
	v_mfma_f32_16x16x32_bf16 v[114:117], v[130:133], v[170:173], v[114:117]
	v_mfma_f32_16x16x32_bf16 v[106:109], v[138:141], v[170:173], v[106:109]
	v_mfma_f32_16x16x32_bf16 v[98:101], v[130:133], v[178:181], v[98:101]
	v_mfma_f32_16x16x32_bf16 v[90:93], v[138:141], v[178:181], v[90:93]
	v_mfma_f32_16x16x32_bf16 v[82:85], v[130:133], v[210:213], v[82:85]
	v_mfma_f32_16x16x32_bf16 v[74:77], v[138:141], v[210:213], v[74:77]
	v_mfma_f32_16x16x32_bf16 v[126:129], v[134:137], v[166:169], v[126:129]
	v_mfma_f32_16x16x32_bf16 v[122:125], v[142:145], v[166:169], v[122:125]
	v_mfma_f32_16x16x32_bf16 v[114:117], v[134:137], v[174:177], v[114:117]
	v_mfma_f32_16x16x32_bf16 v[106:109], v[142:145], v[174:177], v[106:109]
	v_mfma_f32_16x16x32_bf16 v[98:101], v[134:137], v[206:209], v[98:101]
	v_mfma_f32_16x16x32_bf16 v[90:93], v[142:145], v[206:209], v[90:93]
	v_mfma_f32_16x16x32_bf16 v[82:85], v[134:137], v[214:217], v[82:85]
	v_mfma_f32_16x16x32_bf16 v[74:77], v[142:145], v[214:217], v[74:77]
	s_setprio 0
	s_setprio 1
	v_mfma_f32_16x16x32_bf16 v[118:121], v[146:149], v[162:165], v[118:121]
	v_mfma_f32_16x16x32_bf16 v[110:113], v[154:157], v[162:165], v[110:113]
	v_mfma_f32_16x16x32_bf16 v[102:105], v[146:149], v[170:173], v[102:105]
	v_mfma_f32_16x16x32_bf16 v[94:97], v[154:157], v[170:173], v[94:97]
	v_mfma_f32_16x16x32_bf16 v[86:89], v[146:149], v[178:181], v[86:89]
	v_mfma_f32_16x16x32_bf16 v[78:81], v[154:157], v[178:181], v[78:81]
	v_mfma_f32_16x16x32_bf16 v[70:73], v[146:149], v[210:213], v[70:73]
	v_mfma_f32_16x16x32_bf16 v[66:69], v[154:157], v[210:213], v[66:69]
	v_mfma_f32_16x16x32_bf16 v[118:121], v[150:153], v[166:169], v[118:121]
	v_mfma_f32_16x16x32_bf16 v[110:113], v[158:161], v[166:169], v[110:113]
	v_mfma_f32_16x16x32_bf16 v[102:105], v[150:153], v[174:177], v[102:105]
	v_mfma_f32_16x16x32_bf16 v[94:97], v[158:161], v[174:177], v[94:97]
	v_mfma_f32_16x16x32_bf16 v[86:89], v[150:153], v[206:209], v[86:89]
	v_mfma_f32_16x16x32_bf16 v[78:81], v[158:161], v[206:209], v[78:81]
	v_mfma_f32_16x16x32_bf16 v[70:73], v[150:153], v[214:217], v[70:73]
	v_mfma_f32_16x16x32_bf16 v[66:69], v[158:161], v[214:217], v[66:69]
	s_nop 3
	s_barrier
; #define PG8_STAGE(bufoff, gbase, voff) do { _Pragma("unroll") for (int _i = 0; _i < 2; ++_i) \
;         __builtin_amdgcn_global_load_lds((const unsigned*)((const char*)(gbase) + (voff)[_i]), (PG8_LAS unsigned*)(lds + (bufoff) + ldsw + _i * 8192), 16, 0, 0); } while (0)
; #define PG8_WAIT_V(n) asm volatile("s_waitcnt vmcnt(" #n ")" ::: "memory")
; #define PG8_WAIT_L(n) asm volatile("s_waitcnt lgkmcnt(" #n ")" ::: "memory")
; #define PG8_BAR __builtin_amdgcn_s_barrier()
; #define PG8_SCHED __builtin_amdgcn_sched_barrier(0)
; template <class Epi, class Sched, bool ALIGN_EPI = true, bool SP2 = true>
; __device__ __forceinline__ void gemm_phase(PG8_LAS unsigned char* lds, const int K  , const Sched& S, const Epi& E) {
;     ...
;             PG8_LDA(At, 1, 1); PG8_STAGE(PG8_SB(1, 0), b3, voffB); PG8_STAGE(PG8_SB(1, 1), b3 + hstep, voffB); PG8_STAGE(PG8_SA(1, 0), a3, voffA);
;             PG8_WAIT_V(8); PG8_WAIT_L(0); PG8_BAR; PG8_MMA(1, 0, At, B0); PG8_MMA(1, 1, At, B1); PG8_BAR; PG8_SCHED;
	s_setprio 0
	s_add_i32 s24, s55, s29
	v_lshl_add_u64 v[198:199], v[198:199], 0, s[6:7]
	s_mov_b32 m0, s24
	ds_read_b128 v[162:165], v205 offset:49152
	ds_read_b128 v[166:169], v205 offset:50176
	ds_read_b128 v[170:173], v205 offset:51200
	ds_read_b128 v[174:177], v205 offset:52224
	ds_read_b128 v[178:181], v205 offset:53248
	ds_read_b128 v[206:209], v205 offset:54272
	ds_read_b128 v[210:213], v205 offset:55296
	ds_read_b128 v[214:217], v205 offset:56320
	global_load_lds_dwordx4 v[198:199], off
	s_add_i32 m0, s24, 0x2000
	s_add_u32 s22, s22, 0x80080
	v_lshl_add_u64 v[198:199], v[218:219], 0, s[6:7]
	s_addc_u32 s23, s23, 0
	s_add_i32 s24, s56, s29
	global_load_lds_dwordx4 v[198:199], off
	v_lshl_add_u64 v[198:199], s[22:23], 0, v[184:185]
	s_mov_b32 m0, s24
	s_nop 0
	global_load_lds_dwordx4 v[198:199], off
	v_lshl_add_u64 v[198:199], s[22:23], 0, v[188:189]
	s_add_i32 m0, s24, 0x2000
	s_nop 0
	global_load_lds_dwordx4 v[198:199], off
	v_lshl_add_u64 v[198:199], v[220:221], 0, s[6:7]
	s_mov_b32 m0, s38
	s_nop 0
	global_load_lds_dwordx4 v[198:199], off
	v_lshl_add_u64 v[198:199], v[222:223], 0, s[6:7]
	s_mov_b32 m0, s39
	s_nop 0
	global_load_lds_dwordx4 v[198:199], off
	s_waitcnt vmcnt(8)
	s_waitcnt lgkmcnt(0)
	s_setprio 1
	s_barrier
	v_mfma_f32_16x16x32_bf16 v[62:65], v[130:133], v[162:165], v[62:65]
	v_mfma_f32_16x16x32_bf16 v[58:61], v[138:141], v[162:165], v[58:61]
	v_mfma_f32_16x16x32_bf16 v[50:53], v[130:133], v[170:173], v[50:53]
	v_mfma_f32_16x16x32_bf16 v[42:45], v[138:141], v[170:173], v[42:45]
	v_mfma_f32_16x16x32_bf16 v[34:37], v[130:133], v[178:181], v[34:37]
	v_mfma_f32_16x16x32_bf16 v[26:29], v[138:141], v[178:181], v[26:29]
	v_mfma_f32_16x16x32_bf16 v[18:21], v[130:133], v[210:213], v[18:21]
	v_mfma_f32_16x16x32_bf16 v[10:13], v[138:141], v[210:213], v[10:13]
	v_mfma_f32_16x16x32_bf16 v[62:65], v[134:137], v[166:169], v[62:65]
	v_mfma_f32_16x16x32_bf16 v[58:61], v[142:145], v[166:169], v[58:61]
	v_mfma_f32_16x16x32_bf16 v[50:53], v[134:137], v[174:177], v[50:53]
	v_mfma_f32_16x16x32_bf16 v[42:45], v[142:145], v[174:177], v[42:45]
	v_mfma_f32_16x16x32_bf16 v[34:37], v[134:137], v[206:209], v[34:37]
	v_mfma_f32_16x16x32_bf16 v[26:29], v[142:145], v[206:209], v[26:29]
	v_mfma_f32_16x16x32_bf16 v[18:21], v[134:137], v[214:217], v[18:21]
	v_mfma_f32_16x16x32_bf16 v[10:13], v[142:145], v[214:217], v[10:13]
	s_setprio 0
	s_setprio 1
	v_mfma_f32_16x16x32_bf16 v[54:57], v[146:149], v[162:165], v[54:57]
	v_mfma_f32_16x16x32_bf16 v[46:49], v[154:157], v[162:165], v[46:49]
	v_mfma_f32_16x16x32_bf16 v[38:41], v[146:149], v[170:173], v[38:41]
	v_mfma_f32_16x16x32_bf16 v[30:33], v[154:157], v[170:173], v[30:33]
	v_mfma_f32_16x16x32_bf16 v[22:25], v[146:149], v[178:181], v[22:25]
	v_mfma_f32_16x16x32_bf16 v[14:17], v[154:157], v[178:181], v[14:17]
	v_mfma_f32_16x16x32_bf16 v[6:9], v[146:149], v[210:213], v[6:9]
	v_mfma_f32_16x16x32_bf16 v[2:5], v[154:157], v[210:213], v[2:5]
	v_mfma_f32_16x16x32_bf16 v[54:57], v[150:153], v[166:169], v[54:57]
	v_mfma_f32_16x16x32_bf16 v[46:49], v[158:161], v[166:169], v[46:49]
	v_mfma_f32_16x16x32_bf16 v[38:41], v[150:153], v[174:177], v[38:41]
	v_mfma_f32_16x16x32_bf16 v[30:33], v[158:161], v[174:177], v[30:33]
	v_mfma_f32_16x16x32_bf16 v[22:25], v[150:153], v[206:209], v[22:25]
	v_mfma_f32_16x16x32_bf16 v[14:17], v[158:161], v[206:209], v[14:17]
	v_mfma_f32_16x16x32_bf16 v[6:9], v[150:153], v[214:217], v[6:9]
	v_mfma_f32_16x16x32_bf16 v[2:5], v[158:161], v[214:217], v[2:5]
	s_nop 3
	s_barrier
	s_setprio 0
	s_add_i32 s54, s54, 2
	s_add_u32 s20, s20, 0x100
	s_addc_u32 s21, s21, 0
	s_add_u32 s52, s52, 0x100
	s_addc_u32 s53, s53, 0
	s_cmp_gt_u32 s54, 29
	s_cbranch_scc0 .LBB0_2296
	s_and_b64 vcc, exec, s[8:9]
	s_cbranch_vccz .LBB0_2299
	s_barrier

; #define PG8_STAGE(bufoff, gbase, voff) do { _Pragma("unroll") for (int _i = 0; _i < 2; ++_i) \
;         __builtin_amdgcn_global_load_lds((const unsigned*)((const char*)(gbase) + (voff)[_i]), (PG8_LAS unsigned*)(lds + (bufoff) + ldsw + _i * 8192), 16, 0, 0); } while (0)
; #define PG8_WAIT_V(n) asm volatile("s_waitcnt vmcnt(" #n ")" ::: "memory")
; #define PG8_WAIT_L(n) asm volatile("s_waitcnt lgkmcnt(" #n ")" ::: "memory")
; #define PG8_BAR __builtin_amdgcn_s_barrier()
; #define PG8_SCHED __builtin_amdgcn_sched_barrier(0)
; template <class Epi, class Sched, bool ALIGN_EPI = true, bool SP2 = true>
; __device__ __forceinline__ void gemm_phase(PG8_LAS unsigned char* lds, const int K  , const Sched& S, const Epi& E) {
;     ...
;             PG8_LDB(B0, 0, 0); PG8_LDB(B1, 0, 1); PG8_SCHED; PG8_LDA(At, 0, 0); PG8_STAGE(PG8_SA(1, 1), a1 + hstep, voffA);
;             PG8_WAIT_V(8); PG8_WAIT_L(0); PG8_BAR; PG8_MMA(0, 0, At, B0); PG8_MMA(0, 1, At, B1); PG8_BAR; PG8_SCHED;
;             PG8_LDA(At, 0, 1); PG8_STAGE(PG8_SB(0, 0), b2, voffB); PG8_STAGE(PG8_SB(0, 1), b2 + hstep, voffB); PG8_STAGE(PG8_SA(0, 0), a2, voffA);
.LBB0_2433:
	ds_read_b128 v[146:149], v152
	ds_read_b128 v[158:161], v152 offset:1024
	ds_read_b128 v[162:165], v152 offset:2048
	ds_read_b128 v[166:169], v152 offset:3072
	ds_read_b128 v[170:173], v153
	ds_read_b128 v[174:177], v153 offset:1024
	ds_read_b128 v[178:181], v153 offset:2048
	ds_read_b128 v[182:185], v153 offset:3072
	s_add_u32 s22, s20, 0xfff80080
	s_addc_u32 s23, s21, -1
	s_cmp_eq_u32 s48, 28
	s_cselect_b32 s25, s13, s23
	s_cselect_b32 s24, s44, s22
	s_cselect_b32 s23, s11, s47
	s_cselect_b32 s22, s45, s46
	v_lshl_add_u64 v[218:219], s[20:21], 0, v[138:139]
	s_add_i32 m0, s19, 0xc000
	ds_read_b128 v[186:189], v154
	ds_read_b128 v[190:193], v154 offset:1024
	ds_read_b128 v[194:197], v154 offset:2048
	ds_read_b128 v[198:201], v154 offset:3072
	ds_read_b128 v[202:205], v154 offset:4096
	ds_read_b128 v[206:209], v154 offset:5120
	ds_read_b128 v[210:213], v154 offset:6144
	ds_read_b128 v[214:217], v154 offset:7168
	global_load_lds_dwordx4 v[218:219], off
	v_lshl_add_u64 v[218:219], s[20:21], 0, v[140:141]
	s_add_i32 m0, s19, 0xe000
	s_nop 0
	global_load_lds_dwordx4 v[218:219], off
	s_waitcnt vmcnt(8)
	s_waitcnt lgkmcnt(0)
	s_setprio 1
	s_barrier
	v_mfma_f32_16x16x32_bf16 v[126:129], v[146:149], v[186:189], v[126:129]
	v_mfma_f32_16x16x32_bf16 v[118:121], v[162:165], v[186:189], v[118:121]
	v_mfma_f32_16x16x32_bf16 v[110:113], v[146:149], v[194:197], v[110:113]
	v_mfma_f32_16x16x32_bf16 v[102:105], v[162:165], v[194:197], v[102:105]
	v_mfma_f32_16x16x32_bf16 v[94:97], v[146:149], v[202:205], v[94:97]
	v_mfma_f32_16x16x32_bf16 v[86:89], v[162:165], v[202:205], v[86:89]
	v_mfma_f32_16x16x32_bf16 v[78:81], v[146:149], v[210:213], v[78:81]
	v_mfma_f32_16x16x32_bf16 v[70:73], v[162:165], v[210:213], v[70:73]
	v_mfma_f32_16x16x32_bf16 v[126:129], v[158:161], v[190:193], v[126:129]
	v_mfma_f32_16x16x32_bf16 v[118:121], v[166:169], v[190:193], v[118:121]
	v_mfma_f32_16x16x32_bf16 v[110:113], v[158:161], v[198:201], v[110:113]
	v_mfma_f32_16x16x32_bf16 v[102:105], v[166:169], v[198:201], v[102:105]
	v_mfma_f32_16x16x32_bf16 v[94:97], v[158:161], v[206:209], v[94:97]
	v_mfma_f32_16x16x32_bf16 v[86:89], v[166:169], v[206:209], v[86:89]
	v_mfma_f32_16x16x32_bf16 v[78:81], v[158:161], v[214:217], v[78:81]
	v_mfma_f32_16x16x32_bf16 v[70:73], v[166:169], v[214:217], v[70:73]
	s_setprio 0
	s_setprio 1
	v_mfma_f32_16x16x32_bf16 v[122:125], v[170:173], v[186:189], v[122:125]
	v_mfma_f32_16x16x32_bf16 v[114:117], v[178:181], v[186:189], v[114:117]
	v_mfma_f32_16x16x32_bf16 v[106:109], v[170:173], v[194:197], v[106:109]
	v_mfma_f32_16x16x32_bf16 v[98:101], v[178:181], v[194:197], v[98:101]
	v_mfma_f32_16x16x32_bf16 v[90:93], v[170:173], v[202:205], v[90:93]
	v_mfma_f32_16x16x32_bf16 v[82:85], v[178:181], v[202:205], v[82:85]
	v_mfma_f32_16x16x32_bf16 v[74:77], v[170:173], v[210:213], v[74:77]
	v_mfma_f32_16x16x32_bf16 v[66:69], v[178:181], v[210:213], v[66:69]
	v_mfma_f32_16x16x32_bf16 v[122:125], v[174:177], v[190:193], v[122:125]
	v_mfma_f32_16x16x32_bf16 v[114:117], v[182:185], v[190:193], v[114:117]
	v_mfma_f32_16x16x32_bf16 v[106:109], v[174:177], v[198:201], v[106:109]
	v_mfma_f32_16x16x32_bf16 v[98:101], v[182:185], v[198:201], v[98:101]
	v_mfma_f32_16x16x32_bf16 v[90:93], v[174:177], v[206:209], v[90:93]
	v_mfma_f32_16x16x32_bf16 v[82:85], v[182:185], v[206:209], v[82:85]
	v_mfma_f32_16x16x32_bf16 v[74:77], v[174:177], v[214:217], v[74:77]
	v_mfma_f32_16x16x32_bf16 v[66:69], v[182:185], v[214:217], v[66:69]
	s_nop 3
	s_barrier
	s_setprio 0
	s_add_i32 s49, s39, s28
	v_lshl_add_u64 v[218:219], s[22:23], 0, v[134:135]
	s_mov_b32 m0, s49
	ds_read_b128 v[186:189], v154 offset:16384
	ds_read_b128 v[190:193], v154 offset:17408
	ds_read_b128 v[194:197], v154 offset:18432
	ds_read_b128 v[198:201], v154 offset:19456
	ds_read_b128 v[202:205], v154 offset:20480
	ds_read_b128 v[206:209], v154 offset:21504
	ds_read_b128 v[210:213], v154 offset:22528
	ds_read_b128 v[214:217], v154 offset:23552
	global_load_lds_dwordx4 v[218:219], off
	s_add_i32 m0, s49, 0x2000
	s_add_u32 s50, s22, 0x80000
	v_lshl_add_u64 v[220:221], s[22:23], 0, v[130:131]
	s_addc_u32 s51, s23, 0
	s_add_i32 s49, s40, s28
	global_load_lds_dwordx4 v[220:221], off
	v_lshl_add_u64 v[222:223], s[50:51], 0, v[134:135]
	s_mov_b32 m0, s49
	v_lshl_add_u64 v[224:225], s[24:25], 0, v[132:133]
	global_load_lds_dwordx4 v[222:223], off
	v_lshl_add_u64 v[222:223], s[50:51], 0, v[130:131]
	s_add_i32 m0, s49, 0x2000
	s_nop 0
	global_load_lds_dwordx4 v[222:223], off
	v_lshl_add_u64 v[222:223], s[24:25], 0, v[136:137]
	s_mov_b32 m0, s19
	s_nop 0
	global_load_lds_dwordx4 v[222:223], off
	s_mov_b32 m0, s31
	s_nop 0
	global_load_lds_dwordx4 v[224:225], off
	s_waitcnt vmcnt(8)
	s_waitcnt lgkmcnt(0)
	s_setprio 1
	s_barrier
; #define PG8_STAGE(bufoff, gbase, voff) do { _Pragma("unroll") for (int _i = 0; _i < 2; ++_i) \
;         __builtin_amdgcn_global_load_lds((const unsigned*)((const char*)(gbase) + (voff)[_i]), (PG8_LAS unsigned*)(lds + (bufoff) + ldsw + _i * 8192), 16, 0, 0); } while (0)
; #define PG8_WAIT_V(n) asm volatile("s_waitcnt vmcnt(" #n ")" ::: "memory")
; #define PG8_WAIT_L(n) asm volatile("s_waitcnt lgkmcnt(" #n ")" ::: "memory")
; #define PG8_BAR __builtin_amdgcn_s_barrier()
; #define PG8_SCHED __builtin_amdgcn_sched_barrier(0)
; template <class Epi, class Sched, bool ALIGN_EPI = true, bool SP2 = true>
; __device__ __forceinline__ void gemm_phase(PG8_LAS unsigned char* lds, const int K  , const Sched& S, const Epi& E) {
;     ...
;             PG8_WAIT_V(8); PG8_WAIT_L(0); PG8_BAR; PG8_MMA(1, 0, At, B0); PG8_MMA(1, 1, At, B1); PG8_BAR; PG8_SCHED;
;             PG8_LDB(B0, 1, 0); PG8_LDB(B1, 1, 1); PG8_SCHED; PG8_LDA(At, 1, 0); PG8_STAGE(PG8_SA(0, 1), a2 + hstep, voffA);
;             PG8_WAIT_V(8); PG8_WAIT_L(0); PG8_BAR; PG8_MMA(0, 0, At, B0); PG8_MMA(0, 1, At, B1); PG8_BAR; PG8_SCHED;
	v_mfma_f32_16x16x32_bf16 v[62:65], v[146:149], v[186:189], v[62:65]
	v_mfma_f32_16x16x32_bf16 v[54:57], v[162:165], v[186:189], v[54:57]
	v_mfma_f32_16x16x32_bf16 v[46:49], v[146:149], v[194:197], v[46:49]
	v_mfma_f32_16x16x32_bf16 v[38:41], v[162:165], v[194:197], v[38:41]
	v_mfma_f32_16x16x32_bf16 v[30:33], v[146:149], v[202:205], v[30:33]
	v_mfma_f32_16x16x32_bf16 v[22:25], v[162:165], v[202:205], v[22:25]
	v_mfma_f32_16x16x32_bf16 v[14:17], v[146:149], v[210:213], v[14:17]
	v_mfma_f32_16x16x32_bf16 v[6:9], v[162:165], v[210:213], v[6:9]
	v_mfma_f32_16x16x32_bf16 v[62:65], v[158:161], v[190:193], v[62:65]
	v_mfma_f32_16x16x32_bf16 v[54:57], v[166:169], v[190:193], v[54:57]
	v_mfma_f32_16x16x32_bf16 v[46:49], v[158:161], v[198:201], v[46:49]
	v_mfma_f32_16x16x32_bf16 v[38:41], v[166:169], v[198:201], v[38:41]
	v_mfma_f32_16x16x32_bf16 v[30:33], v[158:161], v[206:209], v[30:33]
	v_mfma_f32_16x16x32_bf16 v[22:25], v[166:169], v[206:209], v[22:25]
	v_mfma_f32_16x16x32_bf16 v[14:17], v[158:161], v[214:217], v[14:17]
	v_mfma_f32_16x16x32_bf16 v[6:9], v[166:169], v[214:217], v[6:9]
	s_setprio 0
	s_setprio 1
	v_mfma_f32_16x16x32_bf16 v[58:61], v[170:173], v[186:189], v[58:61]
	v_mfma_f32_16x16x32_bf16 v[50:53], v[178:181], v[186:189], v[50:53]
	v_mfma_f32_16x16x32_bf16 v[42:45], v[170:173], v[194:197], v[42:45]
	v_mfma_f32_16x16x32_bf16 v[34:37], v[178:181], v[194:197], v[34:37]
	v_mfma_f32_16x16x32_bf16 v[26:29], v[170:173], v[202:205], v[26:29]
	v_mfma_f32_16x16x32_bf16 v[18:21], v[178:181], v[202:205], v[18:21]
	v_mfma_f32_16x16x32_bf16 v[10:13], v[170:173], v[210:213], v[10:13]
	v_mfma_f32_16x16x32_bf16 v[2:5], v[178:181], v[210:213], v[2:5]
	v_mfma_f32_16x16x32_bf16 v[58:61], v[174:177], v[190:193], v[58:61]
	v_mfma_f32_16x16x32_bf16 v[50:53], v[182:185], v[190:193], v[50:53]
	v_mfma_f32_16x16x32_bf16 v[42:45], v[174:177], v[198:201], v[42:45]
	v_mfma_f32_16x16x32_bf16 v[34:37], v[182:185], v[198:201], v[34:37]
	v_mfma_f32_16x16x32_bf16 v[26:29], v[174:177], v[206:209], v[26:29]
	v_mfma_f32_16x16x32_bf16 v[18:21], v[182:185], v[206:209], v[18:21]
	v_mfma_f32_16x16x32_bf16 v[10:13], v[174:177], v[214:217], v[10:13]
	v_mfma_f32_16x16x32_bf16 v[2:5], v[182:185], v[214:217], v[2:5]
	s_nop 3
	s_barrier
	s_setprio 0
	s_add_i32 s49, 0, 0x18000
	v_add_u32_e32 v157, s49, v150
	s_add_i32 s50, 0, 0x1c000
	ds_read_b128 v[146:149], v157
	ds_read_b128 v[158:161], v157 offset:1024
	ds_read_b128 v[162:165], v157 offset:2048
	ds_read_b128 v[166:169], v157 offset:3072
	v_add_u32_e32 v157, s50, v150
	ds_read_b128 v[170:173], v157
	ds_read_b128 v[174:177], v157 offset:1024
	ds_read_b128 v[178:181], v157 offset:2048
	ds_read_b128 v[182:185], v157 offset:3072
	s_add_u32 s24, s24, 0x80000
	s_addc_u32 s25, s25, 0
	s_mov_b32 m0, s33
	v_lshl_add_u64 v[226:227], s[24:25], 0, v[136:137]
	ds_read_b128 v[186:189], v154 offset:32768
	ds_read_b128 v[190:193], v154 offset:33792
	ds_read_b128 v[194:197], v154 offset:34816
	ds_read_b128 v[198:201], v154 offset:35840
	ds_read_b128 v[202:205], v154 offset:36864
	ds_read_b128 v[206:209], v154 offset:37888
	ds_read_b128 v[210:213], v154 offset:38912
	ds_read_b128 v[214:217], v154 offset:39936
	global_load_lds_dwordx4 v[226:227], off
	v_lshl_add_u64 v[226:227], s[24:25], 0, v[132:133]
	s_mov_b32 m0, s34
	s_nop 0
	global_load_lds_dwordx4 v[226:227], off
	s_waitcnt vmcnt(8)
	s_waitcnt lgkmcnt(0)
	s_setprio 1
	s_barrier
	v_mfma_f32_16x16x32_bf16 v[126:129], v[146:149], v[186:189], v[126:129]
	v_mfma_f32_16x16x32_bf16 v[118:121], v[162:165], v[186:189], v[118:121]
	v_mfma_f32_16x16x32_bf16 v[110:113], v[146:149], v[194:197], v[110:113]
	v_mfma_f32_16x16x32_bf16 v[102:105], v[162:165], v[194:197], v[102:105]
	v_mfma_f32_16x16x32_bf16 v[94:97], v[146:149], v[202:205], v[94:97]
	v_mfma_f32_16x16x32_bf16 v[86:89], v[162:165], v[202:205], v[86:89]
	v_mfma_f32_16x16x32_bf16 v[78:81], v[146:149], v[210:213], v[78:81]
	v_mfma_f32_16x16x32_bf16 v[70:73], v[162:165], v[210:213], v[70:73]
	v_mfma_f32_16x16x32_bf16 v[126:129], v[158:161], v[190:193], v[126:129]
	v_mfma_f32_16x16x32_bf16 v[118:121], v[166:169], v[190:193], v[118:121]
	v_mfma_f32_16x16x32_bf16 v[110:113], v[158:161], v[198:201], v[110:113]
	v_mfma_f32_16x16x32_bf16 v[102:105], v[166:169], v[198:201], v[102:105]
	v_mfma_f32_16x16x32_bf16 v[94:97], v[158:161], v[206:209], v[94:97]
	v_mfma_f32_16x16x32_bf16 v[86:89], v[166:169], v[206:209], v[86:89]
	v_mfma_f32_16x16x32_bf16 v[78:81], v[158:161], v[214:217], v[78:81]
	v_mfma_f32_16x16x32_bf16 v[70:73], v[166:169], v[214:217], v[70:73]
	s_setprio 0
	s_setprio 1
	v_mfma_f32_16x16x32_bf16 v[122:125], v[170:173], v[186:189], v[122:125]
	v_mfma_f32_16x16x32_bf16 v[114:117], v[178:181], v[186:189], v[114:117]
	v_mfma_f32_16x16x32_bf16 v[106:109], v[170:173], v[194:197], v[106:109]
	v_mfma_f32_16x16x32_bf16 v[98:101], v[178:181], v[194:197], v[98:101]
	v_mfma_f32_16x16x32_bf16 v[90:93], v[170:173], v[202:205], v[90:93]
	v_mfma_f32_16x16x32_bf16 v[82:85], v[178:181], v[202:205], v[82:85]
	v_mfma_f32_16x16x32_bf16 v[74:77], v[170:173], v[210:213], v[74:77]
	v_mfma_f32_16x16x32_bf16 v[66:69], v[178:181], v[210:213], v[66:69]
	v_mfma_f32_16x16x32_bf16 v[122:125], v[174:177], v[190:193], v[122:125]
	v_mfma_f32_16x16x32_bf16 v[114:117], v[182:185], v[190:193], v[114:117]
	v_mfma_f32_16x16x32_bf16 v[106:109], v[174:177], v[198:201], v[106:109]
	v_mfma_f32_16x16x32_bf16 v[98:101], v[182:185], v[198:201], v[98:101]
	v_mfma_f32_16x16x32_bf16 v[90:93], v[174:177], v[206:209], v[90:93]
	v_mfma_f32_16x16x32_bf16 v[82:85], v[182:185], v[206:209], v[82:85]
	v_mfma_f32_16x16x32_bf16 v[74:77], v[174:177], v[214:217], v[74:77]
	v_mfma_f32_16x16x32_bf16 v[66:69], v[182:185], v[214:217], v[66:69]
	s_nop 3
	s_barrier
; #define PG8_STAGE(bufoff, gbase, voff) do { _Pragma("unroll") for (int _i = 0; _i < 2; ++_i) \
;         __builtin_amdgcn_global_load_lds((const unsigned*)((const char*)(gbase) + (voff)[_i]), (PG8_LAS unsigned*)(lds + (bufoff) + ldsw + _i * 8192), 16, 0, 0); } while (0)
; #define PG8_WAIT_V(n) asm volatile("s_waitcnt vmcnt(" #n ")" ::: "memory")
; #define PG8_WAIT_L(n) asm volatile("s_waitcnt lgkmcnt(" #n ")" ::: "memory")
; #define PG8_BAR __builtin_amdgcn_s_barrier()
; #define PG8_SCHED __builtin_amdgcn_sched_barrier(0)
; template <class Epi, class Sched, bool ALIGN_EPI = true, bool SP2 = true>
; __device__ __forceinline__ void gemm_phase(PG8_LAS unsigned char* lds, const int K  , const Sched& S, const Epi& E) {
;     ...
;             PG8_LDA(At, 1, 1); PG8_STAGE(PG8_SB(1, 0), b3, voffB); PG8_STAGE(PG8_SB(1, 1), b3 + hstep, voffB); PG8_STAGE(PG8_SA(1, 0), a3, voffA);
;             PG8_WAIT_V(8); PG8_WAIT_L(0); PG8_BAR; PG8_MMA(1, 0, At, B0); PG8_MMA(1, 1, At, B1); PG8_BAR; PG8_SCHED;
	s_setprio 0
	s_add_i32 s24, s49, s28
	v_lshl_add_u64 v[218:219], v[218:219], 0, s[6:7]
	s_mov_b32 m0, s24
	ds_read_b128 v[186:189], v154 offset:49152
	ds_read_b128 v[190:193], v154 offset:50176
	ds_read_b128 v[194:197], v154 offset:51200
	ds_read_b128 v[198:201], v154 offset:52224
	ds_read_b128 v[202:205], v154 offset:53248
	ds_read_b128 v[206:209], v154 offset:54272
	ds_read_b128 v[210:213], v154 offset:55296
	ds_read_b128 v[214:217], v154 offset:56320
	global_load_lds_dwordx4 v[218:219], off
	s_add_i32 m0, s24, 0x2000
	s_add_u32 s22, s22, 0x80080
	v_lshl_add_u64 v[218:219], v[220:221], 0, s[6:7]
	s_addc_u32 s23, s23, 0
	s_add_i32 s24, s50, s28
	global_load_lds_dwordx4 v[218:219], off
	v_lshl_add_u64 v[218:219], s[22:23], 0, v[134:135]
	s_mov_b32 m0, s24
	s_nop 0
	global_load_lds_dwordx4 v[218:219], off
	v_lshl_add_u64 v[218:219], s[22:23], 0, v[130:131]
	s_add_i32 m0, s24, 0x2000
	s_nop 0
	global_load_lds_dwordx4 v[218:219], off
	v_lshl_add_u64 v[218:219], v[222:223], 0, s[6:7]
	s_mov_b32 m0, s36
	s_nop 0
	global_load_lds_dwordx4 v[218:219], off
	v_lshl_add_u64 v[218:219], v[224:225], 0, s[6:7]
	s_mov_b32 m0, s37
	s_nop 0
	global_load_lds_dwordx4 v[218:219], off
	s_waitcnt vmcnt(8)
	s_waitcnt lgkmcnt(0)
	s_setprio 1
	s_barrier
	v_mfma_f32_16x16x32_bf16 v[62:65], v[146:149], v[186:189], v[62:65]
	v_mfma_f32_16x16x32_bf16 v[54:57], v[162:165], v[186:189], v[54:57]
	v_mfma_f32_16x16x32_bf16 v[46:49], v[146:149], v[194:197], v[46:49]
	v_mfma_f32_16x16x32_bf16 v[38:41], v[162:165], v[194:197], v[38:41]
	v_mfma_f32_16x16x32_bf16 v[30:33], v[146:149], v[202:205], v[30:33]
	v_mfma_f32_16x16x32_bf16 v[22:25], v[162:165], v[202:205], v[22:25]
	v_mfma_f32_16x16x32_bf16 v[14:17], v[146:149], v[210:213], v[14:17]
	v_mfma_f32_16x16x32_bf16 v[6:9], v[162:165], v[210:213], v[6:9]
	v_mfma_f32_16x16x32_bf16 v[62:65], v[158:161], v[190:193], v[62:65]
	v_mfma_f32_16x16x32_bf16 v[54:57], v[166:169], v[190:193], v[54:57]
	v_mfma_f32_16x16x32_bf16 v[46:49], v[158:161], v[198:201], v[46:49]
	v_mfma_f32_16x16x32_bf16 v[38:41], v[166:169], v[198:201], v[38:41]
	v_mfma_f32_16x16x32_bf16 v[30:33], v[158:161], v[206:209], v[30:33]
	v_mfma_f32_16x16x32_bf16 v[22:25], v[166:169], v[206:209], v[22:25]
	v_mfma_f32_16x16x32_bf16 v[14:17], v[158:161], v[214:217], v[14:17]
	v_mfma_f32_16x16x32_bf16 v[6:9], v[166:169], v[214:217], v[6:9]
	s_setprio 0
	s_setprio 1
	v_mfma_f32_16x16x32_bf16 v[58:61], v[170:173], v[186:189], v[58:61]
	v_mfma_f32_16x16x32_bf16 v[50:53], v[178:181], v[186:189], v[50:53]
	v_mfma_f32_16x16x32_bf16 v[42:45], v[170:173], v[194:197], v[42:45]
	v_mfma_f32_16x16x32_bf16 v[34:37], v[178:181], v[194:197], v[34:37]
	v_mfma_f32_16x16x32_bf16 v[26:29], v[170:173], v[202:205], v[26:29]
	v_mfma_f32_16x16x32_bf16 v[18:21], v[178:181], v[202:205], v[18:21]
	v_mfma_f32_16x16x32_bf16 v[10:13], v[170:173], v[210:213], v[10:13]
	v_mfma_f32_16x16x32_bf16 v[2:5], v[178:181], v[210:213], v[2:5]
	v_mfma_f32_16x16x32_bf16 v[58:61], v[174:177], v[190:193], v[58:61]
	v_mfma_f32_16x16x32_bf16 v[50:53], v[182:185], v[190:193], v[50:53]
	v_mfma_f32_16x16x32_bf16 v[42:45], v[174:177], v[198:201], v[42:45]
	v_mfma_f32_16x16x32_bf16 v[34:37], v[182:185], v[198:201], v[34:37]
	v_mfma_f32_16x16x32_bf16 v[26:29], v[174:177], v[206:209], v[26:29]
	v_mfma_f32_16x16x32_bf16 v[18:21], v[182:185], v[206:209], v[18:21]
	v_mfma_f32_16x16x32_bf16 v[10:13], v[174:177], v[214:217], v[10:13]
	v_mfma_f32_16x16x32_bf16 v[2:5], v[182:185], v[214:217], v[2:5]
	s_nop 3
	s_barrier
	s_setprio 0
	s_add_i32 s48, s48, 2
	s_add_u32 s20, s20, 0x100
	s_addc_u32 s21, s21, 0
	s_add_u32 s46, s46, 0x100
	s_addc_u32 s47, s47, 0
	s_cmp_gt_u32 s48, 29
	s_cbranch_scc0 .LBB0_2433
	s_and_b64 vcc, exec, s[8:9]
	s_cbranch_vccz .LBB0_2436
	s_barrier

; #define PG8_STAGE(bufoff, gbase, voff) do { _Pragma("unroll") for (int _i = 0; _i < 2; ++_i) \
;         __builtin_amdgcn_global_load_lds((const unsigned*)((const char*)(gbase) + (voff)[_i]), (PG8_LAS unsigned*)(lds + (bufoff) + ldsw + _i * 8192), 16, 0, 0); } while (0)
; #define PG8_WAIT_V(n) asm volatile("s_waitcnt vmcnt(" #n ")" ::: "memory")
; #define PG8_WAIT_L(n) asm volatile("s_waitcnt lgkmcnt(" #n ")" ::: "memory")
; #define PG8_BAR __builtin_amdgcn_s_barrier()
; #define PG8_SCHED __builtin_amdgcn_sched_barrier(0)
;     __device__ __forceinline__ int nt(const pg8::Unit& u) const { return u.kind == 0 ? ntiles : q_nt(u.kind - 1); }
; template <class Epi, class Sched, bool ALIGN_EPI = true, bool SP2 = true>
; __device__ __forceinline__ void gemm_phase(PG8_LAS unsigned char* lds, const int K  , const Sched& S, const Epi& E) {
;     ...
;             const bool last = (t == nt - 2);
;             const char* a1 = cA + (size_t)(t + 1) * kstep;
;             const char* a2 = last ? nA : cA + (size_t)(t + 2) * kstep; const char* b2 = last ? nB : cB + (size_t)(t + 2) * kstep;
;             const char* a3 = a2 + kstep; const char* b3 = b2 + kstep;
;             if constexpr (SP2) {
;             PG8_LDB(B0, 0, 0); PG8_LDB(B1, 0, 1); PG8_SCHED; PG8_LDA(At, 0, 0); PG8_STAGE(PG8_SA(1, 1), a1 + hstep, voffA);
;             PG8_WAIT_V(8); PG8_WAIT_L(0); PG8_BAR; PG8_MMA(0, 0, At, B0); PG8_MMA(0, 1, At, B1); PG8_BAR; PG8_SCHED;
;             PG8_LDA(At, 0, 1); PG8_STAGE(PG8_SB(0, 0), b2, voffB); PG8_STAGE(PG8_SB(0, 1), b2 + hstep, voffB); PG8_STAGE(PG8_SA(0, 0), a2, voffA);
;             PG8_WAIT_V(8); PG8_WAIT_L(0); PG8_BAR; PG8_MMA(1, 0, At, B0); PG8_MMA(1, 1, At, B1); PG8_BAR; PG8_SCHED;
.LBB0_2516:
	ds_read_b128 v[16:19], v206
	ds_read_b128 v[20:23], v206 offset:1024
	ds_read_b128 v[24:27], v206 offset:2048
	ds_read_b128 v[28:31], v206 offset:3072
	ds_read_b128 v[0:3], v207
	ds_read_b128 v[4:7], v207 offset:1024
	ds_read_b128 v[8:11], v207 offset:2048
	ds_read_b128 v[12:15], v207 offset:3072
	s_add_u32 s18, s16, 0xfff50080
	s_addc_u32 s19, s17, -1
	s_cmp_eq_u32 s57, 40
	s_cselect_b32 s21, s7, s19
	s_cselect_b32 s20, s6, s18
	s_cselect_b32 s19, s15, s56
	s_cselect_b32 s18, s14, s55
	v_lshl_add_u64 v[200:201], s[16:17], 0, v[176:177]
	s_add_i32 m0, s25, 0xc000
	ds_read_b128 v[160:163], v208
	ds_read_b128 v[164:167], v208 offset:1024
	ds_read_b128 v[184:187], v208 offset:2048
	ds_read_b128 v[188:191], v208 offset:3072
	ds_read_b128 v[192:195], v208 offset:4096
	ds_read_b128 v[196:199], v208 offset:5120
	ds_read_b128 v[210:213], v208 offset:6144
	ds_read_b128 v[214:217], v208 offset:7168
	global_load_lds_dwordx4 v[200:201], off
	v_lshl_add_u64 v[200:201], s[16:17], 0, v[178:179]
	s_add_i32 m0, s25, 0xe000
	s_nop 0
	global_load_lds_dwordx4 v[200:201], off
	s_waitcnt vmcnt(8)
	s_waitcnt lgkmcnt(0)
	s_setprio 1
	s_barrier
	v_mfma_scale_f32_16x16x128_f8f6f4 v[156:159], v[16:23], v[160:167], v[156:159], v202, v202 op_sel_hi:[0,0,0]
	v_mfma_scale_f32_16x16x128_f8f6f4 v[152:155], v[24:31], v[160:167], v[152:155], v202, v202 op_sel_hi:[0,0,0]
	v_mfma_scale_f32_16x16x128_f8f6f4 v[140:143], v[16:23], v[184:191], v[140:143], v202, v202 op_sel_hi:[0,0,0]
	v_mfma_scale_f32_16x16x128_f8f6f4 v[136:139], v[24:31], v[184:191], v[136:139], v202, v202 op_sel_hi:[0,0,0]
	v_mfma_scale_f32_16x16x128_f8f6f4 v[124:127], v[16:23], v[192:199], v[124:127], v202, v202 op_sel_hi:[0,0,0]
	v_mfma_scale_f32_16x16x128_f8f6f4 v[120:123], v[24:31], v[192:199], v[120:123], v202, v202 op_sel_hi:[0,0,0]
	v_mfma_scale_f32_16x16x128_f8f6f4 v[108:111], v[16:23], v[210:217], v[108:111], v202, v202 op_sel_hi:[0,0,0]
	v_mfma_scale_f32_16x16x128_f8f6f4 v[104:107], v[24:31], v[210:217], v[104:107], v202, v202 op_sel_hi:[0,0,0]
	s_setprio 0
	s_setprio 1
	v_mfma_scale_f32_16x16x128_f8f6f4 v[148:151], v[0:7], v[160:167], v[148:151], v202, v202 op_sel_hi:[0,0,0]
	v_mfma_scale_f32_16x16x128_f8f6f4 v[144:147], v[8:15], v[160:167], v[144:147], v202, v202 op_sel_hi:[0,0,0]
	v_mfma_scale_f32_16x16x128_f8f6f4 v[132:135], v[0:7], v[184:191], v[132:135], v202, v202 op_sel_hi:[0,0,0]
	v_mfma_scale_f32_16x16x128_f8f6f4 v[128:131], v[8:15], v[184:191], v[128:131], v202, v202 op_sel_hi:[0,0,0]
	v_mfma_scale_f32_16x16x128_f8f6f4 v[116:119], v[0:7], v[192:199], v[116:119], v202, v202 op_sel_hi:[0,0,0]
	v_mfma_scale_f32_16x16x128_f8f6f4 v[112:115], v[8:15], v[192:199], v[112:115], v202, v202 op_sel_hi:[0,0,0]
	v_mfma_scale_f32_16x16x128_f8f6f4 v[100:103], v[0:7], v[210:217], v[100:103], v202, v202 op_sel_hi:[0,0,0]
	v_mfma_scale_f32_16x16x128_f8f6f4 v[96:99], v[8:15], v[210:217], v[96:99], v202, v202 op_sel_hi:[0,0,0]
	s_nop 3
	s_barrier
	s_setprio 0
	s_add_i32 s58, s38, s24
	v_lshl_add_u64 v[160:161], s[18:19], 0, v[170:171]
	s_mov_b32 m0, s58
	ds_read_b128 v[184:187], v208 offset:16384
	ds_read_b128 v[188:191], v208 offset:17408
	ds_read_b128 v[192:195], v208 offset:18432
	ds_read_b128 v[196:199], v208 offset:19456
	ds_read_b128 v[210:213], v208 offset:20480
	ds_read_b128 v[214:217], v208 offset:21504
	ds_read_b128 v[218:221], v208 offset:22528
	ds_read_b128 v[222:225], v208 offset:23552
	global_load_lds_dwordx4 v[160:161], off
	s_add_i32 m0, s58, 0x2000
	s_add_u32 s58, s18, 0xb0000
	v_lshl_add_u64 v[162:163], s[18:19], 0, v[174:175]
	s_addc_u32 s59, s19, 0
	s_add_i32 s60, s39, s24
	global_load_lds_dwordx4 v[162:163], off
	v_lshl_add_u64 v[164:165], s[58:59], 0, v[170:171]
	s_mov_b32 m0, s60
	v_lshl_add_u64 v[166:167], s[20:21], 0, v[172:173]
	global_load_lds_dwordx4 v[164:165], off
	v_lshl_add_u64 v[164:165], s[58:59], 0, v[174:175]
	s_add_i32 m0, s60, 0x2000
	s_nop 0
	global_load_lds_dwordx4 v[164:165], off
	v_lshl_add_u64 v[164:165], s[20:21], 0, v[168:169]
	s_mov_b32 m0, s25
	s_nop 0
	global_load_lds_dwordx4 v[164:165], off
	s_mov_b32 m0, s26
	s_nop 0
	global_load_lds_dwordx4 v[166:167], off
	s_waitcnt vmcnt(8)
	s_waitcnt lgkmcnt(0)
	s_setprio 1
	s_barrier
	v_mfma_scale_f32_16x16x128_f8f6f4 v[92:95], v[16:23], v[184:191], v[92:95], v202, v202 op_sel_hi:[0,0,0]
	v_mfma_scale_f32_16x16x128_f8f6f4 v[88:91], v[24:31], v[184:191], v[88:91], v202, v202 op_sel_hi:[0,0,0]
	v_mfma_scale_f32_16x16x128_f8f6f4 v[76:79], v[16:23], v[192:199], v[76:79], v202, v202 op_sel_hi:[0,0,0]
	v_mfma_scale_f32_16x16x128_f8f6f4 v[72:75], v[24:31], v[192:199], v[72:75], v202, v202 op_sel_hi:[0,0,0]
	v_mfma_scale_f32_16x16x128_f8f6f4 v[60:63], v[16:23], v[210:217], v[60:63], v202, v202 op_sel_hi:[0,0,0]
	v_mfma_scale_f32_16x16x128_f8f6f4 v[56:59], v[24:31], v[210:217], v[56:59], v202, v202 op_sel_hi:[0,0,0]
	v_mfma_scale_f32_16x16x128_f8f6f4 v[44:47], v[16:23], v[218:225], v[44:47], v202, v202 op_sel_hi:[0,0,0]
	v_mfma_scale_f32_16x16x128_f8f6f4 v[40:43], v[24:31], v[218:225], v[40:43], v202, v202 op_sel_hi:[0,0,0]
	s_setprio 0
	s_setprio 1
	v_mfma_scale_f32_16x16x128_f8f6f4 v[84:87], v[0:7], v[184:191], v[84:87], v202, v202 op_sel_hi:[0,0,0]
	v_mfma_scale_f32_16x16x128_f8f6f4 v[80:83], v[8:15], v[184:191], v[80:83], v202, v202 op_sel_hi:[0,0,0]
	v_mfma_scale_f32_16x16x128_f8f6f4 v[68:71], v[0:7], v[192:199], v[68:71], v202, v202 op_sel_hi:[0,0,0]
	v_mfma_scale_f32_16x16x128_f8f6f4 v[64:67], v[8:15], v[192:199], v[64:67], v202, v202 op_sel_hi:[0,0,0]
	v_mfma_scale_f32_16x16x128_f8f6f4 v[52:55], v[0:7], v[210:217], v[52:55], v202, v202 op_sel_hi:[0,0,0]
	v_mfma_scale_f32_16x16x128_f8f6f4 v[48:51], v[8:15], v[210:217], v[48:51], v202, v202 op_sel_hi:[0,0,0]
	v_mfma_scale_f32_16x16x128_f8f6f4 v[36:39], v[0:7], v[218:225], v[36:39], v202, v202 op_sel_hi:[0,0,0]
	v_mfma_scale_f32_16x16x128_f8f6f4 v[32:35], v[8:15], v[218:225], v[32:35], v202, v202 op_sel_hi:[0,0,0]
	s_nop 3
	s_barrier
; #define PG8_STAGE(bufoff, gbase, voff) do { _Pragma("unroll") for (int _i = 0; _i < 2; ++_i) \
;         __builtin_amdgcn_global_load_lds((const unsigned*)((const char*)(gbase) + (voff)[_i]), (PG8_LAS unsigned*)(lds + (bufoff) + ldsw + _i * 8192), 16, 0, 0); } while (0)
; #define PG8_WAIT_V(n) asm volatile("s_waitcnt vmcnt(" #n ")" ::: "memory")
; #define PG8_WAIT_L(n) asm volatile("s_waitcnt lgkmcnt(" #n ")" ::: "memory")
; #define PG8_BAR __builtin_amdgcn_s_barrier()
; #define PG8_SCHED __builtin_amdgcn_sched_barrier(0)
; template <class Epi, class Sched, bool ALIGN_EPI = true, bool SP2 = true>
; __device__ __forceinline__ void gemm_phase(PG8_LAS unsigned char* lds, const int K  , const Sched& S, const Epi& E) {
;     ...
;             PG8_LDB(B0, 1, 0); PG8_LDB(B1, 1, 1); PG8_SCHED; PG8_LDA(At, 1, 0); PG8_STAGE(PG8_SA(0, 1), a2 + hstep, voffA);
;             PG8_WAIT_V(8); PG8_WAIT_L(0); PG8_BAR; PG8_MMA(0, 0, At, B0); PG8_MMA(0, 1, At, B1); PG8_BAR; PG8_SCHED;
;             PG8_LDA(At, 1, 1); PG8_STAGE(PG8_SB(1, 0), b3, voffB); PG8_STAGE(PG8_SB(1, 1), b3 + hstep, voffB); PG8_STAGE(PG8_SA(1, 0), a3, voffA);
;             PG8_WAIT_V(8); PG8_WAIT_L(0); PG8_BAR; PG8_MMA(1, 0, At, B0); PG8_MMA(1, 1, At, B1); PG8_BAR; PG8_SCHED;
;     ...
;         if constexpr (Epi::FP8) asm volatile("s_nop 15\n\ts_nop 15\n\ts_nop 15\n\ts_nop 15\n\ts_nop 15" ::: "memory");
;         if constexpr (ALIGN_EPI) { if (wr == 0) PG8_BAR; }
	s_setprio 0
	s_add_i32 s58, 0, 0x18000
	s_add_i32 s59, 0, 0x1c000
	v_add_u32_e32 v12, s58, v204
	v_add_u32_e32 v28, s59, v204
	ds_read_b128 v[0:3], v12
	ds_read_b128 v[4:7], v12 offset:1024
	ds_read_b128 v[8:11], v12 offset:2048
	ds_read_b128 v[12:15], v12 offset:3072
	ds_read_b128 v[16:19], v28
	ds_read_b128 v[20:23], v28 offset:1024
	ds_read_b128 v[24:27], v28 offset:2048
	ds_read_b128 v[28:31], v28 offset:3072
	s_add_u32 s20, s20, 0xb0000
	s_addc_u32 s21, s21, 0
	s_mov_b32 m0, s27
	v_lshl_add_u64 v[200:201], s[20:21], 0, v[168:169]
	ds_read_b128 v[184:187], v208 offset:32768
	ds_read_b128 v[188:191], v208 offset:33792
	ds_read_b128 v[192:195], v208 offset:34816
	ds_read_b128 v[196:199], v208 offset:35840
	ds_read_b128 v[210:213], v208 offset:36864
	ds_read_b128 v[214:217], v208 offset:37888
	ds_read_b128 v[218:221], v208 offset:38912
	ds_read_b128 v[222:225], v208 offset:39936
	global_load_lds_dwordx4 v[200:201], off
	v_lshl_add_u64 v[200:201], s[20:21], 0, v[172:173]
	s_mov_b32 m0, s28
	s_nop 0
	global_load_lds_dwordx4 v[200:201], off
	s_waitcnt vmcnt(8)
	s_waitcnt lgkmcnt(0)
	s_setprio 1
	s_barrier
	v_mfma_scale_f32_16x16x128_f8f6f4 v[156:159], v[0:7], v[184:191], v[156:159], v202, v202 op_sel_hi:[0,0,0]
	v_mfma_scale_f32_16x16x128_f8f6f4 v[152:155], v[8:15], v[184:191], v[152:155], v202, v202 op_sel_hi:[0,0,0]
	v_mfma_scale_f32_16x16x128_f8f6f4 v[140:143], v[0:7], v[192:199], v[140:143], v202, v202 op_sel_hi:[0,0,0]
	v_mfma_scale_f32_16x16x128_f8f6f4 v[136:139], v[8:15], v[192:199], v[136:139], v202, v202 op_sel_hi:[0,0,0]
	v_mfma_scale_f32_16x16x128_f8f6f4 v[124:127], v[0:7], v[210:217], v[124:127], v202, v202 op_sel_hi:[0,0,0]
	v_mfma_scale_f32_16x16x128_f8f6f4 v[120:123], v[8:15], v[210:217], v[120:123], v202, v202 op_sel_hi:[0,0,0]
	v_mfma_scale_f32_16x16x128_f8f6f4 v[108:111], v[0:7], v[218:225], v[108:111], v202, v202 op_sel_hi:[0,0,0]
	v_mfma_scale_f32_16x16x128_f8f6f4 v[104:107], v[8:15], v[218:225], v[104:107], v202, v202 op_sel_hi:[0,0,0]
	s_setprio 0
	s_setprio 1
	v_mfma_scale_f32_16x16x128_f8f6f4 v[148:151], v[16:23], v[184:191], v[148:151], v202, v202 op_sel_hi:[0,0,0]
	v_mfma_scale_f32_16x16x128_f8f6f4 v[144:147], v[24:31], v[184:191], v[144:147], v202, v202 op_sel_hi:[0,0,0]
	v_mfma_scale_f32_16x16x128_f8f6f4 v[132:135], v[16:23], v[192:199], v[132:135], v202, v202 op_sel_hi:[0,0,0]
	v_mfma_scale_f32_16x16x128_f8f6f4 v[128:131], v[24:31], v[192:199], v[128:131], v202, v202 op_sel_hi:[0,0,0]
	v_mfma_scale_f32_16x16x128_f8f6f4 v[116:119], v[16:23], v[210:217], v[116:119], v202, v202 op_sel_hi:[0,0,0]
	v_mfma_scale_f32_16x16x128_f8f6f4 v[112:115], v[24:31], v[210:217], v[112:115], v202, v202 op_sel_hi:[0,0,0]
	v_mfma_scale_f32_16x16x128_f8f6f4 v[100:103], v[16:23], v[218:225], v[100:103], v202, v202 op_sel_hi:[0,0,0]
	v_mfma_scale_f32_16x16x128_f8f6f4 v[96:99], v[24:31], v[218:225], v[96:99], v202, v202 op_sel_hi:[0,0,0]
	s_nop 3
	s_barrier
	s_setprio 0
	s_add_i32 s20, s58, s24
	v_lshl_add_u64 v[160:161], v[160:161], 0, s[8:9]
	s_mov_b32 m0, s20
	ds_read_b128 v[184:187], v208 offset:49152
	ds_read_b128 v[188:191], v208 offset:50176
	ds_read_b128 v[192:195], v208 offset:51200
	ds_read_b128 v[196:199], v208 offset:52224
	ds_read_b128 v[210:213], v208 offset:53248
	ds_read_b128 v[214:217], v208 offset:54272
	ds_read_b128 v[218:221], v208 offset:55296
	ds_read_b128 v[222:225], v208 offset:56320
	global_load_lds_dwordx4 v[160:161], off
	s_add_i32 m0, s20, 0x2000
	s_add_u32 s18, s18, 0xb0080
	v_lshl_add_u64 v[160:161], v[162:163], 0, s[8:9]
	s_addc_u32 s19, s19, 0
	s_add_i32 s20, s59, s24
	global_load_lds_dwordx4 v[160:161], off
	v_lshl_add_u64 v[160:161], s[18:19], 0, v[170:171]
	s_mov_b32 m0, s20
	s_nop 0
	global_load_lds_dwordx4 v[160:161], off
	v_lshl_add_u64 v[160:161], s[18:19], 0, v[174:175]
	s_add_i32 m0, s20, 0x2000
	s_nop 0
	global_load_lds_dwordx4 v[160:161], off
	v_lshl_add_u64 v[160:161], v[164:165], 0, s[8:9]
	s_mov_b32 m0, s35
	s_nop 0
	global_load_lds_dwordx4 v[160:161], off
	v_lshl_add_u64 v[160:161], v[166:167], 0, s[8:9]
	s_mov_b32 m0, s36
	s_nop 0
	global_load_lds_dwordx4 v[160:161], off
	s_waitcnt vmcnt(8)
	s_waitcnt lgkmcnt(0)
	s_setprio 1
	s_barrier
	v_mfma_scale_f32_16x16x128_f8f6f4 v[92:95], v[0:7], v[184:191], v[92:95], v202, v202 op_sel_hi:[0,0,0]
	v_mfma_scale_f32_16x16x128_f8f6f4 v[88:91], v[8:15], v[184:191], v[88:91], v202, v202 op_sel_hi:[0,0,0]
	v_mfma_scale_f32_16x16x128_f8f6f4 v[76:79], v[0:7], v[192:199], v[76:79], v202, v202 op_sel_hi:[0,0,0]
	v_mfma_scale_f32_16x16x128_f8f6f4 v[72:75], v[8:15], v[192:199], v[72:75], v202, v202 op_sel_hi:[0,0,0]
	v_mfma_scale_f32_16x16x128_f8f6f4 v[60:63], v[0:7], v[210:217], v[60:63], v202, v202 op_sel_hi:[0,0,0]
	v_mfma_scale_f32_16x16x128_f8f6f4 v[56:59], v[8:15], v[210:217], v[56:59], v202, v202 op_sel_hi:[0,0,0]
	v_mfma_scale_f32_16x16x128_f8f6f4 v[44:47], v[0:7], v[218:225], v[44:47], v202, v202 op_sel_hi:[0,0,0]
	v_mfma_scale_f32_16x16x128_f8f6f4 v[40:43], v[8:15], v[218:225], v[40:43], v202, v202 op_sel_hi:[0,0,0]
	s_setprio 0
	s_setprio 1
	v_mfma_scale_f32_16x16x128_f8f6f4 v[84:87], v[16:23], v[184:191], v[84:87], v202, v202 op_sel_hi:[0,0,0]
	v_mfma_scale_f32_16x16x128_f8f6f4 v[80:83], v[24:31], v[184:191], v[80:83], v202, v202 op_sel_hi:[0,0,0]
	v_mfma_scale_f32_16x16x128_f8f6f4 v[68:71], v[16:23], v[192:199], v[68:71], v202, v202 op_sel_hi:[0,0,0]
	v_mfma_scale_f32_16x16x128_f8f6f4 v[64:67], v[24:31], v[192:199], v[64:67], v202, v202 op_sel_hi:[0,0,0]
	v_mfma_scale_f32_16x16x128_f8f6f4 v[52:55], v[16:23], v[210:217], v[52:55], v202, v202 op_sel_hi:[0,0,0]
	v_mfma_scale_f32_16x16x128_f8f6f4 v[48:51], v[24:31], v[210:217], v[48:51], v202, v202 op_sel_hi:[0,0,0]
	v_mfma_scale_f32_16x16x128_f8f6f4 v[36:39], v[16:23], v[218:225], v[36:39], v202, v202 op_sel_hi:[0,0,0]
	v_mfma_scale_f32_16x16x128_f8f6f4 v[32:35], v[24:31], v[218:225], v[32:35], v202, v202 op_sel_hi:[0,0,0]
	s_nop 3
	s_barrier
	s_setprio 0
	s_add_i32 s57, s57, 2
	s_add_u32 s16, s16, 0x100
	s_addc_u32 s17, s17, 0
	s_add_u32 s55, s55, 0x100
	s_addc_u32 s56, s56, 0
	s_cmp_gt_u32 s57, 41
	s_cbranch_scc0 .LBB0_2516
	s_nop 15
	s_nop 15
	s_nop 15
	s_nop 15
	s_nop 15
	s_and_b64 vcc, exec, s[10:11]
	s_cbranch_vccz .LBB0_2519
	s_barrier
